# tile index bits 6/9 swapped so blocks b and b+256 (likely co-resident on a CU) work on the same activation rows at the same time (L1 reuse attempt)
# baseline (speedup 1.0000x reference)
.LBB0_171:
	s_lshr_b32 s88, s75, 3
	s_lshl_b32 s88, s88, 4
	s_and_b32 s90, s75, 7
	s_or_b32 s88, s88, s90
	s_lshl_b32 s90, s89, 3
	s_add_i32 s88, s88, s90
	s_lshr_b32 s90, s88, 3
	s_xor_b32 s90, s90, s88
	s_bfe_u32 s90, s90, 0x10006
	s_mul_i32 s90, s90, 0x240
	s_xor_b32 s88, s88, s90
	s_ashr_i32 s1, s88, 31
	s_lshr_b32 s1, s1, 23
	s_add_i32 s1, s88, s1
	s_ashr_i32 s1, s1, 9
	s_and_b32 s0, s88, 7
	s_lshl_b32 s1, s1, 3
	s_or_b32 s34, s1, s0
	s_mul_hi_i32 s0, s34, 0x92492493
	s_add_i32 s0, s0, s34
	s_lshr_b32 s1, s0, 31
	s_ashr_i32 s70, s0, 2
	s_add_i32 s70, s70, s1
	s_lshl_b32 s0, s70, 3
	s_bfe_u32 s1, s88, 0x30003
	s_or_b32 s66, s0, s1
	s_mul_i32 s0, s70, 7
	s_sub_i32 s77, s34, s0
	s_lshl_b32 s0, s77, 3
	s_bfe_u32 s76, s88, 0x30006
	s_or_b32 s0, s0, s76
	s_ashr_i32 s67, s66, 31
	s_ashr_i32 s1, s0, 31
	s_lshl_b64 s[4:5], s[0:1], 18
	s_lshl_b64 s[6:7], s[66:67], 18
	s_cmp_lg_u32 s89, 0
	s_cbranch_scc1 .Lmy_ip0_pass2
	s_barrier
	s_setprio 2
	s_lshl_b64 s[64:65], s[66:67], 17
	s_add_u32 s84, s50, 0x3a00000
	s_addc_u32 s85, s51, 0
	s_add_u32 s84, s84, s6
	s_addc_u32 s85, s85, s7
	s_add_u32 s92, s84, 0x40000
	s_addc_u32 s93, s85, 0
	s_add_u32 s86, s50, 0x1a00000
	s_addc_u32 s87, s51, 0
	s_add_u32 s86, s86, s4
	s_addc_u32 s87, s87, s5
	v_readfirstlane_b32 s1, v129
	v_and_b32_e32 v200, 15, v131
	v_bfe_u32 v201, v131, 4, 2
	v_and_b32_e32 v202, 63, v131
	v_lshlrev_b32_e32 v202, 4, v202
	v_lshrrev_b32_e32 v203, 6, v131
	v_lshl_add_u32 v142, v203, 16, v202
	v_add_u32_e32 v150, 0x8000, v142
	v_bfe_u32 v202, v131, 1, 3
	v_xor_b32_e32 v202, v201, v202
	v_lshlrev_b32_e32 v202, 4, v202
	v_lshl_or_b32 v212, v200, 7, v202
	v_xor_b32_e32 v213, 64, v212
	v_bfe_u32 v200, v131, 4, 3
	v_and_b32_e32 v201, 7, v131
	v_xor_b32_e32 v200, v200, v201
	v_lshlrev_b32_e32 v200, 4, v200
	v_lshrrev_b32_e32 v201, 3, v131
	v_lshl_or_b32 v151, v201, 11, v200
	v_add_u32_e32 v156, 65536, v151
	v_add_u32_e32 v158, 131072, v151
	v_add_u32_e32 v159, 196608, v151
	s_add_u32 m0, s1, 0
	v_mov_b32_e32 v0, 0
	v_mov_b32_e32 v1, 0
	global_load_lds_dwordx4 v151, s[86:87]
	v_mov_b32_e32 v2, 0
	v_mov_b32_e32 v3, 0
	v_mov_b32_e32 v4, 0
	s_add_u32 m0, s1, 4096
	v_mov_b32_e32 v5, 0
	v_mov_b32_e32 v6, 0
	global_load_lds_dwordx4 v156, s[86:87]
	v_mov_b32_e32 v7, 0
	v_mov_b32_e32 v8, 0
	v_mov_b32_e32 v9, 0
	s_add_u32 m0, s1, 8192
	v_mov_b32_e32 v10, 0
	v_mov_b32_e32 v11, 0
	global_load_lds_dwordx4 v158, s[86:87]
	v_mov_b32_e32 v12, 0
	v_mov_b32_e32 v13, 0
	v_mov_b32_e32 v14, 0
	s_add_u32 m0, s1, 12288
	v_mov_b32_e32 v15, 0
	v_mov_b32_e32 v16, 0
	global_load_lds_dwordx4 v159, s[86:87]
	s_add_u32 s86, s86, 128
	s_addc_u32 s87, s87, 0
	v_mov_b32_e32 v17, 0
	v_mov_b32_e32 v18, 0
	v_mov_b32_e32 v19, 0
	global_load_dwordx4 v[64:67], v142, s[84:85] offset:0
	v_mov_b32_e32 v20, 0
	v_mov_b32_e32 v21, 0
	v_mov_b32_e32 v22, 0
	global_load_dwordx4 v[68:71], v150, s[84:85] offset:0
	v_mov_b32_e32 v23, 0
	v_mov_b32_e32 v24, 0
	v_mov_b32_e32 v25, 0
	global_load_dwordx4 v[72:75], v142, s[92:93] offset:0
	v_mov_b32_e32 v26, 0
	v_mov_b32_e32 v27, 0
	v_mov_b32_e32 v28, 0
	global_load_dwordx4 v[76:79], v150, s[92:93] offset:0
	v_mov_b32_e32 v29, 0
	v_mov_b32_e32 v30, 0
	v_mov_b32_e32 v31, 0
	global_load_dwordx4 v[80:83], v142, s[84:85] offset:1024
	v_mov_b32_e32 v32, 0
	v_mov_b32_e32 v33, 0
	v_mov_b32_e32 v34, 0
	global_load_dwordx4 v[84:87], v150, s[84:85] offset:1024
	v_mov_b32_e32 v35, 0
	v_mov_b32_e32 v36, 0
	v_mov_b32_e32 v37, 0
	global_load_dwordx4 v[88:91], v142, s[92:93] offset:1024
	v_mov_b32_e32 v38, 0
	v_mov_b32_e32 v39, 0
	v_mov_b32_e32 v40, 0
	global_load_dwordx4 v[92:95], v150, s[92:93] offset:1024
	s_add_u32 s84, s84, 0x800
	s_addc_u32 s85, s85, 0
	s_add_u32 s92, s92, 0x800
	s_addc_u32 s93, s93, 0
	v_mov_b32_e32 v41, 0
	v_mov_b32_e32 v42, 0
	v_mov_b32_e32 v43, 0
	s_add_u32 m0, s1, 16384
	v_mov_b32_e32 v44, 0
	v_mov_b32_e32 v45, 0
	global_load_lds_dwordx4 v151, s[86:87]
	v_mov_b32_e32 v46, 0
	v_mov_b32_e32 v47, 0
	v_mov_b32_e32 v48, 0
	s_add_u32 m0, s1, 20480
	v_mov_b32_e32 v49, 0
	v_mov_b32_e32 v50, 0
	global_load_lds_dwordx4 v156, s[86:87]
	v_mov_b32_e32 v51, 0
	v_mov_b32_e32 v52, 0
	v_mov_b32_e32 v53, 0
	s_add_u32 m0, s1, 24576
	v_mov_b32_e32 v54, 0
	v_mov_b32_e32 v55, 0
	global_load_lds_dwordx4 v158, s[86:87]
	v_mov_b32_e32 v56, 0
	v_mov_b32_e32 v57, 0
	v_mov_b32_e32 v58, 0
	s_add_u32 m0, s1, 28672
	v_mov_b32_e32 v59, 0
	v_mov_b32_e32 v60, 0
	global_load_lds_dwordx4 v159, s[86:87]
	s_add_u32 s86, s86, 128
	s_addc_u32 s87, s87, 0
	v_mov_b32_e32 v61, 0
	v_mov_b32_e32 v62, 0
	v_mov_b32_e32 v63, 0
	s_add_u32 m0, s1, 32768
	v_mov_b32_e32 v144, 0
	v_mov_b32_e32 v145, 0
	global_load_lds_dwordx4 v151, s[86:87]
	v_mov_b32_e32 v146, 0
	v_mov_b32_e32 v147, 0
	v_mov_b32_e32 v184, 0
	s_add_u32 m0, s1, 36864
	v_mov_b32_e32 v185, 0
	v_mov_b32_e32 v186, 0
	global_load_lds_dwordx4 v156, s[86:87]
	v_mov_b32_e32 v187, 0
	v_mov_b32_e32 v204, 0
	v_mov_b32_e32 v205, 0
	s_add_u32 m0, s1, 40960
	v_mov_b32_e32 v206, 0
	v_mov_b32_e32 v207, 0
	global_load_lds_dwordx4 v158, s[86:87]
	v_mov_b32_e32 v208, 0
	v_mov_b32_e32 v209, 0
	v_mov_b32_e32 v210, 0
	s_add_u32 m0, s1, 45056
	v_mov_b32_e32 v211, 0
	v_mov_b32_e32 v232, 0
	global_load_lds_dwordx4 v159, s[86:87]
	s_add_u32 s86, s86, 128
	s_addc_u32 s87, s87, 0
	v_mov_b32_e32 v233, 0
	v_mov_b32_e32 v234, 0
	v_mov_b32_e32 v235, 0
	v_mov_b32_e32 v236, 0
	v_mov_b32_e32 v237, 0
	v_mov_b32_e32 v238, 0
	v_mov_b32_e32 v239, 0
	v_mov_b32_e32 v240, 0
	v_mov_b32_e32 v241, 0
	v_mov_b32_e32 v242, 0
	v_mov_b32_e32 v243, 0
	v_mov_b32_e32 v248, 0
	v_mov_b32_e32 v249, 0
	v_mov_b32_e32 v250, 0
	v_mov_b32_e32 v251, 0
	v_mov_b32_e32 v252, 0
	v_mov_b32_e32 v253, 0
	v_mov_b32_e32 v254, 0
	v_mov_b32_e32 v255, 0
	v_mov_b32_e32 v100, 0
	v_mov_b32_e32 v101, 0
	v_mov_b32_e32 v102, 0
	v_mov_b32_e32 v103, 0
	v_mov_b32_e32 v104, 0
	v_mov_b32_e32 v105, 0
	v_mov_b32_e32 v106, 0
	v_mov_b32_e32 v107, 0
	v_mov_b32_e32 v108, 0
	v_mov_b32_e32 v109, 0
	v_mov_b32_e32 v110, 0
	v_mov_b32_e32 v111, 0
	v_mov_b32_e32 v112, 0
	v_mov_b32_e32 v113, 0
	v_mov_b32_e32 v114, 0
	v_mov_b32_e32 v115, 0
	v_mov_b32_e32 v116, 0
	v_mov_b32_e32 v117, 0
	v_mov_b32_e32 v118, 0
	v_mov_b32_e32 v119, 0
	v_mov_b32_e32 v120, 0
	v_mov_b32_e32 v121, 0
	v_mov_b32_e32 v122, 0
	v_mov_b32_e32 v123, 0
	v_mov_b32_e32 v124, 0
	v_mov_b32_e32 v125, 0
	v_mov_b32_e32 v126, 0
	v_mov_b32_e32 v127, 0
	s_waitcnt vmcnt(12)
	s_barrier
	ds_read_b128 v[160:163], v212 offset:0
	ds_read_b128 v[176:179], v212 offset:2048
	ds_read_b128 v[180:183], v212 offset:4096
	ds_read_b128 v[188:191], v212 offset:6144
	ds_read_b128 v[192:195], v212 offset:8192
	global_load_dwordx4 v[96:99], v142, s[84:85] offset:0
	s_waitcnt lgkmcnt(4)
	v_mfma_f32_16x16x32_bf16 v[0:3], v[64:67], v[160:163], v[0:3]
	v_mfma_f32_16x16x32_bf16 v[32:35], v[68:71], v[160:163], v[32:35]
	v_mfma_f32_16x16x32_bf16 v[144:147], v[72:75], v[160:163], v[144:147]
	v_mfma_f32_16x16x32_bf16 v[252:255], v[76:79], v[160:163], v[252:255]
	ds_read_b128 v[196:199], v212 offset:10240
	global_load_dwordx4 v[164:167], v150, s[84:85] offset:0
	s_waitcnt lgkmcnt(4)
	v_mfma_f32_16x16x32_bf16 v[4:7], v[64:67], v[176:179], v[4:7]
	v_mfma_f32_16x16x32_bf16 v[36:39], v[68:71], v[176:179], v[36:39]
	v_mfma_f32_16x16x32_bf16 v[184:187], v[72:75], v[176:179], v[184:187]
	v_mfma_f32_16x16x32_bf16 v[100:103], v[76:79], v[176:179], v[100:103]
	ds_read_b128 v[160:163], v212 offset:12288
	global_load_dwordx4 v[168:171], v142, s[92:93] offset:0
	s_waitcnt lgkmcnt(4)
	v_mfma_f32_16x16x32_bf16 v[8:11], v[64:67], v[180:183], v[8:11]
	v_mfma_f32_16x16x32_bf16 v[40:43], v[68:71], v[180:183], v[40:43]
	v_mfma_f32_16x16x32_bf16 v[204:207], v[72:75], v[180:183], v[204:207]
	v_mfma_f32_16x16x32_bf16 v[104:107], v[76:79], v[180:183], v[104:107]
	ds_read_b128 v[176:179], v212 offset:14336
	global_load_dwordx4 v[172:175], v150, s[92:93] offset:0
	s_waitcnt lgkmcnt(4)
	v_mfma_f32_16x16x32_bf16 v[12:15], v[64:67], v[188:191], v[12:15]
	v_mfma_f32_16x16x32_bf16 v[44:47], v[68:71], v[188:191], v[44:47]
	v_mfma_f32_16x16x32_bf16 v[208:211], v[72:75], v[188:191], v[208:211]
	v_mfma_f32_16x16x32_bf16 v[108:111], v[76:79], v[188:191], v[108:111]
	ds_read_b128 v[180:183], v213 offset:0
	s_waitcnt lgkmcnt(4)
	v_mfma_f32_16x16x32_bf16 v[16:19], v[64:67], v[192:195], v[16:19]
	v_mfma_f32_16x16x32_bf16 v[48:51], v[68:71], v[192:195], v[48:51]
	v_mfma_f32_16x16x32_bf16 v[232:235], v[72:75], v[192:195], v[232:235]
	v_mfma_f32_16x16x32_bf16 v[112:115], v[76:79], v[192:195], v[112:115]
	ds_read_b128 v[188:191], v213 offset:2048
	s_waitcnt lgkmcnt(4)
	v_mfma_f32_16x16x32_bf16 v[20:23], v[64:67], v[196:199], v[20:23]
	v_mfma_f32_16x16x32_bf16 v[52:55], v[68:71], v[196:199], v[52:55]
	v_mfma_f32_16x16x32_bf16 v[236:239], v[72:75], v[196:199], v[236:239]
	v_mfma_f32_16x16x32_bf16 v[116:119], v[76:79], v[196:199], v[116:119]
	ds_read_b128 v[192:195], v213 offset:4096
	s_waitcnt lgkmcnt(4)
	v_mfma_f32_16x16x32_bf16 v[24:27], v[64:67], v[160:163], v[24:27]
	v_mfma_f32_16x16x32_bf16 v[56:59], v[68:71], v[160:163], v[56:59]
	v_mfma_f32_16x16x32_bf16 v[240:243], v[72:75], v[160:163], v[240:243]
	v_mfma_f32_16x16x32_bf16 v[120:123], v[76:79], v[160:163], v[120:123]
	ds_read_b128 v[196:199], v213 offset:6144
	s_waitcnt lgkmcnt(4)
	v_mfma_f32_16x16x32_bf16 v[28:31], v[64:67], v[176:179], v[28:31]
	v_mfma_f32_16x16x32_bf16 v[60:63], v[68:71], v[176:179], v[60:63]
	v_mfma_f32_16x16x32_bf16 v[248:251], v[72:75], v[176:179], v[248:251]
	v_mfma_f32_16x16x32_bf16 v[124:127], v[76:79], v[176:179], v[124:127]
	s_waitcnt vmcnt(8)
	s_barrier
	s_waitcnt vmcnt(12)
	ds_read_b128 v[160:163], v213 offset:8192
	global_load_dwordx4 v[64:67], v142, s[84:85] offset:1024
	s_waitcnt lgkmcnt(4)
	v_mfma_f32_16x16x32_bf16 v[0:3], v[80:83], v[180:183], v[0:3]
	v_mfma_f32_16x16x32_bf16 v[32:35], v[84:87], v[180:183], v[32:35]
	v_mfma_f32_16x16x32_bf16 v[144:147], v[88:91], v[180:183], v[144:147]
	v_mfma_f32_16x16x32_bf16 v[252:255], v[92:95], v[180:183], v[252:255]
	ds_read_b128 v[176:179], v213 offset:10240
	global_load_dwordx4 v[68:71], v150, s[84:85] offset:1024
	s_waitcnt lgkmcnt(4)
	v_mfma_f32_16x16x32_bf16 v[4:7], v[80:83], v[188:191], v[4:7]
	v_mfma_f32_16x16x32_bf16 v[36:39], v[84:87], v[188:191], v[36:39]
	v_mfma_f32_16x16x32_bf16 v[184:187], v[88:91], v[188:191], v[184:187]
	v_mfma_f32_16x16x32_bf16 v[100:103], v[92:95], v[188:191], v[100:103]
	ds_read_b128 v[180:183], v213 offset:12288
	global_load_dwordx4 v[72:75], v142, s[92:93] offset:1024
	s_waitcnt lgkmcnt(4)
	v_mfma_f32_16x16x32_bf16 v[8:11], v[80:83], v[192:195], v[8:11]
	v_mfma_f32_16x16x32_bf16 v[40:43], v[84:87], v[192:195], v[40:43]
	v_mfma_f32_16x16x32_bf16 v[204:207], v[88:91], v[192:195], v[204:207]
	v_mfma_f32_16x16x32_bf16 v[104:107], v[92:95], v[192:195], v[104:107]
	ds_read_b128 v[188:191], v213 offset:14336
	global_load_dwordx4 v[76:79], v150, s[92:93] offset:1024
	s_add_u32 s84, s84, 0x800
	s_addc_u32 s85, s85, 0
	s_add_u32 s92, s92, 0x800
	s_addc_u32 s93, s93, 0
	s_waitcnt lgkmcnt(4)
	v_mfma_f32_16x16x32_bf16 v[12:15], v[80:83], v[196:199], v[12:15]
	v_mfma_f32_16x16x32_bf16 v[44:47], v[84:87], v[196:199], v[44:47]
	v_mfma_f32_16x16x32_bf16 v[208:211], v[88:91], v[196:199], v[208:211]
	v_mfma_f32_16x16x32_bf16 v[108:111], v[92:95], v[196:199], v[108:111]
	ds_read_b128 v[192:195], v212 offset:16384
	s_add_u32 m0, s1, 49152
	s_nop 0
	global_load_lds_dwordx4 v151, s[86:87]
	s_waitcnt lgkmcnt(4)
	v_mfma_f32_16x16x32_bf16 v[16:19], v[80:83], v[160:163], v[16:19]
	v_mfma_f32_16x16x32_bf16 v[48:51], v[84:87], v[160:163], v[48:51]
	v_mfma_f32_16x16x32_bf16 v[232:235], v[88:91], v[160:163], v[232:235]
	v_mfma_f32_16x16x32_bf16 v[112:115], v[92:95], v[160:163], v[112:115]
	ds_read_b128 v[196:199], v212 offset:18432
	s_add_u32 m0, s1, 53248
	s_nop 0
	global_load_lds_dwordx4 v156, s[86:87]
	s_waitcnt lgkmcnt(4)
	v_mfma_f32_16x16x32_bf16 v[20:23], v[80:83], v[176:179], v[20:23]
	v_mfma_f32_16x16x32_bf16 v[52:55], v[84:87], v[176:179], v[52:55]
	v_mfma_f32_16x16x32_bf16 v[236:239], v[88:91], v[176:179], v[236:239]
	v_mfma_f32_16x16x32_bf16 v[116:119], v[92:95], v[176:179], v[116:119]
	ds_read_b128 v[160:163], v212 offset:20480
	s_add_u32 m0, s1, 57344
	s_nop 0
	global_load_lds_dwordx4 v158, s[86:87]
	s_waitcnt lgkmcnt(4)
	v_mfma_f32_16x16x32_bf16 v[24:27], v[80:83], v[180:183], v[24:27]
	v_mfma_f32_16x16x32_bf16 v[56:59], v[84:87], v[180:183], v[56:59]
	v_mfma_f32_16x16x32_bf16 v[240:243], v[88:91], v[180:183], v[240:243]
	v_mfma_f32_16x16x32_bf16 v[120:123], v[92:95], v[180:183], v[120:123]
	ds_read_b128 v[176:179], v212 offset:22528
	s_add_u32 m0, s1, 61440
	s_nop 0
	global_load_lds_dwordx4 v159, s[86:87]
	s_add_u32 s86, s86, 128
	s_addc_u32 s87, s87, 0
	s_waitcnt lgkmcnt(4)
	v_mfma_f32_16x16x32_bf16 v[28:31], v[80:83], v[188:191], v[28:31]
	v_mfma_f32_16x16x32_bf16 v[60:63], v[84:87], v[188:191], v[60:63]
	v_mfma_f32_16x16x32_bf16 v[248:251], v[88:91], v[188:191], v[248:251]
	v_mfma_f32_16x16x32_bf16 v[124:127], v[92:95], v[188:191], v[124:127]
	s_waitcnt vmcnt(8)
	ds_read_b128 v[180:183], v212 offset:24576
	global_load_dwordx4 v[80:83], v142, s[84:85] offset:0
	s_waitcnt lgkmcnt(4)
	v_mfma_f32_16x16x32_bf16 v[0:3], v[96:99], v[192:195], v[0:3]
	v_mfma_f32_16x16x32_bf16 v[32:35], v[164:167], v[192:195], v[32:35]
	v_mfma_f32_16x16x32_bf16 v[144:147], v[168:171], v[192:195], v[144:147]
	v_mfma_f32_16x16x32_bf16 v[252:255], v[172:175], v[192:195], v[252:255]
	ds_read_b128 v[188:191], v212 offset:26624
	global_load_dwordx4 v[84:87], v150, s[84:85] offset:0
	s_waitcnt lgkmcnt(4)
	v_mfma_f32_16x16x32_bf16 v[4:7], v[96:99], v[196:199], v[4:7]
	v_mfma_f32_16x16x32_bf16 v[36:39], v[164:167], v[196:199], v[36:39]
	v_mfma_f32_16x16x32_bf16 v[184:187], v[168:171], v[196:199], v[184:187]
	v_mfma_f32_16x16x32_bf16 v[100:103], v[172:175], v[196:199], v[100:103]
	ds_read_b128 v[192:195], v212 offset:28672
	global_load_dwordx4 v[88:91], v142, s[92:93] offset:0
	s_waitcnt lgkmcnt(4)
	v_mfma_f32_16x16x32_bf16 v[8:11], v[96:99], v[160:163], v[8:11]
	v_mfma_f32_16x16x32_bf16 v[40:43], v[164:167], v[160:163], v[40:43]
	v_mfma_f32_16x16x32_bf16 v[204:207], v[168:171], v[160:163], v[204:207]
	v_mfma_f32_16x16x32_bf16 v[104:107], v[172:175], v[160:163], v[104:107]
	ds_read_b128 v[196:199], v212 offset:30720
	global_load_dwordx4 v[92:95], v150, s[92:93] offset:0
	s_waitcnt lgkmcnt(4)
	v_mfma_f32_16x16x32_bf16 v[12:15], v[96:99], v[176:179], v[12:15]
	v_mfma_f32_16x16x32_bf16 v[44:47], v[164:167], v[176:179], v[44:47]
	v_mfma_f32_16x16x32_bf16 v[208:211], v[168:171], v[176:179], v[208:211]
	v_mfma_f32_16x16x32_bf16 v[108:111], v[172:175], v[176:179], v[108:111]
	ds_read_b128 v[160:163], v213 offset:16384
	s_waitcnt lgkmcnt(4)
	v_mfma_f32_16x16x32_bf16 v[16:19], v[96:99], v[180:183], v[16:19]
	v_mfma_f32_16x16x32_bf16 v[48:51], v[164:167], v[180:183], v[48:51]
	v_mfma_f32_16x16x32_bf16 v[232:235], v[168:171], v[180:183], v[232:235]
	v_mfma_f32_16x16x32_bf16 v[112:115], v[172:175], v[180:183], v[112:115]
	ds_read_b128 v[176:179], v213 offset:18432
	s_waitcnt lgkmcnt(4)
	v_mfma_f32_16x16x32_bf16 v[20:23], v[96:99], v[188:191], v[20:23]
	v_mfma_f32_16x16x32_bf16 v[52:55], v[164:167], v[188:191], v[52:55]
	v_mfma_f32_16x16x32_bf16 v[236:239], v[168:171], v[188:191], v[236:239]
	v_mfma_f32_16x16x32_bf16 v[116:119], v[172:175], v[188:191], v[116:119]
	ds_read_b128 v[180:183], v213 offset:20480
	s_waitcnt lgkmcnt(4)
	v_mfma_f32_16x16x32_bf16 v[24:27], v[96:99], v[192:195], v[24:27]
	v_mfma_f32_16x16x32_bf16 v[56:59], v[164:167], v[192:195], v[56:59]
	v_mfma_f32_16x16x32_bf16 v[240:243], v[168:171], v[192:195], v[240:243]
	v_mfma_f32_16x16x32_bf16 v[120:123], v[172:175], v[192:195], v[120:123]
	ds_read_b128 v[188:191], v213 offset:22528
	s_waitcnt lgkmcnt(4)
	v_mfma_f32_16x16x32_bf16 v[28:31], v[96:99], v[196:199], v[28:31]
	v_mfma_f32_16x16x32_bf16 v[60:63], v[164:167], v[196:199], v[60:63]
	v_mfma_f32_16x16x32_bf16 v[248:251], v[168:171], v[196:199], v[248:251]
	v_mfma_f32_16x16x32_bf16 v[124:127], v[172:175], v[196:199], v[124:127]
	s_waitcnt vmcnt(16)
	s_barrier
	s_waitcnt vmcnt(8)
	ds_read_b128 v[192:195], v213 offset:24576
	global_load_dwordx4 v[96:99], v142, s[84:85] offset:1024
	s_waitcnt lgkmcnt(4)
	v_mfma_f32_16x16x32_bf16 v[0:3], v[64:67], v[160:163], v[0:3]
	v_mfma_f32_16x16x32_bf16 v[32:35], v[68:71], v[160:163], v[32:35]
	v_mfma_f32_16x16x32_bf16 v[144:147], v[72:75], v[160:163], v[144:147]
	v_mfma_f32_16x16x32_bf16 v[252:255], v[76:79], v[160:163], v[252:255]
	ds_read_b128 v[196:199], v213 offset:26624
	global_load_dwordx4 v[164:167], v150, s[84:85] offset:1024
	s_waitcnt lgkmcnt(4)
	v_mfma_f32_16x16x32_bf16 v[4:7], v[64:67], v[176:179], v[4:7]
	v_mfma_f32_16x16x32_bf16 v[36:39], v[68:71], v[176:179], v[36:39]
	v_mfma_f32_16x16x32_bf16 v[184:187], v[72:75], v[176:179], v[184:187]
	v_mfma_f32_16x16x32_bf16 v[100:103], v[76:79], v[176:179], v[100:103]
	ds_read_b128 v[160:163], v213 offset:28672
	global_load_dwordx4 v[168:171], v142, s[92:93] offset:1024
	s_waitcnt lgkmcnt(4)
	v_mfma_f32_16x16x32_bf16 v[8:11], v[64:67], v[180:183], v[8:11]
	v_mfma_f32_16x16x32_bf16 v[40:43], v[68:71], v[180:183], v[40:43]
	v_mfma_f32_16x16x32_bf16 v[204:207], v[72:75], v[180:183], v[204:207]
	v_mfma_f32_16x16x32_bf16 v[104:107], v[76:79], v[180:183], v[104:107]
	ds_read_b128 v[176:179], v213 offset:30720
	global_load_dwordx4 v[172:175], v150, s[92:93] offset:1024
	s_add_u32 s84, s84, 0x800
	s_addc_u32 s85, s85, 0
	s_add_u32 s92, s92, 0x800
	s_addc_u32 s93, s93, 0
	s_waitcnt lgkmcnt(4)
	v_mfma_f32_16x16x32_bf16 v[12:15], v[64:67], v[188:191], v[12:15]
	v_mfma_f32_16x16x32_bf16 v[44:47], v[68:71], v[188:191], v[44:47]
	v_mfma_f32_16x16x32_bf16 v[208:211], v[72:75], v[188:191], v[208:211]
	v_mfma_f32_16x16x32_bf16 v[108:111], v[76:79], v[188:191], v[108:111]
	ds_read_b128 v[180:183], v212 offset:32768
	s_add_u32 m0, s1, 0
	s_nop 0
	global_load_lds_dwordx4 v151, s[86:87]
	s_waitcnt lgkmcnt(4)
	v_mfma_f32_16x16x32_bf16 v[16:19], v[64:67], v[192:195], v[16:19]
	v_mfma_f32_16x16x32_bf16 v[48:51], v[68:71], v[192:195], v[48:51]
	v_mfma_f32_16x16x32_bf16 v[232:235], v[72:75], v[192:195], v[232:235]
	v_mfma_f32_16x16x32_bf16 v[112:115], v[76:79], v[192:195], v[112:115]
	ds_read_b128 v[188:191], v212 offset:34816
	s_add_u32 m0, s1, 4096
	s_nop 0
	global_load_lds_dwordx4 v156, s[86:87]
	s_waitcnt lgkmcnt(4)
	v_mfma_f32_16x16x32_bf16 v[20:23], v[64:67], v[196:199], v[20:23]
	v_mfma_f32_16x16x32_bf16 v[52:55], v[68:71], v[196:199], v[52:55]
	v_mfma_f32_16x16x32_bf16 v[236:239], v[72:75], v[196:199], v[236:239]
	v_mfma_f32_16x16x32_bf16 v[116:119], v[76:79], v[196:199], v[116:119]
	ds_read_b128 v[192:195], v212 offset:36864
	s_add_u32 m0, s1, 8192
	s_nop 0
	global_load_lds_dwordx4 v158, s[86:87]
	s_waitcnt lgkmcnt(4)
	v_mfma_f32_16x16x32_bf16 v[24:27], v[64:67], v[160:163], v[24:27]
	v_mfma_f32_16x16x32_bf16 v[56:59], v[68:71], v[160:163], v[56:59]
	v_mfma_f32_16x16x32_bf16 v[240:243], v[72:75], v[160:163], v[240:243]
	v_mfma_f32_16x16x32_bf16 v[120:123], v[76:79], v[160:163], v[120:123]
	ds_read_b128 v[196:199], v212 offset:38912
	s_add_u32 m0, s1, 12288
	s_nop 0
	global_load_lds_dwordx4 v159, s[86:87]
	s_add_u32 s86, s86, 128
	s_addc_u32 s87, s87, 0
	s_waitcnt lgkmcnt(4)
	v_mfma_f32_16x16x32_bf16 v[28:31], v[64:67], v[176:179], v[28:31]
	v_mfma_f32_16x16x32_bf16 v[60:63], v[68:71], v[176:179], v[60:63]
	v_mfma_f32_16x16x32_bf16 v[248:251], v[72:75], v[176:179], v[248:251]
	v_mfma_f32_16x16x32_bf16 v[124:127], v[76:79], v[176:179], v[124:127]
	s_waitcnt vmcnt(8)
	ds_read_b128 v[160:163], v212 offset:40960
	global_load_dwordx4 v[64:67], v142, s[84:85] offset:0
	s_waitcnt lgkmcnt(4)
	v_mfma_f32_16x16x32_bf16 v[0:3], v[80:83], v[180:183], v[0:3]
	v_mfma_f32_16x16x32_bf16 v[32:35], v[84:87], v[180:183], v[32:35]
	v_mfma_f32_16x16x32_bf16 v[144:147], v[88:91], v[180:183], v[144:147]
	v_mfma_f32_16x16x32_bf16 v[252:255], v[92:95], v[180:183], v[252:255]
	ds_read_b128 v[176:179], v212 offset:43008
	global_load_dwordx4 v[68:71], v150, s[84:85] offset:0
	s_waitcnt lgkmcnt(4)
	v_mfma_f32_16x16x32_bf16 v[4:7], v[80:83], v[188:191], v[4:7]
	v_mfma_f32_16x16x32_bf16 v[36:39], v[84:87], v[188:191], v[36:39]
	v_mfma_f32_16x16x32_bf16 v[184:187], v[88:91], v[188:191], v[184:187]
	v_mfma_f32_16x16x32_bf16 v[100:103], v[92:95], v[188:191], v[100:103]
	ds_read_b128 v[180:183], v212 offset:45056
	global_load_dwordx4 v[72:75], v142, s[92:93] offset:0
	s_waitcnt lgkmcnt(4)
	v_mfma_f32_16x16x32_bf16 v[8:11], v[80:83], v[192:195], v[8:11]
	v_mfma_f32_16x16x32_bf16 v[40:43], v[84:87], v[192:195], v[40:43]
	v_mfma_f32_16x16x32_bf16 v[204:207], v[88:91], v[192:195], v[204:207]
	v_mfma_f32_16x16x32_bf16 v[104:107], v[92:95], v[192:195], v[104:107]
	ds_read_b128 v[188:191], v212 offset:47104
	global_load_dwordx4 v[76:79], v150, s[92:93] offset:0
	s_waitcnt lgkmcnt(4)
	v_mfma_f32_16x16x32_bf16 v[12:15], v[80:83], v[196:199], v[12:15]
	v_mfma_f32_16x16x32_bf16 v[44:47], v[84:87], v[196:199], v[44:47]
	v_mfma_f32_16x16x32_bf16 v[208:211], v[88:91], v[196:199], v[208:211]
	v_mfma_f32_16x16x32_bf16 v[108:111], v[92:95], v[196:199], v[108:111]
	ds_read_b128 v[192:195], v213 offset:32768
	s_waitcnt lgkmcnt(4)
	v_mfma_f32_16x16x32_bf16 v[16:19], v[80:83], v[160:163], v[16:19]
	v_mfma_f32_16x16x32_bf16 v[48:51], v[84:87], v[160:163], v[48:51]
	v_mfma_f32_16x16x32_bf16 v[232:235], v[88:91], v[160:163], v[232:235]
	v_mfma_f32_16x16x32_bf16 v[112:115], v[92:95], v[160:163], v[112:115]
	ds_read_b128 v[196:199], v213 offset:34816
	s_waitcnt lgkmcnt(4)
	v_mfma_f32_16x16x32_bf16 v[20:23], v[80:83], v[176:179], v[20:23]
	v_mfma_f32_16x16x32_bf16 v[52:55], v[84:87], v[176:179], v[52:55]
	v_mfma_f32_16x16x32_bf16 v[236:239], v[88:91], v[176:179], v[236:239]
	v_mfma_f32_16x16x32_bf16 v[116:119], v[92:95], v[176:179], v[116:119]
	ds_read_b128 v[160:163], v213 offset:36864
	s_waitcnt lgkmcnt(4)
	v_mfma_f32_16x16x32_bf16 v[24:27], v[80:83], v[180:183], v[24:27]
	v_mfma_f32_16x16x32_bf16 v[56:59], v[84:87], v[180:183], v[56:59]
	v_mfma_f32_16x16x32_bf16 v[240:243], v[88:91], v[180:183], v[240:243]
	v_mfma_f32_16x16x32_bf16 v[120:123], v[92:95], v[180:183], v[120:123]
	ds_read_b128 v[176:179], v213 offset:38912
	s_waitcnt lgkmcnt(4)
	v_mfma_f32_16x16x32_bf16 v[28:31], v[80:83], v[188:191], v[28:31]
	v_mfma_f32_16x16x32_bf16 v[60:63], v[84:87], v[188:191], v[60:63]
	v_mfma_f32_16x16x32_bf16 v[248:251], v[88:91], v[188:191], v[248:251]
	v_mfma_f32_16x16x32_bf16 v[124:127], v[92:95], v[188:191], v[124:127]
	s_waitcnt vmcnt(16)
	s_barrier
	s_waitcnt vmcnt(8)
	ds_read_b128 v[180:183], v213 offset:40960
	global_load_dwordx4 v[80:83], v142, s[84:85] offset:1024
	s_waitcnt lgkmcnt(4)
	v_mfma_f32_16x16x32_bf16 v[0:3], v[96:99], v[192:195], v[0:3]
	v_mfma_f32_16x16x32_bf16 v[32:35], v[164:167], v[192:195], v[32:35]
	v_mfma_f32_16x16x32_bf16 v[144:147], v[168:171], v[192:195], v[144:147]
	v_mfma_f32_16x16x32_bf16 v[252:255], v[172:175], v[192:195], v[252:255]
	ds_read_b128 v[188:191], v213 offset:43008
	global_load_dwordx4 v[84:87], v150, s[84:85] offset:1024
	s_waitcnt lgkmcnt(4)
	v_mfma_f32_16x16x32_bf16 v[4:7], v[96:99], v[196:199], v[4:7]
	v_mfma_f32_16x16x32_bf16 v[36:39], v[164:167], v[196:199], v[36:39]
	v_mfma_f32_16x16x32_bf16 v[184:187], v[168:171], v[196:199], v[184:187]
	v_mfma_f32_16x16x32_bf16 v[100:103], v[172:175], v[196:199], v[100:103]
	ds_read_b128 v[192:195], v213 offset:45056
	global_load_dwordx4 v[88:91], v142, s[92:93] offset:1024
	s_waitcnt lgkmcnt(4)
	v_mfma_f32_16x16x32_bf16 v[8:11], v[96:99], v[160:163], v[8:11]
	v_mfma_f32_16x16x32_bf16 v[40:43], v[164:167], v[160:163], v[40:43]
	v_mfma_f32_16x16x32_bf16 v[204:207], v[168:171], v[160:163], v[204:207]
	v_mfma_f32_16x16x32_bf16 v[104:107], v[172:175], v[160:163], v[104:107]
	ds_read_b128 v[196:199], v213 offset:47104
	global_load_dwordx4 v[92:95], v150, s[92:93] offset:1024
	s_add_u32 s84, s84, 0x800
	s_addc_u32 s85, s85, 0
	s_add_u32 s92, s92, 0x800
	s_addc_u32 s93, s93, 0
	s_waitcnt lgkmcnt(4)
	v_mfma_f32_16x16x32_bf16 v[12:15], v[96:99], v[176:179], v[12:15]
	v_mfma_f32_16x16x32_bf16 v[44:47], v[164:167], v[176:179], v[44:47]
	v_mfma_f32_16x16x32_bf16 v[208:211], v[168:171], v[176:179], v[208:211]
	v_mfma_f32_16x16x32_bf16 v[108:111], v[172:175], v[176:179], v[108:111]
	ds_read_b128 v[160:163], v212 offset:49152
	s_add_u32 m0, s1, 16384
	s_nop 0
	global_load_lds_dwordx4 v151, s[86:87]
	s_waitcnt lgkmcnt(4)
	v_mfma_f32_16x16x32_bf16 v[16:19], v[96:99], v[180:183], v[16:19]
	v_mfma_f32_16x16x32_bf16 v[48:51], v[164:167], v[180:183], v[48:51]
	v_mfma_f32_16x16x32_bf16 v[232:235], v[168:171], v[180:183], v[232:235]
	v_mfma_f32_16x16x32_bf16 v[112:115], v[172:175], v[180:183], v[112:115]
	ds_read_b128 v[176:179], v212 offset:51200
	s_add_u32 m0, s1, 20480
	s_nop 0
	global_load_lds_dwordx4 v156, s[86:87]
	s_waitcnt lgkmcnt(4)
	v_mfma_f32_16x16x32_bf16 v[20:23], v[96:99], v[188:191], v[20:23]
	v_mfma_f32_16x16x32_bf16 v[52:55], v[164:167], v[188:191], v[52:55]
	v_mfma_f32_16x16x32_bf16 v[236:239], v[168:171], v[188:191], v[236:239]
	v_mfma_f32_16x16x32_bf16 v[116:119], v[172:175], v[188:191], v[116:119]
	ds_read_b128 v[180:183], v212 offset:53248
	s_add_u32 m0, s1, 24576
	s_nop 0
	global_load_lds_dwordx4 v158, s[86:87]
	s_waitcnt lgkmcnt(4)
	v_mfma_f32_16x16x32_bf16 v[24:27], v[96:99], v[192:195], v[24:27]
	v_mfma_f32_16x16x32_bf16 v[56:59], v[164:167], v[192:195], v[56:59]
	v_mfma_f32_16x16x32_bf16 v[240:243], v[168:171], v[192:195], v[240:243]
	v_mfma_f32_16x16x32_bf16 v[120:123], v[172:175], v[192:195], v[120:123]
	ds_read_b128 v[188:191], v212 offset:55296
	s_add_u32 m0, s1, 28672
	s_nop 0
	global_load_lds_dwordx4 v159, s[86:87]
	s_add_u32 s86, s86, 128
	s_addc_u32 s87, s87, 0
	s_waitcnt lgkmcnt(4)
	v_mfma_f32_16x16x32_bf16 v[28:31], v[96:99], v[196:199], v[28:31]
	v_mfma_f32_16x16x32_bf16 v[60:63], v[164:167], v[196:199], v[60:63]
	v_mfma_f32_16x16x32_bf16 v[248:251], v[168:171], v[196:199], v[248:251]
	v_mfma_f32_16x16x32_bf16 v[124:127], v[172:175], v[196:199], v[124:127]
	s_waitcnt vmcnt(8)
	ds_read_b128 v[192:195], v212 offset:57344
	global_load_dwordx4 v[96:99], v142, s[84:85] offset:0
	s_waitcnt lgkmcnt(4)
	v_mfma_f32_16x16x32_bf16 v[0:3], v[64:67], v[160:163], v[0:3]
	v_mfma_f32_16x16x32_bf16 v[32:35], v[68:71], v[160:163], v[32:35]
	v_mfma_f32_16x16x32_bf16 v[144:147], v[72:75], v[160:163], v[144:147]
	v_mfma_f32_16x16x32_bf16 v[252:255], v[76:79], v[160:163], v[252:255]
	ds_read_b128 v[196:199], v212 offset:59392
	global_load_dwordx4 v[164:167], v150, s[84:85] offset:0
	s_waitcnt lgkmcnt(4)
	v_mfma_f32_16x16x32_bf16 v[4:7], v[64:67], v[176:179], v[4:7]
	v_mfma_f32_16x16x32_bf16 v[36:39], v[68:71], v[176:179], v[36:39]
	v_mfma_f32_16x16x32_bf16 v[184:187], v[72:75], v[176:179], v[184:187]
	v_mfma_f32_16x16x32_bf16 v[100:103], v[76:79], v[176:179], v[100:103]
	ds_read_b128 v[160:163], v212 offset:61440
	global_load_dwordx4 v[168:171], v142, s[92:93] offset:0
	s_waitcnt lgkmcnt(4)
	v_mfma_f32_16x16x32_bf16 v[8:11], v[64:67], v[180:183], v[8:11]
	v_mfma_f32_16x16x32_bf16 v[40:43], v[68:71], v[180:183], v[40:43]
	v_mfma_f32_16x16x32_bf16 v[204:207], v[72:75], v[180:183], v[204:207]
	v_mfma_f32_16x16x32_bf16 v[104:107], v[76:79], v[180:183], v[104:107]
	ds_read_b128 v[176:179], v212 offset:63488
	global_load_dwordx4 v[172:175], v150, s[92:93] offset:0
	s_waitcnt lgkmcnt(4)
	v_mfma_f32_16x16x32_bf16 v[12:15], v[64:67], v[188:191], v[12:15]
	v_mfma_f32_16x16x32_bf16 v[44:47], v[68:71], v[188:191], v[44:47]
	v_mfma_f32_16x16x32_bf16 v[208:211], v[72:75], v[188:191], v[208:211]
	v_mfma_f32_16x16x32_bf16 v[108:111], v[76:79], v[188:191], v[108:111]
	ds_read_b128 v[180:183], v213 offset:49152
	s_waitcnt lgkmcnt(4)
	v_mfma_f32_16x16x32_bf16 v[16:19], v[64:67], v[192:195], v[16:19]
	v_mfma_f32_16x16x32_bf16 v[48:51], v[68:71], v[192:195], v[48:51]
	v_mfma_f32_16x16x32_bf16 v[232:235], v[72:75], v[192:195], v[232:235]
	v_mfma_f32_16x16x32_bf16 v[112:115], v[76:79], v[192:195], v[112:115]
	ds_read_b128 v[188:191], v213 offset:51200
	s_waitcnt lgkmcnt(4)
	v_mfma_f32_16x16x32_bf16 v[20:23], v[64:67], v[196:199], v[20:23]
	v_mfma_f32_16x16x32_bf16 v[52:55], v[68:71], v[196:199], v[52:55]
	v_mfma_f32_16x16x32_bf16 v[236:239], v[72:75], v[196:199], v[236:239]
	v_mfma_f32_16x16x32_bf16 v[116:119], v[76:79], v[196:199], v[116:119]
	ds_read_b128 v[192:195], v213 offset:53248
	s_waitcnt lgkmcnt(4)
	v_mfma_f32_16x16x32_bf16 v[24:27], v[64:67], v[160:163], v[24:27]
	v_mfma_f32_16x16x32_bf16 v[56:59], v[68:71], v[160:163], v[56:59]
	v_mfma_f32_16x16x32_bf16 v[240:243], v[72:75], v[160:163], v[240:243]
	v_mfma_f32_16x16x32_bf16 v[120:123], v[76:79], v[160:163], v[120:123]
	ds_read_b128 v[196:199], v213 offset:55296
	s_waitcnt lgkmcnt(4)
	v_mfma_f32_16x16x32_bf16 v[28:31], v[64:67], v[176:179], v[28:31]
	v_mfma_f32_16x16x32_bf16 v[60:63], v[68:71], v[176:179], v[60:63]
	v_mfma_f32_16x16x32_bf16 v[248:251], v[72:75], v[176:179], v[248:251]
	v_mfma_f32_16x16x32_bf16 v[124:127], v[76:79], v[176:179], v[124:127]
	s_waitcnt vmcnt(16)
	s_barrier
	s_waitcnt vmcnt(8)
	ds_read_b128 v[160:163], v213 offset:57344
	global_load_dwordx4 v[64:67], v142, s[84:85] offset:1024
	s_waitcnt lgkmcnt(4)
	v_mfma_f32_16x16x32_bf16 v[0:3], v[80:83], v[180:183], v[0:3]
	v_mfma_f32_16x16x32_bf16 v[32:35], v[84:87], v[180:183], v[32:35]
	v_mfma_f32_16x16x32_bf16 v[144:147], v[88:91], v[180:183], v[144:147]
	v_mfma_f32_16x16x32_bf16 v[252:255], v[92:95], v[180:183], v[252:255]
	ds_read_b128 v[176:179], v213 offset:59392
	global_load_dwordx4 v[68:71], v150, s[84:85] offset:1024
	s_waitcnt lgkmcnt(4)
	v_mfma_f32_16x16x32_bf16 v[4:7], v[80:83], v[188:191], v[4:7]
	v_mfma_f32_16x16x32_bf16 v[36:39], v[84:87], v[188:191], v[36:39]
	v_mfma_f32_16x16x32_bf16 v[184:187], v[88:91], v[188:191], v[184:187]
	v_mfma_f32_16x16x32_bf16 v[100:103], v[92:95], v[188:191], v[100:103]
	ds_read_b128 v[180:183], v213 offset:61440
	global_load_dwordx4 v[72:75], v142, s[92:93] offset:1024
	s_waitcnt lgkmcnt(4)
	v_mfma_f32_16x16x32_bf16 v[8:11], v[80:83], v[192:195], v[8:11]
	v_mfma_f32_16x16x32_bf16 v[40:43], v[84:87], v[192:195], v[40:43]
	v_mfma_f32_16x16x32_bf16 v[204:207], v[88:91], v[192:195], v[204:207]
	v_mfma_f32_16x16x32_bf16 v[104:107], v[92:95], v[192:195], v[104:107]
	ds_read_b128 v[188:191], v213 offset:63488
	global_load_dwordx4 v[76:79], v150, s[92:93] offset:1024
	s_add_u32 s84, s84, 0x800
	s_addc_u32 s85, s85, 0
	s_add_u32 s92, s92, 0x800
	s_addc_u32 s93, s93, 0
	s_waitcnt lgkmcnt(4)
	v_mfma_f32_16x16x32_bf16 v[12:15], v[80:83], v[196:199], v[12:15]
	v_mfma_f32_16x16x32_bf16 v[44:47], v[84:87], v[196:199], v[44:47]
	v_mfma_f32_16x16x32_bf16 v[208:211], v[88:91], v[196:199], v[208:211]
	v_mfma_f32_16x16x32_bf16 v[108:111], v[92:95], v[196:199], v[108:111]
	ds_read_b128 v[192:195], v212 offset:0
	s_add_u32 m0, s1, 32768
	s_nop 0
	global_load_lds_dwordx4 v151, s[86:87]
	s_waitcnt lgkmcnt(4)
	v_mfma_f32_16x16x32_bf16 v[16:19], v[80:83], v[160:163], v[16:19]
	v_mfma_f32_16x16x32_bf16 v[48:51], v[84:87], v[160:163], v[48:51]
	v_mfma_f32_16x16x32_bf16 v[232:235], v[88:91], v[160:163], v[232:235]
	v_mfma_f32_16x16x32_bf16 v[112:115], v[92:95], v[160:163], v[112:115]
	ds_read_b128 v[196:199], v212 offset:2048
	s_add_u32 m0, s1, 36864
	s_nop 0
	global_load_lds_dwordx4 v156, s[86:87]
	s_waitcnt lgkmcnt(4)
	v_mfma_f32_16x16x32_bf16 v[20:23], v[80:83], v[176:179], v[20:23]
	v_mfma_f32_16x16x32_bf16 v[52:55], v[84:87], v[176:179], v[52:55]
	v_mfma_f32_16x16x32_bf16 v[236:239], v[88:91], v[176:179], v[236:239]
	v_mfma_f32_16x16x32_bf16 v[116:119], v[92:95], v[176:179], v[116:119]
	ds_read_b128 v[160:163], v212 offset:4096
	s_add_u32 m0, s1, 40960
	s_nop 0
	global_load_lds_dwordx4 v158, s[86:87]
	s_waitcnt lgkmcnt(4)
	v_mfma_f32_16x16x32_bf16 v[24:27], v[80:83], v[180:183], v[24:27]
	v_mfma_f32_16x16x32_bf16 v[56:59], v[84:87], v[180:183], v[56:59]
	v_mfma_f32_16x16x32_bf16 v[240:243], v[88:91], v[180:183], v[240:243]
	v_mfma_f32_16x16x32_bf16 v[120:123], v[92:95], v[180:183], v[120:123]
	ds_read_b128 v[176:179], v212 offset:6144
	s_add_u32 m0, s1, 45056
	s_nop 0
	global_load_lds_dwordx4 v159, s[86:87]
	s_add_u32 s86, s86, 128
	s_addc_u32 s87, s87, 0
	s_waitcnt lgkmcnt(4)
	v_mfma_f32_16x16x32_bf16 v[28:31], v[80:83], v[188:191], v[28:31]
	v_mfma_f32_16x16x32_bf16 v[60:63], v[84:87], v[188:191], v[60:63]
	v_mfma_f32_16x16x32_bf16 v[248:251], v[88:91], v[188:191], v[248:251]
	v_mfma_f32_16x16x32_bf16 v[124:127], v[92:95], v[188:191], v[124:127]
	s_waitcnt vmcnt(8)
	ds_read_b128 v[180:183], v212 offset:8192
	global_load_dwordx4 v[80:83], v142, s[84:85] offset:0
	s_waitcnt lgkmcnt(4)
	v_mfma_f32_16x16x32_bf16 v[0:3], v[96:99], v[192:195], v[0:3]
	v_mfma_f32_16x16x32_bf16 v[32:35], v[164:167], v[192:195], v[32:35]
	v_mfma_f32_16x16x32_bf16 v[144:147], v[168:171], v[192:195], v[144:147]
	v_mfma_f32_16x16x32_bf16 v[252:255], v[172:175], v[192:195], v[252:255]
	ds_read_b128 v[188:191], v212 offset:10240
	global_load_dwordx4 v[84:87], v150, s[84:85] offset:0
	s_waitcnt lgkmcnt(4)
	v_mfma_f32_16x16x32_bf16 v[4:7], v[96:99], v[196:199], v[4:7]
	v_mfma_f32_16x16x32_bf16 v[36:39], v[164:167], v[196:199], v[36:39]
	v_mfma_f32_16x16x32_bf16 v[184:187], v[168:171], v[196:199], v[184:187]
	v_mfma_f32_16x16x32_bf16 v[100:103], v[172:175], v[196:199], v[100:103]
	ds_read_b128 v[192:195], v212 offset:12288
	global_load_dwordx4 v[88:91], v142, s[92:93] offset:0
	s_waitcnt lgkmcnt(4)
	v_mfma_f32_16x16x32_bf16 v[8:11], v[96:99], v[160:163], v[8:11]
	v_mfma_f32_16x16x32_bf16 v[40:43], v[164:167], v[160:163], v[40:43]
	v_mfma_f32_16x16x32_bf16 v[204:207], v[168:171], v[160:163], v[204:207]
	v_mfma_f32_16x16x32_bf16 v[104:107], v[172:175], v[160:163], v[104:107]
	ds_read_b128 v[196:199], v212 offset:14336
	global_load_dwordx4 v[92:95], v150, s[92:93] offset:0
	s_waitcnt lgkmcnt(4)
	v_mfma_f32_16x16x32_bf16 v[12:15], v[96:99], v[176:179], v[12:15]
	v_mfma_f32_16x16x32_bf16 v[44:47], v[164:167], v[176:179], v[44:47]
	v_mfma_f32_16x16x32_bf16 v[208:211], v[168:171], v[176:179], v[208:211]
	v_mfma_f32_16x16x32_bf16 v[108:111], v[172:175], v[176:179], v[108:111]
	ds_read_b128 v[160:163], v213 offset:0
	s_waitcnt lgkmcnt(4)
	v_mfma_f32_16x16x32_bf16 v[16:19], v[96:99], v[180:183], v[16:19]
	v_mfma_f32_16x16x32_bf16 v[48:51], v[164:167], v[180:183], v[48:51]
	v_mfma_f32_16x16x32_bf16 v[232:235], v[168:171], v[180:183], v[232:235]
	v_mfma_f32_16x16x32_bf16 v[112:115], v[172:175], v[180:183], v[112:115]
	ds_read_b128 v[176:179], v213 offset:2048
	s_waitcnt lgkmcnt(4)
	v_mfma_f32_16x16x32_bf16 v[20:23], v[96:99], v[188:191], v[20:23]
	v_mfma_f32_16x16x32_bf16 v[52:55], v[164:167], v[188:191], v[52:55]
	v_mfma_f32_16x16x32_bf16 v[236:239], v[168:171], v[188:191], v[236:239]
	v_mfma_f32_16x16x32_bf16 v[116:119], v[172:175], v[188:191], v[116:119]
	ds_read_b128 v[180:183], v213 offset:4096
	s_waitcnt lgkmcnt(4)
	v_mfma_f32_16x16x32_bf16 v[24:27], v[96:99], v[192:195], v[24:27]
	v_mfma_f32_16x16x32_bf16 v[56:59], v[164:167], v[192:195], v[56:59]
	v_mfma_f32_16x16x32_bf16 v[240:243], v[168:171], v[192:195], v[240:243]
	v_mfma_f32_16x16x32_bf16 v[120:123], v[172:175], v[192:195], v[120:123]
	ds_read_b128 v[188:191], v213 offset:6144
	s_waitcnt lgkmcnt(4)
	v_mfma_f32_16x16x32_bf16 v[28:31], v[96:99], v[196:199], v[28:31]
	v_mfma_f32_16x16x32_bf16 v[60:63], v[164:167], v[196:199], v[60:63]
	v_mfma_f32_16x16x32_bf16 v[248:251], v[168:171], v[196:199], v[248:251]
	v_mfma_f32_16x16x32_bf16 v[124:127], v[172:175], v[196:199], v[124:127]
	s_waitcnt vmcnt(16)
	s_barrier
	s_waitcnt vmcnt(8)
	ds_read_b128 v[192:195], v213 offset:8192
	global_load_dwordx4 v[96:99], v142, s[84:85] offset:1024
	s_waitcnt lgkmcnt(4)
	v_mfma_f32_16x16x32_bf16 v[0:3], v[64:67], v[160:163], v[0:3]
	v_mfma_f32_16x16x32_bf16 v[32:35], v[68:71], v[160:163], v[32:35]
	v_mfma_f32_16x16x32_bf16 v[144:147], v[72:75], v[160:163], v[144:147]
	v_mfma_f32_16x16x32_bf16 v[252:255], v[76:79], v[160:163], v[252:255]
	ds_read_b128 v[196:199], v213 offset:10240
	global_load_dwordx4 v[164:167], v150, s[84:85] offset:1024
	s_waitcnt lgkmcnt(4)
	v_mfma_f32_16x16x32_bf16 v[4:7], v[64:67], v[176:179], v[4:7]
	v_mfma_f32_16x16x32_bf16 v[36:39], v[68:71], v[176:179], v[36:39]
	v_mfma_f32_16x16x32_bf16 v[184:187], v[72:75], v[176:179], v[184:187]
	v_mfma_f32_16x16x32_bf16 v[100:103], v[76:79], v[176:179], v[100:103]
	ds_read_b128 v[160:163], v213 offset:12288
	global_load_dwordx4 v[168:171], v142, s[92:93] offset:1024
	s_waitcnt lgkmcnt(4)
	v_mfma_f32_16x16x32_bf16 v[8:11], v[64:67], v[180:183], v[8:11]
	v_mfma_f32_16x16x32_bf16 v[40:43], v[68:71], v[180:183], v[40:43]
	v_mfma_f32_16x16x32_bf16 v[204:207], v[72:75], v[180:183], v[204:207]
	v_mfma_f32_16x16x32_bf16 v[104:107], v[76:79], v[180:183], v[104:107]
	ds_read_b128 v[176:179], v213 offset:14336
	global_load_dwordx4 v[172:175], v150, s[92:93] offset:1024
	s_add_u32 s84, s84, 0x800
	s_addc_u32 s85, s85, 0
	s_add_u32 s92, s92, 0x800
	s_addc_u32 s93, s93, 0
	s_waitcnt lgkmcnt(4)
	v_mfma_f32_16x16x32_bf16 v[12:15], v[64:67], v[188:191], v[12:15]
	v_mfma_f32_16x16x32_bf16 v[44:47], v[68:71], v[188:191], v[44:47]
	v_mfma_f32_16x16x32_bf16 v[208:211], v[72:75], v[188:191], v[208:211]
	v_mfma_f32_16x16x32_bf16 v[108:111], v[76:79], v[188:191], v[108:111]
	ds_read_b128 v[180:183], v212 offset:16384
	s_add_u32 m0, s1, 49152
	s_nop 0
	global_load_lds_dwordx4 v151, s[86:87]
	s_waitcnt lgkmcnt(4)
	v_mfma_f32_16x16x32_bf16 v[16:19], v[64:67], v[192:195], v[16:19]
	v_mfma_f32_16x16x32_bf16 v[48:51], v[68:71], v[192:195], v[48:51]
	v_mfma_f32_16x16x32_bf16 v[232:235], v[72:75], v[192:195], v[232:235]
	v_mfma_f32_16x16x32_bf16 v[112:115], v[76:79], v[192:195], v[112:115]
	ds_read_b128 v[188:191], v212 offset:18432
	s_add_u32 m0, s1, 53248
	s_nop 0
	global_load_lds_dwordx4 v156, s[86:87]
	s_waitcnt lgkmcnt(4)
	v_mfma_f32_16x16x32_bf16 v[20:23], v[64:67], v[196:199], v[20:23]
	v_mfma_f32_16x16x32_bf16 v[52:55], v[68:71], v[196:199], v[52:55]
	v_mfma_f32_16x16x32_bf16 v[236:239], v[72:75], v[196:199], v[236:239]
	v_mfma_f32_16x16x32_bf16 v[116:119], v[76:79], v[196:199], v[116:119]
	ds_read_b128 v[192:195], v212 offset:20480
	s_add_u32 m0, s1, 57344
	s_nop 0
	global_load_lds_dwordx4 v158, s[86:87]
	s_waitcnt lgkmcnt(4)
	v_mfma_f32_16x16x32_bf16 v[24:27], v[64:67], v[160:163], v[24:27]
	v_mfma_f32_16x16x32_bf16 v[56:59], v[68:71], v[160:163], v[56:59]
	v_mfma_f32_16x16x32_bf16 v[240:243], v[72:75], v[160:163], v[240:243]
	v_mfma_f32_16x16x32_bf16 v[120:123], v[76:79], v[160:163], v[120:123]
	ds_read_b128 v[196:199], v212 offset:22528
	s_add_u32 m0, s1, 61440
	s_nop 0
	global_load_lds_dwordx4 v159, s[86:87]
	s_add_u32 s86, s86, 128
	s_addc_u32 s87, s87, 0
	s_waitcnt lgkmcnt(4)
	v_mfma_f32_16x16x32_bf16 v[28:31], v[64:67], v[176:179], v[28:31]
	v_mfma_f32_16x16x32_bf16 v[60:63], v[68:71], v[176:179], v[60:63]
	v_mfma_f32_16x16x32_bf16 v[248:251], v[72:75], v[176:179], v[248:251]
	v_mfma_f32_16x16x32_bf16 v[124:127], v[76:79], v[176:179], v[124:127]
	s_waitcnt vmcnt(8)
	ds_read_b128 v[160:163], v212 offset:24576
	global_load_dwordx4 v[64:67], v142, s[84:85] offset:0
	s_waitcnt lgkmcnt(4)
	v_mfma_f32_16x16x32_bf16 v[0:3], v[80:83], v[180:183], v[0:3]
	v_mfma_f32_16x16x32_bf16 v[32:35], v[84:87], v[180:183], v[32:35]
	v_mfma_f32_16x16x32_bf16 v[144:147], v[88:91], v[180:183], v[144:147]
	v_mfma_f32_16x16x32_bf16 v[252:255], v[92:95], v[180:183], v[252:255]
	ds_read_b128 v[176:179], v212 offset:26624
	global_load_dwordx4 v[68:71], v150, s[84:85] offset:0
	s_waitcnt lgkmcnt(4)
	v_mfma_f32_16x16x32_bf16 v[4:7], v[80:83], v[188:191], v[4:7]
	v_mfma_f32_16x16x32_bf16 v[36:39], v[84:87], v[188:191], v[36:39]
	v_mfma_f32_16x16x32_bf16 v[184:187], v[88:91], v[188:191], v[184:187]
	v_mfma_f32_16x16x32_bf16 v[100:103], v[92:95], v[188:191], v[100:103]
	ds_read_b128 v[180:183], v212 offset:28672
	global_load_dwordx4 v[72:75], v142, s[92:93] offset:0
	s_waitcnt lgkmcnt(4)
	v_mfma_f32_16x16x32_bf16 v[8:11], v[80:83], v[192:195], v[8:11]
	v_mfma_f32_16x16x32_bf16 v[40:43], v[84:87], v[192:195], v[40:43]
	v_mfma_f32_16x16x32_bf16 v[204:207], v[88:91], v[192:195], v[204:207]
	v_mfma_f32_16x16x32_bf16 v[104:107], v[92:95], v[192:195], v[104:107]
	ds_read_b128 v[188:191], v212 offset:30720
	global_load_dwordx4 v[76:79], v150, s[92:93] offset:0
	s_waitcnt lgkmcnt(4)
	v_mfma_f32_16x16x32_bf16 v[12:15], v[80:83], v[196:199], v[12:15]
	v_mfma_f32_16x16x32_bf16 v[44:47], v[84:87], v[196:199], v[44:47]
	v_mfma_f32_16x16x32_bf16 v[208:211], v[88:91], v[196:199], v[208:211]
	v_mfma_f32_16x16x32_bf16 v[108:111], v[92:95], v[196:199], v[108:111]
	ds_read_b128 v[192:195], v213 offset:16384
	s_waitcnt lgkmcnt(4)
	v_mfma_f32_16x16x32_bf16 v[16:19], v[80:83], v[160:163], v[16:19]
	v_mfma_f32_16x16x32_bf16 v[48:51], v[84:87], v[160:163], v[48:51]
	v_mfma_f32_16x16x32_bf16 v[232:235], v[88:91], v[160:163], v[232:235]
	v_mfma_f32_16x16x32_bf16 v[112:115], v[92:95], v[160:163], v[112:115]
	ds_read_b128 v[196:199], v213 offset:18432
	s_waitcnt lgkmcnt(4)
	v_mfma_f32_16x16x32_bf16 v[20:23], v[80:83], v[176:179], v[20:23]
	v_mfma_f32_16x16x32_bf16 v[52:55], v[84:87], v[176:179], v[52:55]
	v_mfma_f32_16x16x32_bf16 v[236:239], v[88:91], v[176:179], v[236:239]
	v_mfma_f32_16x16x32_bf16 v[116:119], v[92:95], v[176:179], v[116:119]
	ds_read_b128 v[160:163], v213 offset:20480
	s_waitcnt lgkmcnt(4)
	v_mfma_f32_16x16x32_bf16 v[24:27], v[80:83], v[180:183], v[24:27]
	v_mfma_f32_16x16x32_bf16 v[56:59], v[84:87], v[180:183], v[56:59]
	v_mfma_f32_16x16x32_bf16 v[240:243], v[88:91], v[180:183], v[240:243]
	v_mfma_f32_16x16x32_bf16 v[120:123], v[92:95], v[180:183], v[120:123]
	ds_read_b128 v[176:179], v213 offset:22528
	s_waitcnt lgkmcnt(4)
	v_mfma_f32_16x16x32_bf16 v[28:31], v[80:83], v[188:191], v[28:31]
	v_mfma_f32_16x16x32_bf16 v[60:63], v[84:87], v[188:191], v[60:63]
	v_mfma_f32_16x16x32_bf16 v[248:251], v[88:91], v[188:191], v[248:251]
	v_mfma_f32_16x16x32_bf16 v[124:127], v[92:95], v[188:191], v[124:127]
	s_waitcnt vmcnt(16)
	s_barrier
	s_waitcnt vmcnt(8)
	ds_read_b128 v[180:183], v213 offset:24576
	global_load_dwordx4 v[80:83], v142, s[84:85] offset:1024
	s_waitcnt lgkmcnt(4)
	v_mfma_f32_16x16x32_bf16 v[0:3], v[96:99], v[192:195], v[0:3]
	v_mfma_f32_16x16x32_bf16 v[32:35], v[164:167], v[192:195], v[32:35]
	v_mfma_f32_16x16x32_bf16 v[144:147], v[168:171], v[192:195], v[144:147]
	v_mfma_f32_16x16x32_bf16 v[252:255], v[172:175], v[192:195], v[252:255]
	ds_read_b128 v[188:191], v213 offset:26624
	global_load_dwordx4 v[84:87], v150, s[84:85] offset:1024
	s_waitcnt lgkmcnt(4)
	v_mfma_f32_16x16x32_bf16 v[4:7], v[96:99], v[196:199], v[4:7]
	v_mfma_f32_16x16x32_bf16 v[36:39], v[164:167], v[196:199], v[36:39]
	v_mfma_f32_16x16x32_bf16 v[184:187], v[168:171], v[196:199], v[184:187]
	v_mfma_f32_16x16x32_bf16 v[100:103], v[172:175], v[196:199], v[100:103]
	ds_read_b128 v[192:195], v213 offset:28672
	global_load_dwordx4 v[88:91], v142, s[92:93] offset:1024
	s_waitcnt lgkmcnt(4)
	v_mfma_f32_16x16x32_bf16 v[8:11], v[96:99], v[160:163], v[8:11]
	v_mfma_f32_16x16x32_bf16 v[40:43], v[164:167], v[160:163], v[40:43]
	v_mfma_f32_16x16x32_bf16 v[204:207], v[168:171], v[160:163], v[204:207]
	v_mfma_f32_16x16x32_bf16 v[104:107], v[172:175], v[160:163], v[104:107]
	ds_read_b128 v[196:199], v213 offset:30720
	global_load_dwordx4 v[92:95], v150, s[92:93] offset:1024
	s_add_u32 s84, s84, 0x800
	s_addc_u32 s85, s85, 0
	s_add_u32 s92, s92, 0x800
	s_addc_u32 s93, s93, 0
	s_waitcnt lgkmcnt(4)
	v_mfma_f32_16x16x32_bf16 v[12:15], v[96:99], v[176:179], v[12:15]
	v_mfma_f32_16x16x32_bf16 v[44:47], v[164:167], v[176:179], v[44:47]
	v_mfma_f32_16x16x32_bf16 v[208:211], v[168:171], v[176:179], v[208:211]
	v_mfma_f32_16x16x32_bf16 v[108:111], v[172:175], v[176:179], v[108:111]
	ds_read_b128 v[160:163], v212 offset:32768
	s_add_u32 m0, s1, 0
	s_nop 0
	global_load_lds_dwordx4 v151, s[86:87]
	s_waitcnt lgkmcnt(4)
	v_mfma_f32_16x16x32_bf16 v[16:19], v[96:99], v[180:183], v[16:19]
	v_mfma_f32_16x16x32_bf16 v[48:51], v[164:167], v[180:183], v[48:51]
	v_mfma_f32_16x16x32_bf16 v[232:235], v[168:171], v[180:183], v[232:235]
	v_mfma_f32_16x16x32_bf16 v[112:115], v[172:175], v[180:183], v[112:115]
	ds_read_b128 v[176:179], v212 offset:34816
	s_add_u32 m0, s1, 4096
	s_nop 0
	global_load_lds_dwordx4 v156, s[86:87]
	s_waitcnt lgkmcnt(4)
	v_mfma_f32_16x16x32_bf16 v[20:23], v[96:99], v[188:191], v[20:23]
	v_mfma_f32_16x16x32_bf16 v[52:55], v[164:167], v[188:191], v[52:55]
	v_mfma_f32_16x16x32_bf16 v[236:239], v[168:171], v[188:191], v[236:239]
	v_mfma_f32_16x16x32_bf16 v[116:119], v[172:175], v[188:191], v[116:119]
	ds_read_b128 v[180:183], v212 offset:36864
	s_add_u32 m0, s1, 8192
	s_nop 0
	global_load_lds_dwordx4 v158, s[86:87]
	s_waitcnt lgkmcnt(4)
	v_mfma_f32_16x16x32_bf16 v[24:27], v[96:99], v[192:195], v[24:27]
	v_mfma_f32_16x16x32_bf16 v[56:59], v[164:167], v[192:195], v[56:59]
	v_mfma_f32_16x16x32_bf16 v[240:243], v[168:171], v[192:195], v[240:243]
	v_mfma_f32_16x16x32_bf16 v[120:123], v[172:175], v[192:195], v[120:123]
	ds_read_b128 v[188:191], v212 offset:38912
	s_add_u32 m0, s1, 12288
	s_nop 0
	global_load_lds_dwordx4 v159, s[86:87]
	s_add_u32 s86, s86, 128
	s_addc_u32 s87, s87, 0
	s_waitcnt lgkmcnt(4)
	v_mfma_f32_16x16x32_bf16 v[28:31], v[96:99], v[196:199], v[28:31]
	v_mfma_f32_16x16x32_bf16 v[60:63], v[164:167], v[196:199], v[60:63]
	v_mfma_f32_16x16x32_bf16 v[248:251], v[168:171], v[196:199], v[248:251]
	v_mfma_f32_16x16x32_bf16 v[124:127], v[172:175], v[196:199], v[124:127]
	s_waitcnt vmcnt(8)
	ds_read_b128 v[192:195], v212 offset:40960
	global_load_dwordx4 v[96:99], v142, s[84:85] offset:0
	s_waitcnt lgkmcnt(4)
	v_mfma_f32_16x16x32_bf16 v[0:3], v[64:67], v[160:163], v[0:3]
	v_mfma_f32_16x16x32_bf16 v[32:35], v[68:71], v[160:163], v[32:35]
	v_mfma_f32_16x16x32_bf16 v[144:147], v[72:75], v[160:163], v[144:147]
	v_mfma_f32_16x16x32_bf16 v[252:255], v[76:79], v[160:163], v[252:255]
	ds_read_b128 v[196:199], v212 offset:43008
	global_load_dwordx4 v[164:167], v150, s[84:85] offset:0
	s_waitcnt lgkmcnt(4)
	v_mfma_f32_16x16x32_bf16 v[4:7], v[64:67], v[176:179], v[4:7]
	v_mfma_f32_16x16x32_bf16 v[36:39], v[68:71], v[176:179], v[36:39]
	v_mfma_f32_16x16x32_bf16 v[184:187], v[72:75], v[176:179], v[184:187]
	v_mfma_f32_16x16x32_bf16 v[100:103], v[76:79], v[176:179], v[100:103]
	ds_read_b128 v[160:163], v212 offset:45056
	global_load_dwordx4 v[168:171], v142, s[92:93] offset:0
	s_waitcnt lgkmcnt(4)
	v_mfma_f32_16x16x32_bf16 v[8:11], v[64:67], v[180:183], v[8:11]
	v_mfma_f32_16x16x32_bf16 v[40:43], v[68:71], v[180:183], v[40:43]
	v_mfma_f32_16x16x32_bf16 v[204:207], v[72:75], v[180:183], v[204:207]
	v_mfma_f32_16x16x32_bf16 v[104:107], v[76:79], v[180:183], v[104:107]
	ds_read_b128 v[176:179], v212 offset:47104
	global_load_dwordx4 v[172:175], v150, s[92:93] offset:0
	s_waitcnt lgkmcnt(4)
	v_mfma_f32_16x16x32_bf16 v[12:15], v[64:67], v[188:191], v[12:15]
	v_mfma_f32_16x16x32_bf16 v[44:47], v[68:71], v[188:191], v[44:47]
	v_mfma_f32_16x16x32_bf16 v[208:211], v[72:75], v[188:191], v[208:211]
	v_mfma_f32_16x16x32_bf16 v[108:111], v[76:79], v[188:191], v[108:111]
	ds_read_b128 v[180:183], v213 offset:32768
	s_waitcnt lgkmcnt(4)
	v_mfma_f32_16x16x32_bf16 v[16:19], v[64:67], v[192:195], v[16:19]
	v_mfma_f32_16x16x32_bf16 v[48:51], v[68:71], v[192:195], v[48:51]
	v_mfma_f32_16x16x32_bf16 v[232:235], v[72:75], v[192:195], v[232:235]
	v_mfma_f32_16x16x32_bf16 v[112:115], v[76:79], v[192:195], v[112:115]
	ds_read_b128 v[188:191], v213 offset:34816
	s_waitcnt lgkmcnt(4)
	v_mfma_f32_16x16x32_bf16 v[20:23], v[64:67], v[196:199], v[20:23]
	v_mfma_f32_16x16x32_bf16 v[52:55], v[68:71], v[196:199], v[52:55]
	v_mfma_f32_16x16x32_bf16 v[236:239], v[72:75], v[196:199], v[236:239]
	v_mfma_f32_16x16x32_bf16 v[116:119], v[76:79], v[196:199], v[116:119]
	ds_read_b128 v[192:195], v213 offset:36864
	s_waitcnt lgkmcnt(4)
	v_mfma_f32_16x16x32_bf16 v[24:27], v[64:67], v[160:163], v[24:27]
	v_mfma_f32_16x16x32_bf16 v[56:59], v[68:71], v[160:163], v[56:59]
	v_mfma_f32_16x16x32_bf16 v[240:243], v[72:75], v[160:163], v[240:243]
	v_mfma_f32_16x16x32_bf16 v[120:123], v[76:79], v[160:163], v[120:123]
	ds_read_b128 v[196:199], v213 offset:38912
	s_waitcnt lgkmcnt(4)
	v_mfma_f32_16x16x32_bf16 v[28:31], v[64:67], v[176:179], v[28:31]
	v_mfma_f32_16x16x32_bf16 v[60:63], v[68:71], v[176:179], v[60:63]
	v_mfma_f32_16x16x32_bf16 v[248:251], v[72:75], v[176:179], v[248:251]
	v_mfma_f32_16x16x32_bf16 v[124:127], v[76:79], v[176:179], v[124:127]
	s_waitcnt vmcnt(16)
	s_barrier
	s_waitcnt vmcnt(8)
	ds_read_b128 v[160:163], v213 offset:40960
	global_load_dwordx4 v[64:67], v142, s[84:85] offset:1024
	s_waitcnt lgkmcnt(4)
	v_mfma_f32_16x16x32_bf16 v[0:3], v[80:83], v[180:183], v[0:3]
	v_mfma_f32_16x16x32_bf16 v[32:35], v[84:87], v[180:183], v[32:35]
	v_mfma_f32_16x16x32_bf16 v[144:147], v[88:91], v[180:183], v[144:147]
	v_mfma_f32_16x16x32_bf16 v[252:255], v[92:95], v[180:183], v[252:255]
	ds_read_b128 v[176:179], v213 offset:43008
	global_load_dwordx4 v[68:71], v150, s[84:85] offset:1024
	s_waitcnt lgkmcnt(4)
	v_mfma_f32_16x16x32_bf16 v[4:7], v[80:83], v[188:191], v[4:7]
	v_mfma_f32_16x16x32_bf16 v[36:39], v[84:87], v[188:191], v[36:39]
	v_mfma_f32_16x16x32_bf16 v[184:187], v[88:91], v[188:191], v[184:187]
	v_mfma_f32_16x16x32_bf16 v[100:103], v[92:95], v[188:191], v[100:103]
	ds_read_b128 v[180:183], v213 offset:45056
	global_load_dwordx4 v[72:75], v142, s[92:93] offset:1024
	s_waitcnt lgkmcnt(4)
	v_mfma_f32_16x16x32_bf16 v[8:11], v[80:83], v[192:195], v[8:11]
	v_mfma_f32_16x16x32_bf16 v[40:43], v[84:87], v[192:195], v[40:43]
	v_mfma_f32_16x16x32_bf16 v[204:207], v[88:91], v[192:195], v[204:207]
	v_mfma_f32_16x16x32_bf16 v[104:107], v[92:95], v[192:195], v[104:107]
	ds_read_b128 v[188:191], v213 offset:47104
	global_load_dwordx4 v[76:79], v150, s[92:93] offset:1024
	s_add_u32 s84, s84, 0x800
	s_addc_u32 s85, s85, 0
	s_add_u32 s92, s92, 0x800
	s_addc_u32 s93, s93, 0
	s_waitcnt lgkmcnt(4)
	v_mfma_f32_16x16x32_bf16 v[12:15], v[80:83], v[196:199], v[12:15]
	v_mfma_f32_16x16x32_bf16 v[44:47], v[84:87], v[196:199], v[44:47]
	v_mfma_f32_16x16x32_bf16 v[208:211], v[88:91], v[196:199], v[208:211]
	v_mfma_f32_16x16x32_bf16 v[108:111], v[92:95], v[196:199], v[108:111]
	ds_read_b128 v[192:195], v212 offset:49152
	s_add_u32 m0, s1, 16384
	s_nop 0
	global_load_lds_dwordx4 v151, s[86:87]
	s_waitcnt lgkmcnt(4)
	v_mfma_f32_16x16x32_bf16 v[16:19], v[80:83], v[160:163], v[16:19]
	v_mfma_f32_16x16x32_bf16 v[48:51], v[84:87], v[160:163], v[48:51]
	v_mfma_f32_16x16x32_bf16 v[232:235], v[88:91], v[160:163], v[232:235]
	v_mfma_f32_16x16x32_bf16 v[112:115], v[92:95], v[160:163], v[112:115]
	ds_read_b128 v[196:199], v212 offset:51200
	s_add_u32 m0, s1, 20480
	s_nop 0
	global_load_lds_dwordx4 v156, s[86:87]
	s_waitcnt lgkmcnt(4)
	v_mfma_f32_16x16x32_bf16 v[20:23], v[80:83], v[176:179], v[20:23]
	v_mfma_f32_16x16x32_bf16 v[52:55], v[84:87], v[176:179], v[52:55]
	v_mfma_f32_16x16x32_bf16 v[236:239], v[88:91], v[176:179], v[236:239]
	v_mfma_f32_16x16x32_bf16 v[116:119], v[92:95], v[176:179], v[116:119]
	ds_read_b128 v[160:163], v212 offset:53248
	s_add_u32 m0, s1, 24576
	s_nop 0
	global_load_lds_dwordx4 v158, s[86:87]
	s_waitcnt lgkmcnt(4)
	v_mfma_f32_16x16x32_bf16 v[24:27], v[80:83], v[180:183], v[24:27]
	v_mfma_f32_16x16x32_bf16 v[56:59], v[84:87], v[180:183], v[56:59]
	v_mfma_f32_16x16x32_bf16 v[240:243], v[88:91], v[180:183], v[240:243]
	v_mfma_f32_16x16x32_bf16 v[120:123], v[92:95], v[180:183], v[120:123]
	ds_read_b128 v[176:179], v212 offset:55296
	s_add_u32 m0, s1, 28672
	s_nop 0
	global_load_lds_dwordx4 v159, s[86:87]
	s_add_u32 s86, s86, 128
	s_addc_u32 s87, s87, 0
	s_waitcnt lgkmcnt(4)
	v_mfma_f32_16x16x32_bf16 v[28:31], v[80:83], v[188:191], v[28:31]
	v_mfma_f32_16x16x32_bf16 v[60:63], v[84:87], v[188:191], v[60:63]
	v_mfma_f32_16x16x32_bf16 v[248:251], v[88:91], v[188:191], v[248:251]
	v_mfma_f32_16x16x32_bf16 v[124:127], v[92:95], v[188:191], v[124:127]
	s_waitcnt vmcnt(8)
	ds_read_b128 v[180:183], v212 offset:57344
	global_load_dwordx4 v[80:83], v142, s[84:85] offset:0
	s_waitcnt lgkmcnt(4)
	v_mfma_f32_16x16x32_bf16 v[0:3], v[96:99], v[192:195], v[0:3]
	v_mfma_f32_16x16x32_bf16 v[32:35], v[164:167], v[192:195], v[32:35]
	v_mfma_f32_16x16x32_bf16 v[144:147], v[168:171], v[192:195], v[144:147]
	v_mfma_f32_16x16x32_bf16 v[252:255], v[172:175], v[192:195], v[252:255]
	ds_read_b128 v[188:191], v212 offset:59392
	global_load_dwordx4 v[84:87], v150, s[84:85] offset:0
	s_waitcnt lgkmcnt(4)
	v_mfma_f32_16x16x32_bf16 v[4:7], v[96:99], v[196:199], v[4:7]
	v_mfma_f32_16x16x32_bf16 v[36:39], v[164:167], v[196:199], v[36:39]
	v_mfma_f32_16x16x32_bf16 v[184:187], v[168:171], v[196:199], v[184:187]
	v_mfma_f32_16x16x32_bf16 v[100:103], v[172:175], v[196:199], v[100:103]
	ds_read_b128 v[192:195], v212 offset:61440
	global_load_dwordx4 v[88:91], v142, s[92:93] offset:0
	s_waitcnt lgkmcnt(4)
	v_mfma_f32_16x16x32_bf16 v[8:11], v[96:99], v[160:163], v[8:11]
	v_mfma_f32_16x16x32_bf16 v[40:43], v[164:167], v[160:163], v[40:43]
	v_mfma_f32_16x16x32_bf16 v[204:207], v[168:171], v[160:163], v[204:207]
	v_mfma_f32_16x16x32_bf16 v[104:107], v[172:175], v[160:163], v[104:107]
	ds_read_b128 v[196:199], v212 offset:63488
	global_load_dwordx4 v[92:95], v150, s[92:93] offset:0
	s_waitcnt lgkmcnt(4)
	v_mfma_f32_16x16x32_bf16 v[12:15], v[96:99], v[176:179], v[12:15]
	v_mfma_f32_16x16x32_bf16 v[44:47], v[164:167], v[176:179], v[44:47]
	v_mfma_f32_16x16x32_bf16 v[208:211], v[168:171], v[176:179], v[208:211]
	v_mfma_f32_16x16x32_bf16 v[108:111], v[172:175], v[176:179], v[108:111]
	ds_read_b128 v[160:163], v213 offset:49152
	s_waitcnt lgkmcnt(4)
	v_mfma_f32_16x16x32_bf16 v[16:19], v[96:99], v[180:183], v[16:19]
	v_mfma_f32_16x16x32_bf16 v[48:51], v[164:167], v[180:183], v[48:51]
	v_mfma_f32_16x16x32_bf16 v[232:235], v[168:171], v[180:183], v[232:235]
	v_mfma_f32_16x16x32_bf16 v[112:115], v[172:175], v[180:183], v[112:115]
	ds_read_b128 v[176:179], v213 offset:51200
	s_waitcnt lgkmcnt(4)
	v_mfma_f32_16x16x32_bf16 v[20:23], v[96:99], v[188:191], v[20:23]
	v_mfma_f32_16x16x32_bf16 v[52:55], v[164:167], v[188:191], v[52:55]
	v_mfma_f32_16x16x32_bf16 v[236:239], v[168:171], v[188:191], v[236:239]
	v_mfma_f32_16x16x32_bf16 v[116:119], v[172:175], v[188:191], v[116:119]
	ds_read_b128 v[180:183], v213 offset:53248
	s_waitcnt lgkmcnt(4)
	v_mfma_f32_16x16x32_bf16 v[24:27], v[96:99], v[192:195], v[24:27]
	v_mfma_f32_16x16x32_bf16 v[56:59], v[164:167], v[192:195], v[56:59]
	v_mfma_f32_16x16x32_bf16 v[240:243], v[168:171], v[192:195], v[240:243]
	v_mfma_f32_16x16x32_bf16 v[120:123], v[172:175], v[192:195], v[120:123]
	ds_read_b128 v[188:191], v213 offset:55296
	s_waitcnt lgkmcnt(4)
	v_mfma_f32_16x16x32_bf16 v[28:31], v[96:99], v[196:199], v[28:31]
	v_mfma_f32_16x16x32_bf16 v[60:63], v[164:167], v[196:199], v[60:63]
	v_mfma_f32_16x16x32_bf16 v[248:251], v[168:171], v[196:199], v[248:251]
	v_mfma_f32_16x16x32_bf16 v[124:127], v[172:175], v[196:199], v[124:127]
	s_waitcnt vmcnt(16)
	s_barrier
	s_waitcnt vmcnt(8)
	ds_read_b128 v[192:195], v213 offset:57344
	global_load_dwordx4 v[96:99], v142, s[84:85] offset:1024
	s_waitcnt lgkmcnt(4)
	v_mfma_f32_16x16x32_bf16 v[0:3], v[64:67], v[160:163], v[0:3]
	v_mfma_f32_16x16x32_bf16 v[32:35], v[68:71], v[160:163], v[32:35]
	v_mfma_f32_16x16x32_bf16 v[144:147], v[72:75], v[160:163], v[144:147]
	v_mfma_f32_16x16x32_bf16 v[252:255], v[76:79], v[160:163], v[252:255]
	ds_read_b128 v[196:199], v213 offset:59392
	global_load_dwordx4 v[164:167], v150, s[84:85] offset:1024
	s_waitcnt lgkmcnt(4)
	v_mfma_f32_16x16x32_bf16 v[4:7], v[64:67], v[176:179], v[4:7]
	v_mfma_f32_16x16x32_bf16 v[36:39], v[68:71], v[176:179], v[36:39]
	v_mfma_f32_16x16x32_bf16 v[184:187], v[72:75], v[176:179], v[184:187]
	v_mfma_f32_16x16x32_bf16 v[100:103], v[76:79], v[176:179], v[100:103]
	ds_read_b128 v[160:163], v213 offset:61440
	global_load_dwordx4 v[168:171], v142, s[92:93] offset:1024
	s_waitcnt lgkmcnt(4)
	v_mfma_f32_16x16x32_bf16 v[8:11], v[64:67], v[180:183], v[8:11]
	v_mfma_f32_16x16x32_bf16 v[40:43], v[68:71], v[180:183], v[40:43]
	v_mfma_f32_16x16x32_bf16 v[204:207], v[72:75], v[180:183], v[204:207]
	v_mfma_f32_16x16x32_bf16 v[104:107], v[76:79], v[180:183], v[104:107]
	ds_read_b128 v[176:179], v213 offset:63488
	global_load_dwordx4 v[172:175], v150, s[92:93] offset:1024
	s_add_u32 s84, s84, 0x800
	s_addc_u32 s85, s85, 0
	s_add_u32 s92, s92, 0x800
	s_addc_u32 s93, s93, 0
	s_waitcnt lgkmcnt(4)
	v_mfma_f32_16x16x32_bf16 v[12:15], v[64:67], v[188:191], v[12:15]
	v_mfma_f32_16x16x32_bf16 v[44:47], v[68:71], v[188:191], v[44:47]
	v_mfma_f32_16x16x32_bf16 v[208:211], v[72:75], v[188:191], v[208:211]
	v_mfma_f32_16x16x32_bf16 v[108:111], v[76:79], v[188:191], v[108:111]
	ds_read_b128 v[180:183], v212 offset:0
	s_add_u32 m0, s1, 32768
	s_nop 0
	global_load_lds_dwordx4 v151, s[86:87]
	s_waitcnt lgkmcnt(4)
	v_mfma_f32_16x16x32_bf16 v[16:19], v[64:67], v[192:195], v[16:19]
	v_mfma_f32_16x16x32_bf16 v[48:51], v[68:71], v[192:195], v[48:51]
	v_mfma_f32_16x16x32_bf16 v[232:235], v[72:75], v[192:195], v[232:235]
	v_mfma_f32_16x16x32_bf16 v[112:115], v[76:79], v[192:195], v[112:115]
	ds_read_b128 v[188:191], v212 offset:2048
	s_add_u32 m0, s1, 36864
	s_nop 0
	global_load_lds_dwordx4 v156, s[86:87]
	s_waitcnt lgkmcnt(4)
	v_mfma_f32_16x16x32_bf16 v[20:23], v[64:67], v[196:199], v[20:23]
	v_mfma_f32_16x16x32_bf16 v[52:55], v[68:71], v[196:199], v[52:55]
	v_mfma_f32_16x16x32_bf16 v[236:239], v[72:75], v[196:199], v[236:239]
	v_mfma_f32_16x16x32_bf16 v[116:119], v[76:79], v[196:199], v[116:119]
	ds_read_b128 v[192:195], v212 offset:4096
	s_add_u32 m0, s1, 40960
	s_nop 0
	global_load_lds_dwordx4 v158, s[86:87]
	s_waitcnt lgkmcnt(4)
	v_mfma_f32_16x16x32_bf16 v[24:27], v[64:67], v[160:163], v[24:27]
	v_mfma_f32_16x16x32_bf16 v[56:59], v[68:71], v[160:163], v[56:59]
	v_mfma_f32_16x16x32_bf16 v[240:243], v[72:75], v[160:163], v[240:243]
	v_mfma_f32_16x16x32_bf16 v[120:123], v[76:79], v[160:163], v[120:123]
	ds_read_b128 v[196:199], v212 offset:6144
	s_add_u32 m0, s1, 45056
	s_nop 0
	global_load_lds_dwordx4 v159, s[86:87]
	s_add_u32 s86, s86, 128
	s_addc_u32 s87, s87, 0
	s_waitcnt lgkmcnt(4)
	v_mfma_f32_16x16x32_bf16 v[28:31], v[64:67], v[176:179], v[28:31]
	v_mfma_f32_16x16x32_bf16 v[60:63], v[68:71], v[176:179], v[60:63]
	v_mfma_f32_16x16x32_bf16 v[248:251], v[72:75], v[176:179], v[248:251]
	v_mfma_f32_16x16x32_bf16 v[124:127], v[76:79], v[176:179], v[124:127]
	s_waitcnt vmcnt(8)
	ds_read_b128 v[160:163], v212 offset:8192
	global_load_dwordx4 v[64:67], v142, s[84:85] offset:0
	s_waitcnt lgkmcnt(4)
	v_mfma_f32_16x16x32_bf16 v[0:3], v[80:83], v[180:183], v[0:3]
	v_mfma_f32_16x16x32_bf16 v[32:35], v[84:87], v[180:183], v[32:35]
	v_mfma_f32_16x16x32_bf16 v[144:147], v[88:91], v[180:183], v[144:147]
	v_mfma_f32_16x16x32_bf16 v[252:255], v[92:95], v[180:183], v[252:255]
	ds_read_b128 v[176:179], v212 offset:10240
	global_load_dwordx4 v[68:71], v150, s[84:85] offset:0
	s_waitcnt lgkmcnt(4)
	v_mfma_f32_16x16x32_bf16 v[4:7], v[80:83], v[188:191], v[4:7]
	v_mfma_f32_16x16x32_bf16 v[36:39], v[84:87], v[188:191], v[36:39]
	v_mfma_f32_16x16x32_bf16 v[184:187], v[88:91], v[188:191], v[184:187]
	v_mfma_f32_16x16x32_bf16 v[100:103], v[92:95], v[188:191], v[100:103]
	ds_read_b128 v[180:183], v212 offset:12288
	global_load_dwordx4 v[72:75], v142, s[92:93] offset:0
	s_waitcnt lgkmcnt(4)
	v_mfma_f32_16x16x32_bf16 v[8:11], v[80:83], v[192:195], v[8:11]
	v_mfma_f32_16x16x32_bf16 v[40:43], v[84:87], v[192:195], v[40:43]
	v_mfma_f32_16x16x32_bf16 v[204:207], v[88:91], v[192:195], v[204:207]
	v_mfma_f32_16x16x32_bf16 v[104:107], v[92:95], v[192:195], v[104:107]
	ds_read_b128 v[188:191], v212 offset:14336
	global_load_dwordx4 v[76:79], v150, s[92:93] offset:0
	s_waitcnt lgkmcnt(4)
	v_mfma_f32_16x16x32_bf16 v[12:15], v[80:83], v[196:199], v[12:15]
	v_mfma_f32_16x16x32_bf16 v[44:47], v[84:87], v[196:199], v[44:47]
	v_mfma_f32_16x16x32_bf16 v[208:211], v[88:91], v[196:199], v[208:211]
	v_mfma_f32_16x16x32_bf16 v[108:111], v[92:95], v[196:199], v[108:111]
	ds_read_b128 v[192:195], v213 offset:0
	s_waitcnt lgkmcnt(4)
	v_mfma_f32_16x16x32_bf16 v[16:19], v[80:83], v[160:163], v[16:19]
	v_mfma_f32_16x16x32_bf16 v[48:51], v[84:87], v[160:163], v[48:51]
	v_mfma_f32_16x16x32_bf16 v[232:235], v[88:91], v[160:163], v[232:235]
	v_mfma_f32_16x16x32_bf16 v[112:115], v[92:95], v[160:163], v[112:115]
	ds_read_b128 v[196:199], v213 offset:2048
	s_waitcnt lgkmcnt(4)
	v_mfma_f32_16x16x32_bf16 v[20:23], v[80:83], v[176:179], v[20:23]
	v_mfma_f32_16x16x32_bf16 v[52:55], v[84:87], v[176:179], v[52:55]
	v_mfma_f32_16x16x32_bf16 v[236:239], v[88:91], v[176:179], v[236:239]
	v_mfma_f32_16x16x32_bf16 v[116:119], v[92:95], v[176:179], v[116:119]
	ds_read_b128 v[160:163], v213 offset:4096
	s_waitcnt lgkmcnt(4)
	v_mfma_f32_16x16x32_bf16 v[24:27], v[80:83], v[180:183], v[24:27]
	v_mfma_f32_16x16x32_bf16 v[56:59], v[84:87], v[180:183], v[56:59]
	v_mfma_f32_16x16x32_bf16 v[240:243], v[88:91], v[180:183], v[240:243]
	v_mfma_f32_16x16x32_bf16 v[120:123], v[92:95], v[180:183], v[120:123]
	ds_read_b128 v[176:179], v213 offset:6144
	s_waitcnt lgkmcnt(4)
	v_mfma_f32_16x16x32_bf16 v[28:31], v[80:83], v[188:191], v[28:31]
	v_mfma_f32_16x16x32_bf16 v[60:63], v[84:87], v[188:191], v[60:63]
	v_mfma_f32_16x16x32_bf16 v[248:251], v[88:91], v[188:191], v[248:251]
	v_mfma_f32_16x16x32_bf16 v[124:127], v[92:95], v[188:191], v[124:127]
	s_waitcnt vmcnt(16)
	s_barrier
	s_waitcnt vmcnt(8)
	ds_read_b128 v[180:183], v213 offset:8192
	global_load_dwordx4 v[80:83], v142, s[84:85] offset:1024
	s_waitcnt lgkmcnt(4)
	v_mfma_f32_16x16x32_bf16 v[0:3], v[96:99], v[192:195], v[0:3]
	v_mfma_f32_16x16x32_bf16 v[32:35], v[164:167], v[192:195], v[32:35]
	v_mfma_f32_16x16x32_bf16 v[144:147], v[168:171], v[192:195], v[144:147]
	v_mfma_f32_16x16x32_bf16 v[252:255], v[172:175], v[192:195], v[252:255]
	ds_read_b128 v[188:191], v213 offset:10240
	global_load_dwordx4 v[84:87], v150, s[84:85] offset:1024
	s_waitcnt lgkmcnt(4)
	v_mfma_f32_16x16x32_bf16 v[4:7], v[96:99], v[196:199], v[4:7]
	v_mfma_f32_16x16x32_bf16 v[36:39], v[164:167], v[196:199], v[36:39]
	v_mfma_f32_16x16x32_bf16 v[184:187], v[168:171], v[196:199], v[184:187]
	v_mfma_f32_16x16x32_bf16 v[100:103], v[172:175], v[196:199], v[100:103]
	ds_read_b128 v[192:195], v213 offset:12288
	global_load_dwordx4 v[88:91], v142, s[92:93] offset:1024
	s_waitcnt lgkmcnt(4)
	v_mfma_f32_16x16x32_bf16 v[8:11], v[96:99], v[160:163], v[8:11]
	v_mfma_f32_16x16x32_bf16 v[40:43], v[164:167], v[160:163], v[40:43]
	v_mfma_f32_16x16x32_bf16 v[204:207], v[168:171], v[160:163], v[204:207]
	v_mfma_f32_16x16x32_bf16 v[104:107], v[172:175], v[160:163], v[104:107]
	ds_read_b128 v[196:199], v213 offset:14336
	global_load_dwordx4 v[92:95], v150, s[92:93] offset:1024
	s_add_u32 s84, s84, 0x800
	s_addc_u32 s85, s85, 0
	s_add_u32 s92, s92, 0x800
	s_addc_u32 s93, s93, 0
	s_waitcnt lgkmcnt(4)
	v_mfma_f32_16x16x32_bf16 v[12:15], v[96:99], v[176:179], v[12:15]
	v_mfma_f32_16x16x32_bf16 v[44:47], v[164:167], v[176:179], v[44:47]
	v_mfma_f32_16x16x32_bf16 v[208:211], v[168:171], v[176:179], v[208:211]
	v_mfma_f32_16x16x32_bf16 v[108:111], v[172:175], v[176:179], v[108:111]
	ds_read_b128 v[160:163], v212 offset:16384
	s_add_u32 m0, s1, 49152
	s_nop 0
	global_load_lds_dwordx4 v151, s[86:87]
	s_waitcnt lgkmcnt(4)
	v_mfma_f32_16x16x32_bf16 v[16:19], v[96:99], v[180:183], v[16:19]
	v_mfma_f32_16x16x32_bf16 v[48:51], v[164:167], v[180:183], v[48:51]
	v_mfma_f32_16x16x32_bf16 v[232:235], v[168:171], v[180:183], v[232:235]
	v_mfma_f32_16x16x32_bf16 v[112:115], v[172:175], v[180:183], v[112:115]
	ds_read_b128 v[176:179], v212 offset:18432
	s_add_u32 m0, s1, 53248
	s_nop 0
	global_load_lds_dwordx4 v156, s[86:87]
	s_waitcnt lgkmcnt(4)
	v_mfma_f32_16x16x32_bf16 v[20:23], v[96:99], v[188:191], v[20:23]
	v_mfma_f32_16x16x32_bf16 v[52:55], v[164:167], v[188:191], v[52:55]
	v_mfma_f32_16x16x32_bf16 v[236:239], v[168:171], v[188:191], v[236:239]
	v_mfma_f32_16x16x32_bf16 v[116:119], v[172:175], v[188:191], v[116:119]
	ds_read_b128 v[180:183], v212 offset:20480
	s_add_u32 m0, s1, 57344
	s_nop 0
	global_load_lds_dwordx4 v158, s[86:87]
	s_waitcnt lgkmcnt(4)
	v_mfma_f32_16x16x32_bf16 v[24:27], v[96:99], v[192:195], v[24:27]
	v_mfma_f32_16x16x32_bf16 v[56:59], v[164:167], v[192:195], v[56:59]
	v_mfma_f32_16x16x32_bf16 v[240:243], v[168:171], v[192:195], v[240:243]
	v_mfma_f32_16x16x32_bf16 v[120:123], v[172:175], v[192:195], v[120:123]
	ds_read_b128 v[188:191], v212 offset:22528
	s_add_u32 m0, s1, 61440
	s_nop 0
	global_load_lds_dwordx4 v159, s[86:87]
	s_add_u32 s86, s86, 128
	s_addc_u32 s87, s87, 0
	s_waitcnt lgkmcnt(4)
	v_mfma_f32_16x16x32_bf16 v[28:31], v[96:99], v[196:199], v[28:31]
	v_mfma_f32_16x16x32_bf16 v[60:63], v[164:167], v[196:199], v[60:63]
	v_mfma_f32_16x16x32_bf16 v[248:251], v[168:171], v[196:199], v[248:251]
	v_mfma_f32_16x16x32_bf16 v[124:127], v[172:175], v[196:199], v[124:127]
	s_waitcnt vmcnt(8)
	ds_read_b128 v[192:195], v212 offset:24576
	global_load_dwordx4 v[96:99], v142, s[84:85] offset:0
	s_waitcnt lgkmcnt(4)
	v_mfma_f32_16x16x32_bf16 v[0:3], v[64:67], v[160:163], v[0:3]
	v_mfma_f32_16x16x32_bf16 v[32:35], v[68:71], v[160:163], v[32:35]
	v_mfma_f32_16x16x32_bf16 v[144:147], v[72:75], v[160:163], v[144:147]
	v_mfma_f32_16x16x32_bf16 v[252:255], v[76:79], v[160:163], v[252:255]
	ds_read_b128 v[196:199], v212 offset:26624
	global_load_dwordx4 v[164:167], v150, s[84:85] offset:0
	s_waitcnt lgkmcnt(4)
	v_mfma_f32_16x16x32_bf16 v[4:7], v[64:67], v[176:179], v[4:7]
	v_mfma_f32_16x16x32_bf16 v[36:39], v[68:71], v[176:179], v[36:39]
	v_mfma_f32_16x16x32_bf16 v[184:187], v[72:75], v[176:179], v[184:187]
	v_mfma_f32_16x16x32_bf16 v[100:103], v[76:79], v[176:179], v[100:103]
	ds_read_b128 v[160:163], v212 offset:28672
	global_load_dwordx4 v[168:171], v142, s[92:93] offset:0
	s_waitcnt lgkmcnt(4)
	v_mfma_f32_16x16x32_bf16 v[8:11], v[64:67], v[180:183], v[8:11]
	v_mfma_f32_16x16x32_bf16 v[40:43], v[68:71], v[180:183], v[40:43]
	v_mfma_f32_16x16x32_bf16 v[204:207], v[72:75], v[180:183], v[204:207]
	v_mfma_f32_16x16x32_bf16 v[104:107], v[76:79], v[180:183], v[104:107]
	ds_read_b128 v[176:179], v212 offset:30720
	global_load_dwordx4 v[172:175], v150, s[92:93] offset:0
	s_waitcnt lgkmcnt(4)
	v_mfma_f32_16x16x32_bf16 v[12:15], v[64:67], v[188:191], v[12:15]
	v_mfma_f32_16x16x32_bf16 v[44:47], v[68:71], v[188:191], v[44:47]
	v_mfma_f32_16x16x32_bf16 v[208:211], v[72:75], v[188:191], v[208:211]
	v_mfma_f32_16x16x32_bf16 v[108:111], v[76:79], v[188:191], v[108:111]
	ds_read_b128 v[180:183], v213 offset:16384
	s_waitcnt lgkmcnt(4)
	v_mfma_f32_16x16x32_bf16 v[16:19], v[64:67], v[192:195], v[16:19]
	v_mfma_f32_16x16x32_bf16 v[48:51], v[68:71], v[192:195], v[48:51]
	v_mfma_f32_16x16x32_bf16 v[232:235], v[72:75], v[192:195], v[232:235]
	v_mfma_f32_16x16x32_bf16 v[112:115], v[76:79], v[192:195], v[112:115]
	ds_read_b128 v[188:191], v213 offset:18432
	s_waitcnt lgkmcnt(4)
	v_mfma_f32_16x16x32_bf16 v[20:23], v[64:67], v[196:199], v[20:23]
	v_mfma_f32_16x16x32_bf16 v[52:55], v[68:71], v[196:199], v[52:55]
	v_mfma_f32_16x16x32_bf16 v[236:239], v[72:75], v[196:199], v[236:239]
	v_mfma_f32_16x16x32_bf16 v[116:119], v[76:79], v[196:199], v[116:119]
	ds_read_b128 v[192:195], v213 offset:20480
	s_waitcnt lgkmcnt(4)
	v_mfma_f32_16x16x32_bf16 v[24:27], v[64:67], v[160:163], v[24:27]
	v_mfma_f32_16x16x32_bf16 v[56:59], v[68:71], v[160:163], v[56:59]
	v_mfma_f32_16x16x32_bf16 v[240:243], v[72:75], v[160:163], v[240:243]
	v_mfma_f32_16x16x32_bf16 v[120:123], v[76:79], v[160:163], v[120:123]
	ds_read_b128 v[196:199], v213 offset:22528
	s_waitcnt lgkmcnt(4)
	v_mfma_f32_16x16x32_bf16 v[28:31], v[64:67], v[176:179], v[28:31]
	v_mfma_f32_16x16x32_bf16 v[60:63], v[68:71], v[176:179], v[60:63]
	v_mfma_f32_16x16x32_bf16 v[248:251], v[72:75], v[176:179], v[248:251]
	v_mfma_f32_16x16x32_bf16 v[124:127], v[76:79], v[176:179], v[124:127]
	s_waitcnt vmcnt(16)
	s_barrier
	s_waitcnt vmcnt(8)
	ds_read_b128 v[160:163], v213 offset:24576
	global_load_dwordx4 v[64:67], v142, s[84:85] offset:1024
	s_waitcnt lgkmcnt(4)
	v_mfma_f32_16x16x32_bf16 v[0:3], v[80:83], v[180:183], v[0:3]
	v_mfma_f32_16x16x32_bf16 v[32:35], v[84:87], v[180:183], v[32:35]
	v_mfma_f32_16x16x32_bf16 v[144:147], v[88:91], v[180:183], v[144:147]
	v_mfma_f32_16x16x32_bf16 v[252:255], v[92:95], v[180:183], v[252:255]
	ds_read_b128 v[176:179], v213 offset:26624
	global_load_dwordx4 v[68:71], v150, s[84:85] offset:1024
	s_waitcnt lgkmcnt(4)
	v_mfma_f32_16x16x32_bf16 v[4:7], v[80:83], v[188:191], v[4:7]
	v_mfma_f32_16x16x32_bf16 v[36:39], v[84:87], v[188:191], v[36:39]
	v_mfma_f32_16x16x32_bf16 v[184:187], v[88:91], v[188:191], v[184:187]
	v_mfma_f32_16x16x32_bf16 v[100:103], v[92:95], v[188:191], v[100:103]
	ds_read_b128 v[180:183], v213 offset:28672
	global_load_dwordx4 v[72:75], v142, s[92:93] offset:1024
	s_waitcnt lgkmcnt(4)
	v_mfma_f32_16x16x32_bf16 v[8:11], v[80:83], v[192:195], v[8:11]
	v_mfma_f32_16x16x32_bf16 v[40:43], v[84:87], v[192:195], v[40:43]
	v_mfma_f32_16x16x32_bf16 v[204:207], v[88:91], v[192:195], v[204:207]
	v_mfma_f32_16x16x32_bf16 v[104:107], v[92:95], v[192:195], v[104:107]
	ds_read_b128 v[188:191], v213 offset:30720
	global_load_dwordx4 v[76:79], v150, s[92:93] offset:1024
	s_add_u32 s84, s84, 0x800
	s_addc_u32 s85, s85, 0
	s_add_u32 s92, s92, 0x800
	s_addc_u32 s93, s93, 0
	s_waitcnt lgkmcnt(4)
	v_mfma_f32_16x16x32_bf16 v[12:15], v[80:83], v[196:199], v[12:15]
	v_mfma_f32_16x16x32_bf16 v[44:47], v[84:87], v[196:199], v[44:47]
	v_mfma_f32_16x16x32_bf16 v[208:211], v[88:91], v[196:199], v[208:211]
	v_mfma_f32_16x16x32_bf16 v[108:111], v[92:95], v[196:199], v[108:111]
	ds_read_b128 v[192:195], v212 offset:32768
	s_add_u32 m0, s1, 0
	s_nop 0
	global_load_lds_dwordx4 v151, s[86:87]
	s_waitcnt lgkmcnt(4)
	v_mfma_f32_16x16x32_bf16 v[16:19], v[80:83], v[160:163], v[16:19]
	v_mfma_f32_16x16x32_bf16 v[48:51], v[84:87], v[160:163], v[48:51]
	v_mfma_f32_16x16x32_bf16 v[232:235], v[88:91], v[160:163], v[232:235]
	v_mfma_f32_16x16x32_bf16 v[112:115], v[92:95], v[160:163], v[112:115]
	ds_read_b128 v[196:199], v212 offset:34816
	s_add_u32 m0, s1, 4096
	s_nop 0
	global_load_lds_dwordx4 v156, s[86:87]
	s_waitcnt lgkmcnt(4)
	v_mfma_f32_16x16x32_bf16 v[20:23], v[80:83], v[176:179], v[20:23]
	v_mfma_f32_16x16x32_bf16 v[52:55], v[84:87], v[176:179], v[52:55]
	v_mfma_f32_16x16x32_bf16 v[236:239], v[88:91], v[176:179], v[236:239]
	v_mfma_f32_16x16x32_bf16 v[116:119], v[92:95], v[176:179], v[116:119]
	ds_read_b128 v[160:163], v212 offset:36864
	s_add_u32 m0, s1, 8192
	s_nop 0
	global_load_lds_dwordx4 v158, s[86:87]
	s_waitcnt lgkmcnt(4)
	v_mfma_f32_16x16x32_bf16 v[24:27], v[80:83], v[180:183], v[24:27]
	v_mfma_f32_16x16x32_bf16 v[56:59], v[84:87], v[180:183], v[56:59]
	v_mfma_f32_16x16x32_bf16 v[240:243], v[88:91], v[180:183], v[240:243]
	v_mfma_f32_16x16x32_bf16 v[120:123], v[92:95], v[180:183], v[120:123]
	ds_read_b128 v[176:179], v212 offset:38912
	s_add_u32 m0, s1, 12288
	s_nop 0
	global_load_lds_dwordx4 v159, s[86:87]
	s_add_u32 s86, s86, 128
	s_addc_u32 s87, s87, 0
	s_waitcnt lgkmcnt(4)
	v_mfma_f32_16x16x32_bf16 v[28:31], v[80:83], v[188:191], v[28:31]
	v_mfma_f32_16x16x32_bf16 v[60:63], v[84:87], v[188:191], v[60:63]
	v_mfma_f32_16x16x32_bf16 v[248:251], v[88:91], v[188:191], v[248:251]
	v_mfma_f32_16x16x32_bf16 v[124:127], v[92:95], v[188:191], v[124:127]
	s_waitcnt vmcnt(8)
	ds_read_b128 v[180:183], v212 offset:40960
	global_load_dwordx4 v[80:83], v142, s[84:85] offset:0
	s_waitcnt lgkmcnt(4)
	v_mfma_f32_16x16x32_bf16 v[0:3], v[96:99], v[192:195], v[0:3]
	v_mfma_f32_16x16x32_bf16 v[32:35], v[164:167], v[192:195], v[32:35]
	v_mfma_f32_16x16x32_bf16 v[144:147], v[168:171], v[192:195], v[144:147]
	v_mfma_f32_16x16x32_bf16 v[252:255], v[172:175], v[192:195], v[252:255]
	ds_read_b128 v[188:191], v212 offset:43008
	global_load_dwordx4 v[84:87], v150, s[84:85] offset:0
	s_waitcnt lgkmcnt(4)
	v_mfma_f32_16x16x32_bf16 v[4:7], v[96:99], v[196:199], v[4:7]
	v_mfma_f32_16x16x32_bf16 v[36:39], v[164:167], v[196:199], v[36:39]
	v_mfma_f32_16x16x32_bf16 v[184:187], v[168:171], v[196:199], v[184:187]
	v_mfma_f32_16x16x32_bf16 v[100:103], v[172:175], v[196:199], v[100:103]
	ds_read_b128 v[192:195], v212 offset:45056
	global_load_dwordx4 v[88:91], v142, s[92:93] offset:0
	s_waitcnt lgkmcnt(4)
	v_mfma_f32_16x16x32_bf16 v[8:11], v[96:99], v[160:163], v[8:11]
	v_mfma_f32_16x16x32_bf16 v[40:43], v[164:167], v[160:163], v[40:43]
	v_mfma_f32_16x16x32_bf16 v[204:207], v[168:171], v[160:163], v[204:207]
	v_mfma_f32_16x16x32_bf16 v[104:107], v[172:175], v[160:163], v[104:107]
	ds_read_b128 v[196:199], v212 offset:47104
	global_load_dwordx4 v[92:95], v150, s[92:93] offset:0
	s_waitcnt lgkmcnt(4)
	v_mfma_f32_16x16x32_bf16 v[12:15], v[96:99], v[176:179], v[12:15]
	v_mfma_f32_16x16x32_bf16 v[44:47], v[164:167], v[176:179], v[44:47]
	v_mfma_f32_16x16x32_bf16 v[208:211], v[168:171], v[176:179], v[208:211]
	v_mfma_f32_16x16x32_bf16 v[108:111], v[172:175], v[176:179], v[108:111]
	ds_read_b128 v[160:163], v213 offset:32768
	s_waitcnt lgkmcnt(4)
	v_mfma_f32_16x16x32_bf16 v[16:19], v[96:99], v[180:183], v[16:19]
	v_mfma_f32_16x16x32_bf16 v[48:51], v[164:167], v[180:183], v[48:51]
	v_mfma_f32_16x16x32_bf16 v[232:235], v[168:171], v[180:183], v[232:235]
	v_mfma_f32_16x16x32_bf16 v[112:115], v[172:175], v[180:183], v[112:115]
	ds_read_b128 v[176:179], v213 offset:34816
	s_waitcnt lgkmcnt(4)
	v_mfma_f32_16x16x32_bf16 v[20:23], v[96:99], v[188:191], v[20:23]
	v_mfma_f32_16x16x32_bf16 v[52:55], v[164:167], v[188:191], v[52:55]
	v_mfma_f32_16x16x32_bf16 v[236:239], v[168:171], v[188:191], v[236:239]
	v_mfma_f32_16x16x32_bf16 v[116:119], v[172:175], v[188:191], v[116:119]
	ds_read_b128 v[180:183], v213 offset:36864
	s_waitcnt lgkmcnt(4)
	v_mfma_f32_16x16x32_bf16 v[24:27], v[96:99], v[192:195], v[24:27]
	v_mfma_f32_16x16x32_bf16 v[56:59], v[164:167], v[192:195], v[56:59]
	v_mfma_f32_16x16x32_bf16 v[240:243], v[168:171], v[192:195], v[240:243]
	v_mfma_f32_16x16x32_bf16 v[120:123], v[172:175], v[192:195], v[120:123]
	ds_read_b128 v[188:191], v213 offset:38912
	s_waitcnt lgkmcnt(4)
	v_mfma_f32_16x16x32_bf16 v[28:31], v[96:99], v[196:199], v[28:31]
	v_mfma_f32_16x16x32_bf16 v[60:63], v[164:167], v[196:199], v[60:63]
	v_mfma_f32_16x16x32_bf16 v[248:251], v[168:171], v[196:199], v[248:251]
	v_mfma_f32_16x16x32_bf16 v[124:127], v[172:175], v[196:199], v[124:127]
	s_waitcnt vmcnt(16)
	s_barrier
	s_waitcnt vmcnt(8)
	ds_read_b128 v[192:195], v213 offset:40960
	global_load_dwordx4 v[96:99], v142, s[84:85] offset:1024
	s_waitcnt lgkmcnt(4)
	v_mfma_f32_16x16x32_bf16 v[0:3], v[64:67], v[160:163], v[0:3]
	v_mfma_f32_16x16x32_bf16 v[32:35], v[68:71], v[160:163], v[32:35]
	v_mfma_f32_16x16x32_bf16 v[144:147], v[72:75], v[160:163], v[144:147]
	v_mfma_f32_16x16x32_bf16 v[252:255], v[76:79], v[160:163], v[252:255]
	ds_read_b128 v[196:199], v213 offset:43008
	global_load_dwordx4 v[164:167], v150, s[84:85] offset:1024
	s_waitcnt lgkmcnt(4)
	v_mfma_f32_16x16x32_bf16 v[4:7], v[64:67], v[176:179], v[4:7]
	v_mfma_f32_16x16x32_bf16 v[36:39], v[68:71], v[176:179], v[36:39]
	v_mfma_f32_16x16x32_bf16 v[184:187], v[72:75], v[176:179], v[184:187]
	v_mfma_f32_16x16x32_bf16 v[100:103], v[76:79], v[176:179], v[100:103]
	ds_read_b128 v[160:163], v213 offset:45056
	global_load_dwordx4 v[168:171], v142, s[92:93] offset:1024
	s_waitcnt lgkmcnt(4)
	v_mfma_f32_16x16x32_bf16 v[8:11], v[64:67], v[180:183], v[8:11]
	v_mfma_f32_16x16x32_bf16 v[40:43], v[68:71], v[180:183], v[40:43]
	v_mfma_f32_16x16x32_bf16 v[204:207], v[72:75], v[180:183], v[204:207]
	v_mfma_f32_16x16x32_bf16 v[104:107], v[76:79], v[180:183], v[104:107]
	ds_read_b128 v[176:179], v213 offset:47104
	global_load_dwordx4 v[172:175], v150, s[92:93] offset:1024
	s_add_u32 s84, s84, 0x800
	s_addc_u32 s85, s85, 0
	s_add_u32 s92, s92, 0x800
	s_addc_u32 s93, s93, 0
	s_waitcnt lgkmcnt(4)
	v_mfma_f32_16x16x32_bf16 v[12:15], v[64:67], v[188:191], v[12:15]
	v_mfma_f32_16x16x32_bf16 v[44:47], v[68:71], v[188:191], v[44:47]
	v_mfma_f32_16x16x32_bf16 v[208:211], v[72:75], v[188:191], v[208:211]
	v_mfma_f32_16x16x32_bf16 v[108:111], v[76:79], v[188:191], v[108:111]
	ds_read_b128 v[180:183], v212 offset:49152
	s_add_u32 m0, s1, 16384
	s_nop 0
	global_load_lds_dwordx4 v151, s[86:87]
	s_waitcnt lgkmcnt(4)
	v_mfma_f32_16x16x32_bf16 v[16:19], v[64:67], v[192:195], v[16:19]
	v_mfma_f32_16x16x32_bf16 v[48:51], v[68:71], v[192:195], v[48:51]
	v_mfma_f32_16x16x32_bf16 v[232:235], v[72:75], v[192:195], v[232:235]
	v_mfma_f32_16x16x32_bf16 v[112:115], v[76:79], v[192:195], v[112:115]
	ds_read_b128 v[188:191], v212 offset:51200
	s_add_u32 m0, s1, 20480
	s_nop 0
	global_load_lds_dwordx4 v156, s[86:87]
	s_waitcnt lgkmcnt(4)
	v_mfma_f32_16x16x32_bf16 v[20:23], v[64:67], v[196:199], v[20:23]
	v_mfma_f32_16x16x32_bf16 v[52:55], v[68:71], v[196:199], v[52:55]
	v_mfma_f32_16x16x32_bf16 v[236:239], v[72:75], v[196:199], v[236:239]
	v_mfma_f32_16x16x32_bf16 v[116:119], v[76:79], v[196:199], v[116:119]
	ds_read_b128 v[192:195], v212 offset:53248
	s_add_u32 m0, s1, 24576
	s_nop 0
	global_load_lds_dwordx4 v158, s[86:87]
	s_waitcnt lgkmcnt(4)
	v_mfma_f32_16x16x32_bf16 v[24:27], v[64:67], v[160:163], v[24:27]
	v_mfma_f32_16x16x32_bf16 v[56:59], v[68:71], v[160:163], v[56:59]
	v_mfma_f32_16x16x32_bf16 v[240:243], v[72:75], v[160:163], v[240:243]
	v_mfma_f32_16x16x32_bf16 v[120:123], v[76:79], v[160:163], v[120:123]
	ds_read_b128 v[196:199], v212 offset:55296
	s_add_u32 m0, s1, 28672
	s_nop 0
	global_load_lds_dwordx4 v159, s[86:87]
	s_add_u32 s86, s86, 128
	s_addc_u32 s87, s87, 0
	s_waitcnt lgkmcnt(4)
	v_mfma_f32_16x16x32_bf16 v[28:31], v[64:67], v[176:179], v[28:31]
	v_mfma_f32_16x16x32_bf16 v[60:63], v[68:71], v[176:179], v[60:63]
	v_mfma_f32_16x16x32_bf16 v[248:251], v[72:75], v[176:179], v[248:251]
	v_mfma_f32_16x16x32_bf16 v[124:127], v[76:79], v[176:179], v[124:127]
	s_waitcnt vmcnt(8)
	ds_read_b128 v[160:163], v212 offset:57344
	global_load_dwordx4 v[64:67], v142, s[84:85] offset:0
	s_waitcnt lgkmcnt(4)
	v_mfma_f32_16x16x32_bf16 v[0:3], v[80:83], v[180:183], v[0:3]
	v_mfma_f32_16x16x32_bf16 v[32:35], v[84:87], v[180:183], v[32:35]
	v_mfma_f32_16x16x32_bf16 v[144:147], v[88:91], v[180:183], v[144:147]
	v_mfma_f32_16x16x32_bf16 v[252:255], v[92:95], v[180:183], v[252:255]
	ds_read_b128 v[176:179], v212 offset:59392
	global_load_dwordx4 v[68:71], v150, s[84:85] offset:0
	s_waitcnt lgkmcnt(4)
	v_mfma_f32_16x16x32_bf16 v[4:7], v[80:83], v[188:191], v[4:7]
	v_mfma_f32_16x16x32_bf16 v[36:39], v[84:87], v[188:191], v[36:39]
	v_mfma_f32_16x16x32_bf16 v[184:187], v[88:91], v[188:191], v[184:187]
	v_mfma_f32_16x16x32_bf16 v[100:103], v[92:95], v[188:191], v[100:103]
	ds_read_b128 v[180:183], v212 offset:61440
	global_load_dwordx4 v[72:75], v142, s[92:93] offset:0
	s_waitcnt lgkmcnt(4)
	v_mfma_f32_16x16x32_bf16 v[8:11], v[80:83], v[192:195], v[8:11]
	v_mfma_f32_16x16x32_bf16 v[40:43], v[84:87], v[192:195], v[40:43]
	v_mfma_f32_16x16x32_bf16 v[204:207], v[88:91], v[192:195], v[204:207]
	v_mfma_f32_16x16x32_bf16 v[104:107], v[92:95], v[192:195], v[104:107]
	ds_read_b128 v[188:191], v212 offset:63488
	global_load_dwordx4 v[76:79], v150, s[92:93] offset:0
	s_waitcnt lgkmcnt(4)
	v_mfma_f32_16x16x32_bf16 v[12:15], v[80:83], v[196:199], v[12:15]
	v_mfma_f32_16x16x32_bf16 v[44:47], v[84:87], v[196:199], v[44:47]
	v_mfma_f32_16x16x32_bf16 v[208:211], v[88:91], v[196:199], v[208:211]
	v_mfma_f32_16x16x32_bf16 v[108:111], v[92:95], v[196:199], v[108:111]
	ds_read_b128 v[192:195], v213 offset:49152
	s_waitcnt lgkmcnt(4)
	v_mfma_f32_16x16x32_bf16 v[16:19], v[80:83], v[160:163], v[16:19]
	v_mfma_f32_16x16x32_bf16 v[48:51], v[84:87], v[160:163], v[48:51]
	v_mfma_f32_16x16x32_bf16 v[232:235], v[88:91], v[160:163], v[232:235]
	v_mfma_f32_16x16x32_bf16 v[112:115], v[92:95], v[160:163], v[112:115]
	ds_read_b128 v[196:199], v213 offset:51200
	s_waitcnt lgkmcnt(4)
	v_mfma_f32_16x16x32_bf16 v[20:23], v[80:83], v[176:179], v[20:23]
	v_mfma_f32_16x16x32_bf16 v[52:55], v[84:87], v[176:179], v[52:55]
	v_mfma_f32_16x16x32_bf16 v[236:239], v[88:91], v[176:179], v[236:239]
	v_mfma_f32_16x16x32_bf16 v[116:119], v[92:95], v[176:179], v[116:119]
	ds_read_b128 v[160:163], v213 offset:53248
	s_waitcnt lgkmcnt(4)
	v_mfma_f32_16x16x32_bf16 v[24:27], v[80:83], v[180:183], v[24:27]
	v_mfma_f32_16x16x32_bf16 v[56:59], v[84:87], v[180:183], v[56:59]
	v_mfma_f32_16x16x32_bf16 v[240:243], v[88:91], v[180:183], v[240:243]
	v_mfma_f32_16x16x32_bf16 v[120:123], v[92:95], v[180:183], v[120:123]
	ds_read_b128 v[176:179], v213 offset:55296
	s_waitcnt lgkmcnt(4)
	v_mfma_f32_16x16x32_bf16 v[28:31], v[80:83], v[188:191], v[28:31]
	v_mfma_f32_16x16x32_bf16 v[60:63], v[84:87], v[188:191], v[60:63]
	v_mfma_f32_16x16x32_bf16 v[248:251], v[88:91], v[188:191], v[248:251]
	v_mfma_f32_16x16x32_bf16 v[124:127], v[92:95], v[188:191], v[124:127]
	s_waitcnt vmcnt(16)
	s_barrier
	s_waitcnt vmcnt(8)
	ds_read_b128 v[180:183], v213 offset:57344
	global_load_dwordx4 v[80:83], v142, s[84:85] offset:1024
	s_waitcnt lgkmcnt(4)
	v_mfma_f32_16x16x32_bf16 v[0:3], v[96:99], v[192:195], v[0:3]
	v_mfma_f32_16x16x32_bf16 v[32:35], v[164:167], v[192:195], v[32:35]
	v_mfma_f32_16x16x32_bf16 v[144:147], v[168:171], v[192:195], v[144:147]
	v_mfma_f32_16x16x32_bf16 v[252:255], v[172:175], v[192:195], v[252:255]
	ds_read_b128 v[188:191], v213 offset:59392
	global_load_dwordx4 v[84:87], v150, s[84:85] offset:1024
	s_waitcnt lgkmcnt(4)
	v_mfma_f32_16x16x32_bf16 v[4:7], v[96:99], v[196:199], v[4:7]
	v_mfma_f32_16x16x32_bf16 v[36:39], v[164:167], v[196:199], v[36:39]
	v_mfma_f32_16x16x32_bf16 v[184:187], v[168:171], v[196:199], v[184:187]
	v_mfma_f32_16x16x32_bf16 v[100:103], v[172:175], v[196:199], v[100:103]
	ds_read_b128 v[192:195], v213 offset:61440
	global_load_dwordx4 v[88:91], v142, s[92:93] offset:1024
	s_waitcnt lgkmcnt(4)
	v_mfma_f32_16x16x32_bf16 v[8:11], v[96:99], v[160:163], v[8:11]
	v_mfma_f32_16x16x32_bf16 v[40:43], v[164:167], v[160:163], v[40:43]
	v_mfma_f32_16x16x32_bf16 v[204:207], v[168:171], v[160:163], v[204:207]
	v_mfma_f32_16x16x32_bf16 v[104:107], v[172:175], v[160:163], v[104:107]
	ds_read_b128 v[196:199], v213 offset:63488
	global_load_dwordx4 v[92:95], v150, s[92:93] offset:1024
	s_add_u32 s84, s84, 0x800
	s_addc_u32 s85, s85, 0
	s_add_u32 s92, s92, 0x800
	s_addc_u32 s93, s93, 0
	s_waitcnt lgkmcnt(4)
	v_mfma_f32_16x16x32_bf16 v[12:15], v[96:99], v[176:179], v[12:15]
	v_mfma_f32_16x16x32_bf16 v[44:47], v[164:167], v[176:179], v[44:47]
	v_mfma_f32_16x16x32_bf16 v[208:211], v[168:171], v[176:179], v[208:211]
	v_mfma_f32_16x16x32_bf16 v[108:111], v[172:175], v[176:179], v[108:111]
	ds_read_b128 v[160:163], v212 offset:0
	s_add_u32 m0, s1, 32768
	s_nop 0
	global_load_lds_dwordx4 v151, s[86:87]
	s_waitcnt lgkmcnt(4)
	v_mfma_f32_16x16x32_bf16 v[16:19], v[96:99], v[180:183], v[16:19]
	v_mfma_f32_16x16x32_bf16 v[48:51], v[164:167], v[180:183], v[48:51]
	v_mfma_f32_16x16x32_bf16 v[232:235], v[168:171], v[180:183], v[232:235]
	v_mfma_f32_16x16x32_bf16 v[112:115], v[172:175], v[180:183], v[112:115]
	ds_read_b128 v[176:179], v212 offset:2048
	s_add_u32 m0, s1, 36864
	s_nop 0
	global_load_lds_dwordx4 v156, s[86:87]
	s_waitcnt lgkmcnt(4)
	v_mfma_f32_16x16x32_bf16 v[20:23], v[96:99], v[188:191], v[20:23]
	v_mfma_f32_16x16x32_bf16 v[52:55], v[164:167], v[188:191], v[52:55]
	v_mfma_f32_16x16x32_bf16 v[236:239], v[168:171], v[188:191], v[236:239]
	v_mfma_f32_16x16x32_bf16 v[116:119], v[172:175], v[188:191], v[116:119]
	ds_read_b128 v[180:183], v212 offset:4096
	s_add_u32 m0, s1, 40960
	s_nop 0
	global_load_lds_dwordx4 v158, s[86:87]
	s_waitcnt lgkmcnt(4)
	v_mfma_f32_16x16x32_bf16 v[24:27], v[96:99], v[192:195], v[24:27]
	v_mfma_f32_16x16x32_bf16 v[56:59], v[164:167], v[192:195], v[56:59]
	v_mfma_f32_16x16x32_bf16 v[240:243], v[168:171], v[192:195], v[240:243]
	v_mfma_f32_16x16x32_bf16 v[120:123], v[172:175], v[192:195], v[120:123]
	ds_read_b128 v[188:191], v212 offset:6144
	s_add_u32 m0, s1, 45056
	s_nop 0
	global_load_lds_dwordx4 v159, s[86:87]
	s_add_u32 s86, s86, 128
	s_addc_u32 s87, s87, 0
	s_waitcnt lgkmcnt(4)
	v_mfma_f32_16x16x32_bf16 v[28:31], v[96:99], v[196:199], v[28:31]
	v_mfma_f32_16x16x32_bf16 v[60:63], v[164:167], v[196:199], v[60:63]
	v_mfma_f32_16x16x32_bf16 v[248:251], v[168:171], v[196:199], v[248:251]
	v_mfma_f32_16x16x32_bf16 v[124:127], v[172:175], v[196:199], v[124:127]
	s_waitcnt vmcnt(8)
	ds_read_b128 v[192:195], v212 offset:8192
	global_load_dwordx4 v[96:99], v142, s[84:85] offset:0
	s_waitcnt lgkmcnt(4)
	v_mfma_f32_16x16x32_bf16 v[0:3], v[64:67], v[160:163], v[0:3]
	v_mfma_f32_16x16x32_bf16 v[32:35], v[68:71], v[160:163], v[32:35]
	v_mfma_f32_16x16x32_bf16 v[144:147], v[72:75], v[160:163], v[144:147]
	v_mfma_f32_16x16x32_bf16 v[252:255], v[76:79], v[160:163], v[252:255]
	ds_read_b128 v[196:199], v212 offset:10240
	global_load_dwordx4 v[164:167], v150, s[84:85] offset:0
	s_waitcnt lgkmcnt(4)
	v_mfma_f32_16x16x32_bf16 v[4:7], v[64:67], v[176:179], v[4:7]
	v_mfma_f32_16x16x32_bf16 v[36:39], v[68:71], v[176:179], v[36:39]
	v_mfma_f32_16x16x32_bf16 v[184:187], v[72:75], v[176:179], v[184:187]
	v_mfma_f32_16x16x32_bf16 v[100:103], v[76:79], v[176:179], v[100:103]
	ds_read_b128 v[160:163], v212 offset:12288
	global_load_dwordx4 v[168:171], v142, s[92:93] offset:0
	s_waitcnt lgkmcnt(4)
	v_mfma_f32_16x16x32_bf16 v[8:11], v[64:67], v[180:183], v[8:11]
	v_mfma_f32_16x16x32_bf16 v[40:43], v[68:71], v[180:183], v[40:43]
	v_mfma_f32_16x16x32_bf16 v[204:207], v[72:75], v[180:183], v[204:207]
	v_mfma_f32_16x16x32_bf16 v[104:107], v[76:79], v[180:183], v[104:107]
	ds_read_b128 v[176:179], v212 offset:14336
	global_load_dwordx4 v[172:175], v150, s[92:93] offset:0
	s_waitcnt lgkmcnt(4)
	v_mfma_f32_16x16x32_bf16 v[12:15], v[64:67], v[188:191], v[12:15]
	v_mfma_f32_16x16x32_bf16 v[44:47], v[68:71], v[188:191], v[44:47]
	v_mfma_f32_16x16x32_bf16 v[208:211], v[72:75], v[188:191], v[208:211]
	v_mfma_f32_16x16x32_bf16 v[108:111], v[76:79], v[188:191], v[108:111]
	ds_read_b128 v[180:183], v213 offset:0
	s_waitcnt lgkmcnt(4)
	v_mfma_f32_16x16x32_bf16 v[16:19], v[64:67], v[192:195], v[16:19]
	v_mfma_f32_16x16x32_bf16 v[48:51], v[68:71], v[192:195], v[48:51]
	v_mfma_f32_16x16x32_bf16 v[232:235], v[72:75], v[192:195], v[232:235]
	v_mfma_f32_16x16x32_bf16 v[112:115], v[76:79], v[192:195], v[112:115]
	ds_read_b128 v[188:191], v213 offset:2048
	s_waitcnt lgkmcnt(4)
	v_mfma_f32_16x16x32_bf16 v[20:23], v[64:67], v[196:199], v[20:23]
	v_mfma_f32_16x16x32_bf16 v[52:55], v[68:71], v[196:199], v[52:55]
	v_mfma_f32_16x16x32_bf16 v[236:239], v[72:75], v[196:199], v[236:239]
	v_mfma_f32_16x16x32_bf16 v[116:119], v[76:79], v[196:199], v[116:119]
	ds_read_b128 v[192:195], v213 offset:4096
	s_waitcnt lgkmcnt(4)
	v_mfma_f32_16x16x32_bf16 v[24:27], v[64:67], v[160:163], v[24:27]
	v_mfma_f32_16x16x32_bf16 v[56:59], v[68:71], v[160:163], v[56:59]
	v_mfma_f32_16x16x32_bf16 v[240:243], v[72:75], v[160:163], v[240:243]
	v_mfma_f32_16x16x32_bf16 v[120:123], v[76:79], v[160:163], v[120:123]
	ds_read_b128 v[196:199], v213 offset:6144
	s_waitcnt lgkmcnt(4)
	v_mfma_f32_16x16x32_bf16 v[28:31], v[64:67], v[176:179], v[28:31]
	v_mfma_f32_16x16x32_bf16 v[60:63], v[68:71], v[176:179], v[60:63]
	v_mfma_f32_16x16x32_bf16 v[248:251], v[72:75], v[176:179], v[248:251]
	v_mfma_f32_16x16x32_bf16 v[124:127], v[76:79], v[176:179], v[124:127]
	s_waitcnt vmcnt(16)
	s_barrier
	s_waitcnt vmcnt(8)
	ds_read_b128 v[160:163], v213 offset:8192
	global_load_dwordx4 v[64:67], v142, s[84:85] offset:1024
	s_waitcnt lgkmcnt(4)
	v_mfma_f32_16x16x32_bf16 v[0:3], v[80:83], v[180:183], v[0:3]
	v_mfma_f32_16x16x32_bf16 v[32:35], v[84:87], v[180:183], v[32:35]
	v_mfma_f32_16x16x32_bf16 v[144:147], v[88:91], v[180:183], v[144:147]
	v_mfma_f32_16x16x32_bf16 v[252:255], v[92:95], v[180:183], v[252:255]
	ds_read_b128 v[176:179], v213 offset:10240
	global_load_dwordx4 v[68:71], v150, s[84:85] offset:1024
	s_waitcnt lgkmcnt(4)
	v_mfma_f32_16x16x32_bf16 v[4:7], v[80:83], v[188:191], v[4:7]
	v_mfma_f32_16x16x32_bf16 v[36:39], v[84:87], v[188:191], v[36:39]
	v_mfma_f32_16x16x32_bf16 v[184:187], v[88:91], v[188:191], v[184:187]
	v_mfma_f32_16x16x32_bf16 v[100:103], v[92:95], v[188:191], v[100:103]
	ds_read_b128 v[180:183], v213 offset:12288
	global_load_dwordx4 v[72:75], v142, s[92:93] offset:1024
	s_waitcnt lgkmcnt(4)
	v_mfma_f32_16x16x32_bf16 v[8:11], v[80:83], v[192:195], v[8:11]
	v_mfma_f32_16x16x32_bf16 v[40:43], v[84:87], v[192:195], v[40:43]
	v_mfma_f32_16x16x32_bf16 v[204:207], v[88:91], v[192:195], v[204:207]
	v_mfma_f32_16x16x32_bf16 v[104:107], v[92:95], v[192:195], v[104:107]
	ds_read_b128 v[188:191], v213 offset:14336
	global_load_dwordx4 v[76:79], v150, s[92:93] offset:1024
	s_add_u32 s84, s84, 0x800
	s_addc_u32 s85, s85, 0
	s_add_u32 s92, s92, 0x800
	s_addc_u32 s93, s93, 0
	s_waitcnt lgkmcnt(4)
	v_mfma_f32_16x16x32_bf16 v[12:15], v[80:83], v[196:199], v[12:15]
	v_mfma_f32_16x16x32_bf16 v[44:47], v[84:87], v[196:199], v[44:47]
	v_mfma_f32_16x16x32_bf16 v[208:211], v[88:91], v[196:199], v[208:211]
	v_mfma_f32_16x16x32_bf16 v[108:111], v[92:95], v[196:199], v[108:111]
	ds_read_b128 v[192:195], v212 offset:16384
	s_add_u32 m0, s1, 49152
	s_nop 0
	global_load_lds_dwordx4 v151, s[86:87]
	s_waitcnt lgkmcnt(4)
	v_mfma_f32_16x16x32_bf16 v[16:19], v[80:83], v[160:163], v[16:19]
	v_mfma_f32_16x16x32_bf16 v[48:51], v[84:87], v[160:163], v[48:51]
	v_mfma_f32_16x16x32_bf16 v[232:235], v[88:91], v[160:163], v[232:235]
	v_mfma_f32_16x16x32_bf16 v[112:115], v[92:95], v[160:163], v[112:115]
	ds_read_b128 v[196:199], v212 offset:18432
	s_add_u32 m0, s1, 53248
	s_nop 0
	global_load_lds_dwordx4 v156, s[86:87]
	s_waitcnt lgkmcnt(4)
	v_mfma_f32_16x16x32_bf16 v[20:23], v[80:83], v[176:179], v[20:23]
	v_mfma_f32_16x16x32_bf16 v[52:55], v[84:87], v[176:179], v[52:55]
	v_mfma_f32_16x16x32_bf16 v[236:239], v[88:91], v[176:179], v[236:239]
	v_mfma_f32_16x16x32_bf16 v[116:119], v[92:95], v[176:179], v[116:119]
	ds_read_b128 v[160:163], v212 offset:20480
	s_add_u32 m0, s1, 57344
	s_nop 0
	global_load_lds_dwordx4 v158, s[86:87]
	s_waitcnt lgkmcnt(4)
	v_mfma_f32_16x16x32_bf16 v[24:27], v[80:83], v[180:183], v[24:27]
	v_mfma_f32_16x16x32_bf16 v[56:59], v[84:87], v[180:183], v[56:59]
	v_mfma_f32_16x16x32_bf16 v[240:243], v[88:91], v[180:183], v[240:243]
	v_mfma_f32_16x16x32_bf16 v[120:123], v[92:95], v[180:183], v[120:123]
	ds_read_b128 v[176:179], v212 offset:22528
	s_add_u32 m0, s1, 61440
	s_nop 0
	global_load_lds_dwordx4 v159, s[86:87]
	s_add_u32 s86, s86, 128
	s_addc_u32 s87, s87, 0
	s_waitcnt lgkmcnt(4)
	v_mfma_f32_16x16x32_bf16 v[28:31], v[80:83], v[188:191], v[28:31]
	v_mfma_f32_16x16x32_bf16 v[60:63], v[84:87], v[188:191], v[60:63]
	v_mfma_f32_16x16x32_bf16 v[248:251], v[88:91], v[188:191], v[248:251]
	v_mfma_f32_16x16x32_bf16 v[124:127], v[92:95], v[188:191], v[124:127]
	s_waitcnt vmcnt(8)
	ds_read_b128 v[180:183], v212 offset:24576
	global_load_dwordx4 v[80:83], v142, s[84:85] offset:0
	s_waitcnt lgkmcnt(4)
	v_mfma_f32_16x16x32_bf16 v[0:3], v[96:99], v[192:195], v[0:3]
	v_mfma_f32_16x16x32_bf16 v[32:35], v[164:167], v[192:195], v[32:35]
	v_mfma_f32_16x16x32_bf16 v[144:147], v[168:171], v[192:195], v[144:147]
	v_mfma_f32_16x16x32_bf16 v[252:255], v[172:175], v[192:195], v[252:255]
	ds_read_b128 v[188:191], v212 offset:26624
	global_load_dwordx4 v[84:87], v150, s[84:85] offset:0
	s_waitcnt lgkmcnt(4)
	v_mfma_f32_16x16x32_bf16 v[4:7], v[96:99], v[196:199], v[4:7]
	v_mfma_f32_16x16x32_bf16 v[36:39], v[164:167], v[196:199], v[36:39]
	v_mfma_f32_16x16x32_bf16 v[184:187], v[168:171], v[196:199], v[184:187]
	v_mfma_f32_16x16x32_bf16 v[100:103], v[172:175], v[196:199], v[100:103]
	ds_read_b128 v[192:195], v212 offset:28672
	global_load_dwordx4 v[88:91], v142, s[92:93] offset:0
	s_waitcnt lgkmcnt(4)
	v_mfma_f32_16x16x32_bf16 v[8:11], v[96:99], v[160:163], v[8:11]
	v_mfma_f32_16x16x32_bf16 v[40:43], v[164:167], v[160:163], v[40:43]
	v_mfma_f32_16x16x32_bf16 v[204:207], v[168:171], v[160:163], v[204:207]
	v_mfma_f32_16x16x32_bf16 v[104:107], v[172:175], v[160:163], v[104:107]
	ds_read_b128 v[196:199], v212 offset:30720
	global_load_dwordx4 v[92:95], v150, s[92:93] offset:0
	s_waitcnt lgkmcnt(4)
	v_mfma_f32_16x16x32_bf16 v[12:15], v[96:99], v[176:179], v[12:15]
	v_mfma_f32_16x16x32_bf16 v[44:47], v[164:167], v[176:179], v[44:47]
	v_mfma_f32_16x16x32_bf16 v[208:211], v[168:171], v[176:179], v[208:211]
	v_mfma_f32_16x16x32_bf16 v[108:111], v[172:175], v[176:179], v[108:111]
	ds_read_b128 v[160:163], v213 offset:16384
	s_waitcnt lgkmcnt(4)
	v_mfma_f32_16x16x32_bf16 v[16:19], v[96:99], v[180:183], v[16:19]
	v_mfma_f32_16x16x32_bf16 v[48:51], v[164:167], v[180:183], v[48:51]
	v_mfma_f32_16x16x32_bf16 v[232:235], v[168:171], v[180:183], v[232:235]
	v_mfma_f32_16x16x32_bf16 v[112:115], v[172:175], v[180:183], v[112:115]
	ds_read_b128 v[176:179], v213 offset:18432
	s_waitcnt lgkmcnt(4)
	v_mfma_f32_16x16x32_bf16 v[20:23], v[96:99], v[188:191], v[20:23]
	v_mfma_f32_16x16x32_bf16 v[52:55], v[164:167], v[188:191], v[52:55]
	v_mfma_f32_16x16x32_bf16 v[236:239], v[168:171], v[188:191], v[236:239]
	v_mfma_f32_16x16x32_bf16 v[116:119], v[172:175], v[188:191], v[116:119]
	ds_read_b128 v[180:183], v213 offset:20480
	s_waitcnt lgkmcnt(4)
	v_mfma_f32_16x16x32_bf16 v[24:27], v[96:99], v[192:195], v[24:27]
	v_mfma_f32_16x16x32_bf16 v[56:59], v[164:167], v[192:195], v[56:59]
	v_mfma_f32_16x16x32_bf16 v[240:243], v[168:171], v[192:195], v[240:243]
	v_mfma_f32_16x16x32_bf16 v[120:123], v[172:175], v[192:195], v[120:123]
	ds_read_b128 v[188:191], v213 offset:22528
	s_waitcnt lgkmcnt(4)
	v_mfma_f32_16x16x32_bf16 v[28:31], v[96:99], v[196:199], v[28:31]
	v_mfma_f32_16x16x32_bf16 v[60:63], v[164:167], v[196:199], v[60:63]
	v_mfma_f32_16x16x32_bf16 v[248:251], v[168:171], v[196:199], v[248:251]
	v_mfma_f32_16x16x32_bf16 v[124:127], v[172:175], v[196:199], v[124:127]
	s_waitcnt vmcnt(16)
	s_barrier
	s_waitcnt vmcnt(8)
	ds_read_b128 v[192:195], v213 offset:24576
	global_load_dwordx4 v[96:99], v142, s[84:85] offset:1024
	s_waitcnt lgkmcnt(4)
	v_mfma_f32_16x16x32_bf16 v[0:3], v[64:67], v[160:163], v[0:3]
	v_mfma_f32_16x16x32_bf16 v[32:35], v[68:71], v[160:163], v[32:35]
	v_mfma_f32_16x16x32_bf16 v[144:147], v[72:75], v[160:163], v[144:147]
	v_mfma_f32_16x16x32_bf16 v[252:255], v[76:79], v[160:163], v[252:255]
	ds_read_b128 v[196:199], v213 offset:26624
	global_load_dwordx4 v[164:167], v150, s[84:85] offset:1024
	s_waitcnt lgkmcnt(4)
	v_mfma_f32_16x16x32_bf16 v[4:7], v[64:67], v[176:179], v[4:7]
	v_mfma_f32_16x16x32_bf16 v[36:39], v[68:71], v[176:179], v[36:39]
	v_mfma_f32_16x16x32_bf16 v[184:187], v[72:75], v[176:179], v[184:187]
	v_mfma_f32_16x16x32_bf16 v[100:103], v[76:79], v[176:179], v[100:103]
	ds_read_b128 v[160:163], v213 offset:28672
	global_load_dwordx4 v[168:171], v142, s[92:93] offset:1024
	s_waitcnt lgkmcnt(4)
	v_mfma_f32_16x16x32_bf16 v[8:11], v[64:67], v[180:183], v[8:11]
	v_mfma_f32_16x16x32_bf16 v[40:43], v[68:71], v[180:183], v[40:43]
	v_mfma_f32_16x16x32_bf16 v[204:207], v[72:75], v[180:183], v[204:207]
	v_mfma_f32_16x16x32_bf16 v[104:107], v[76:79], v[180:183], v[104:107]
	ds_read_b128 v[176:179], v213 offset:30720
	global_load_dwordx4 v[172:175], v150, s[92:93] offset:1024
	s_add_u32 s84, s84, 0x800
	s_addc_u32 s85, s85, 0
	s_add_u32 s92, s92, 0x800
	s_addc_u32 s93, s93, 0
	s_waitcnt lgkmcnt(4)
	v_mfma_f32_16x16x32_bf16 v[12:15], v[64:67], v[188:191], v[12:15]
	v_mfma_f32_16x16x32_bf16 v[44:47], v[68:71], v[188:191], v[44:47]
	v_mfma_f32_16x16x32_bf16 v[208:211], v[72:75], v[188:191], v[208:211]
	v_mfma_f32_16x16x32_bf16 v[108:111], v[76:79], v[188:191], v[108:111]
	ds_read_b128 v[180:183], v212 offset:32768
	s_waitcnt lgkmcnt(4)
	v_mfma_f32_16x16x32_bf16 v[16:19], v[64:67], v[192:195], v[16:19]
	v_mfma_f32_16x16x32_bf16 v[48:51], v[68:71], v[192:195], v[48:51]
	v_mfma_f32_16x16x32_bf16 v[232:235], v[72:75], v[192:195], v[232:235]
	v_mfma_f32_16x16x32_bf16 v[112:115], v[76:79], v[192:195], v[112:115]
	ds_read_b128 v[188:191], v212 offset:34816
	s_waitcnt lgkmcnt(4)
	v_mfma_f32_16x16x32_bf16 v[20:23], v[64:67], v[196:199], v[20:23]
	v_mfma_f32_16x16x32_bf16 v[52:55], v[68:71], v[196:199], v[52:55]
	v_mfma_f32_16x16x32_bf16 v[236:239], v[72:75], v[196:199], v[236:239]
	v_mfma_f32_16x16x32_bf16 v[116:119], v[76:79], v[196:199], v[116:119]
	ds_read_b128 v[192:195], v212 offset:36864
	s_waitcnt lgkmcnt(4)
	v_mfma_f32_16x16x32_bf16 v[24:27], v[64:67], v[160:163], v[24:27]
	v_mfma_f32_16x16x32_bf16 v[56:59], v[68:71], v[160:163], v[56:59]
	v_mfma_f32_16x16x32_bf16 v[240:243], v[72:75], v[160:163], v[240:243]
	v_mfma_f32_16x16x32_bf16 v[120:123], v[76:79], v[160:163], v[120:123]
	ds_read_b128 v[196:199], v212 offset:38912
	s_waitcnt lgkmcnt(4)
	v_mfma_f32_16x16x32_bf16 v[28:31], v[64:67], v[176:179], v[28:31]
	v_mfma_f32_16x16x32_bf16 v[60:63], v[68:71], v[176:179], v[60:63]
	v_mfma_f32_16x16x32_bf16 v[248:251], v[72:75], v[176:179], v[248:251]
	v_mfma_f32_16x16x32_bf16 v[124:127], v[76:79], v[176:179], v[124:127]
	s_waitcnt vmcnt(4)
	ds_read_b128 v[160:163], v212 offset:40960
	global_load_dwordx4 v[64:67], v142, s[84:85] offset:0
	s_waitcnt lgkmcnt(4)
	v_mfma_f32_16x16x32_bf16 v[0:3], v[80:83], v[180:183], v[0:3]
	v_mfma_f32_16x16x32_bf16 v[32:35], v[84:87], v[180:183], v[32:35]
	v_mfma_f32_16x16x32_bf16 v[144:147], v[88:91], v[180:183], v[144:147]
	v_mfma_f32_16x16x32_bf16 v[252:255], v[92:95], v[180:183], v[252:255]
	ds_read_b128 v[176:179], v212 offset:43008
	global_load_dwordx4 v[68:71], v150, s[84:85] offset:0
	s_waitcnt lgkmcnt(4)
	v_mfma_f32_16x16x32_bf16 v[4:7], v[80:83], v[188:191], v[4:7]
	v_mfma_f32_16x16x32_bf16 v[36:39], v[84:87], v[188:191], v[36:39]
	v_mfma_f32_16x16x32_bf16 v[184:187], v[88:91], v[188:191], v[184:187]
	v_mfma_f32_16x16x32_bf16 v[100:103], v[92:95], v[188:191], v[100:103]
	ds_read_b128 v[180:183], v212 offset:45056
	global_load_dwordx4 v[72:75], v142, s[92:93] offset:0
	s_waitcnt lgkmcnt(4)
	v_mfma_f32_16x16x32_bf16 v[8:11], v[80:83], v[192:195], v[8:11]
	v_mfma_f32_16x16x32_bf16 v[40:43], v[84:87], v[192:195], v[40:43]
	v_mfma_f32_16x16x32_bf16 v[204:207], v[88:91], v[192:195], v[204:207]
	v_mfma_f32_16x16x32_bf16 v[104:107], v[92:95], v[192:195], v[104:107]
	ds_read_b128 v[188:191], v212 offset:47104
	global_load_dwordx4 v[76:79], v150, s[92:93] offset:0
	s_waitcnt lgkmcnt(4)
	v_mfma_f32_16x16x32_bf16 v[12:15], v[80:83], v[196:199], v[12:15]
	v_mfma_f32_16x16x32_bf16 v[44:47], v[84:87], v[196:199], v[44:47]
	v_mfma_f32_16x16x32_bf16 v[208:211], v[88:91], v[196:199], v[208:211]
	v_mfma_f32_16x16x32_bf16 v[108:111], v[92:95], v[196:199], v[108:111]
	ds_read_b128 v[192:195], v213 offset:32768
	s_waitcnt lgkmcnt(4)
	v_mfma_f32_16x16x32_bf16 v[16:19], v[80:83], v[160:163], v[16:19]
	v_mfma_f32_16x16x32_bf16 v[48:51], v[84:87], v[160:163], v[48:51]
	v_mfma_f32_16x16x32_bf16 v[232:235], v[88:91], v[160:163], v[232:235]
	v_mfma_f32_16x16x32_bf16 v[112:115], v[92:95], v[160:163], v[112:115]
	ds_read_b128 v[196:199], v213 offset:34816
	s_waitcnt lgkmcnt(4)
	v_mfma_f32_16x16x32_bf16 v[20:23], v[80:83], v[176:179], v[20:23]
	v_mfma_f32_16x16x32_bf16 v[52:55], v[84:87], v[176:179], v[52:55]
	v_mfma_f32_16x16x32_bf16 v[236:239], v[88:91], v[176:179], v[236:239]
	v_mfma_f32_16x16x32_bf16 v[116:119], v[92:95], v[176:179], v[116:119]
	ds_read_b128 v[160:163], v213 offset:36864
	s_waitcnt lgkmcnt(4)
	v_mfma_f32_16x16x32_bf16 v[24:27], v[80:83], v[180:183], v[24:27]
	v_mfma_f32_16x16x32_bf16 v[56:59], v[84:87], v[180:183], v[56:59]
	v_mfma_f32_16x16x32_bf16 v[240:243], v[88:91], v[180:183], v[240:243]
	v_mfma_f32_16x16x32_bf16 v[120:123], v[92:95], v[180:183], v[120:123]
	ds_read_b128 v[176:179], v213 offset:38912
	s_waitcnt lgkmcnt(4)
	v_mfma_f32_16x16x32_bf16 v[28:31], v[80:83], v[188:191], v[28:31]
	v_mfma_f32_16x16x32_bf16 v[60:63], v[84:87], v[188:191], v[60:63]
	v_mfma_f32_16x16x32_bf16 v[248:251], v[88:91], v[188:191], v[248:251]
	v_mfma_f32_16x16x32_bf16 v[124:127], v[92:95], v[188:191], v[124:127]
	s_waitcnt vmcnt(12)
	s_barrier
	s_waitcnt vmcnt(4)
	ds_read_b128 v[180:183], v213 offset:40960
	global_load_dwordx4 v[80:83], v142, s[84:85] offset:1024
	s_waitcnt lgkmcnt(4)
	v_mfma_f32_16x16x32_bf16 v[0:3], v[96:99], v[192:195], v[0:3]
	v_mfma_f32_16x16x32_bf16 v[32:35], v[164:167], v[192:195], v[32:35]
	v_mfma_f32_16x16x32_bf16 v[144:147], v[168:171], v[192:195], v[144:147]
	v_mfma_f32_16x16x32_bf16 v[252:255], v[172:175], v[192:195], v[252:255]
	ds_read_b128 v[188:191], v213 offset:43008
	global_load_dwordx4 v[84:87], v150, s[84:85] offset:1024
	s_waitcnt lgkmcnt(4)
	v_mfma_f32_16x16x32_bf16 v[4:7], v[96:99], v[196:199], v[4:7]
	v_mfma_f32_16x16x32_bf16 v[36:39], v[164:167], v[196:199], v[36:39]
	v_mfma_f32_16x16x32_bf16 v[184:187], v[168:171], v[196:199], v[184:187]
	v_mfma_f32_16x16x32_bf16 v[100:103], v[172:175], v[196:199], v[100:103]
	ds_read_b128 v[192:195], v213 offset:45056
	global_load_dwordx4 v[88:91], v142, s[92:93] offset:1024
	s_waitcnt lgkmcnt(4)
	v_mfma_f32_16x16x32_bf16 v[8:11], v[96:99], v[160:163], v[8:11]
	v_mfma_f32_16x16x32_bf16 v[40:43], v[164:167], v[160:163], v[40:43]
	v_mfma_f32_16x16x32_bf16 v[204:207], v[168:171], v[160:163], v[204:207]
	v_mfma_f32_16x16x32_bf16 v[104:107], v[172:175], v[160:163], v[104:107]
	ds_read_b128 v[196:199], v213 offset:47104
	global_load_dwordx4 v[92:95], v150, s[92:93] offset:1024
	s_add_u32 s84, s84, 0x800
	s_addc_u32 s85, s85, 0
	s_add_u32 s92, s92, 0x800
	s_addc_u32 s93, s93, 0
	s_waitcnt lgkmcnt(4)
	v_mfma_f32_16x16x32_bf16 v[12:15], v[96:99], v[176:179], v[12:15]
	v_mfma_f32_16x16x32_bf16 v[44:47], v[164:167], v[176:179], v[44:47]
	v_mfma_f32_16x16x32_bf16 v[208:211], v[168:171], v[176:179], v[208:211]
	v_mfma_f32_16x16x32_bf16 v[108:111], v[172:175], v[176:179], v[108:111]
	ds_read_b128 v[160:163], v212 offset:49152
	s_waitcnt lgkmcnt(4)
	v_mfma_f32_16x16x32_bf16 v[16:19], v[96:99], v[180:183], v[16:19]
	v_mfma_f32_16x16x32_bf16 v[48:51], v[164:167], v[180:183], v[48:51]
	v_mfma_f32_16x16x32_bf16 v[232:235], v[168:171], v[180:183], v[232:235]
	v_mfma_f32_16x16x32_bf16 v[112:115], v[172:175], v[180:183], v[112:115]
	ds_read_b128 v[176:179], v212 offset:51200
	s_waitcnt lgkmcnt(4)
	v_mfma_f32_16x16x32_bf16 v[20:23], v[96:99], v[188:191], v[20:23]
	v_mfma_f32_16x16x32_bf16 v[52:55], v[164:167], v[188:191], v[52:55]
	v_mfma_f32_16x16x32_bf16 v[236:239], v[168:171], v[188:191], v[236:239]
	v_mfma_f32_16x16x32_bf16 v[116:119], v[172:175], v[188:191], v[116:119]
	ds_read_b128 v[180:183], v212 offset:53248
	s_waitcnt lgkmcnt(4)
	v_mfma_f32_16x16x32_bf16 v[24:27], v[96:99], v[192:195], v[24:27]
	v_mfma_f32_16x16x32_bf16 v[56:59], v[164:167], v[192:195], v[56:59]
	v_mfma_f32_16x16x32_bf16 v[240:243], v[168:171], v[192:195], v[240:243]
	v_mfma_f32_16x16x32_bf16 v[120:123], v[172:175], v[192:195], v[120:123]
	ds_read_b128 v[188:191], v212 offset:55296
	s_waitcnt lgkmcnt(4)
	v_mfma_f32_16x16x32_bf16 v[28:31], v[96:99], v[196:199], v[28:31]
	v_mfma_f32_16x16x32_bf16 v[60:63], v[164:167], v[196:199], v[60:63]
	v_mfma_f32_16x16x32_bf16 v[248:251], v[168:171], v[196:199], v[248:251]
	v_mfma_f32_16x16x32_bf16 v[124:127], v[172:175], v[196:199], v[124:127]
	s_waitcnt vmcnt(4)
	ds_read_b128 v[192:195], v212 offset:57344
	s_waitcnt lgkmcnt(4)
	v_mfma_f32_16x16x32_bf16 v[0:3], v[64:67], v[160:163], v[0:3]
	v_mfma_f32_16x16x32_bf16 v[32:35], v[68:71], v[160:163], v[32:35]
	v_mfma_f32_16x16x32_bf16 v[144:147], v[72:75], v[160:163], v[144:147]
	v_mfma_f32_16x16x32_bf16 v[252:255], v[76:79], v[160:163], v[252:255]
	ds_read_b128 v[196:199], v212 offset:59392
	s_waitcnt lgkmcnt(4)
	v_mfma_f32_16x16x32_bf16 v[4:7], v[64:67], v[176:179], v[4:7]
	v_mfma_f32_16x16x32_bf16 v[36:39], v[68:71], v[176:179], v[36:39]
	v_mfma_f32_16x16x32_bf16 v[184:187], v[72:75], v[176:179], v[184:187]
	v_mfma_f32_16x16x32_bf16 v[100:103], v[76:79], v[176:179], v[100:103]
	ds_read_b128 v[160:163], v212 offset:61440
	s_waitcnt lgkmcnt(4)
	v_mfma_f32_16x16x32_bf16 v[8:11], v[64:67], v[180:183], v[8:11]
	v_mfma_f32_16x16x32_bf16 v[40:43], v[68:71], v[180:183], v[40:43]
	v_mfma_f32_16x16x32_bf16 v[204:207], v[72:75], v[180:183], v[204:207]
	v_mfma_f32_16x16x32_bf16 v[104:107], v[76:79], v[180:183], v[104:107]
	ds_read_b128 v[176:179], v212 offset:63488
	s_waitcnt lgkmcnt(4)
	v_mfma_f32_16x16x32_bf16 v[12:15], v[64:67], v[188:191], v[12:15]
	v_mfma_f32_16x16x32_bf16 v[44:47], v[68:71], v[188:191], v[44:47]
	v_mfma_f32_16x16x32_bf16 v[208:211], v[72:75], v[188:191], v[208:211]
	v_mfma_f32_16x16x32_bf16 v[108:111], v[76:79], v[188:191], v[108:111]
	ds_read_b128 v[180:183], v213 offset:49152
	s_waitcnt lgkmcnt(4)
	v_mfma_f32_16x16x32_bf16 v[16:19], v[64:67], v[192:195], v[16:19]
	v_mfma_f32_16x16x32_bf16 v[48:51], v[68:71], v[192:195], v[48:51]
	v_mfma_f32_16x16x32_bf16 v[232:235], v[72:75], v[192:195], v[232:235]
	v_mfma_f32_16x16x32_bf16 v[112:115], v[76:79], v[192:195], v[112:115]
	ds_read_b128 v[188:191], v213 offset:51200
	s_waitcnt lgkmcnt(4)
	v_mfma_f32_16x16x32_bf16 v[20:23], v[64:67], v[196:199], v[20:23]
	v_mfma_f32_16x16x32_bf16 v[52:55], v[68:71], v[196:199], v[52:55]
	v_mfma_f32_16x16x32_bf16 v[236:239], v[72:75], v[196:199], v[236:239]
	v_mfma_f32_16x16x32_bf16 v[116:119], v[76:79], v[196:199], v[116:119]
	ds_read_b128 v[192:195], v213 offset:53248
	s_waitcnt lgkmcnt(4)
	v_mfma_f32_16x16x32_bf16 v[24:27], v[64:67], v[160:163], v[24:27]
	v_mfma_f32_16x16x32_bf16 v[56:59], v[68:71], v[160:163], v[56:59]
	v_mfma_f32_16x16x32_bf16 v[240:243], v[72:75], v[160:163], v[240:243]
	v_mfma_f32_16x16x32_bf16 v[120:123], v[76:79], v[160:163], v[120:123]
	ds_read_b128 v[196:199], v213 offset:55296
	s_waitcnt lgkmcnt(4)
	v_mfma_f32_16x16x32_bf16 v[28:31], v[64:67], v[176:179], v[28:31]
	v_mfma_f32_16x16x32_bf16 v[60:63], v[68:71], v[176:179], v[60:63]
	v_mfma_f32_16x16x32_bf16 v[248:251], v[72:75], v[176:179], v[248:251]
	v_mfma_f32_16x16x32_bf16 v[124:127], v[76:79], v[176:179], v[124:127]
	s_waitcnt vmcnt(0)
	ds_read_b128 v[160:163], v213 offset:57344
	s_waitcnt lgkmcnt(4)
	v_mfma_f32_16x16x32_bf16 v[0:3], v[80:83], v[180:183], v[0:3]
	v_mfma_f32_16x16x32_bf16 v[32:35], v[84:87], v[180:183], v[32:35]
	v_mfma_f32_16x16x32_bf16 v[144:147], v[88:91], v[180:183], v[144:147]
	v_mfma_f32_16x16x32_bf16 v[252:255], v[92:95], v[180:183], v[252:255]
	ds_read_b128 v[176:179], v213 offset:59392
	s_waitcnt lgkmcnt(4)
	v_mfma_f32_16x16x32_bf16 v[4:7], v[80:83], v[188:191], v[4:7]
	v_mfma_f32_16x16x32_bf16 v[36:39], v[84:87], v[188:191], v[36:39]
	v_mfma_f32_16x16x32_bf16 v[184:187], v[88:91], v[188:191], v[184:187]
	v_mfma_f32_16x16x32_bf16 v[100:103], v[92:95], v[188:191], v[100:103]
	ds_read_b128 v[180:183], v213 offset:61440
	s_waitcnt lgkmcnt(4)
	v_mfma_f32_16x16x32_bf16 v[8:11], v[80:83], v[192:195], v[8:11]
	v_mfma_f32_16x16x32_bf16 v[40:43], v[84:87], v[192:195], v[40:43]
	v_mfma_f32_16x16x32_bf16 v[204:207], v[88:91], v[192:195], v[204:207]
	v_mfma_f32_16x16x32_bf16 v[104:107], v[92:95], v[192:195], v[104:107]
	ds_read_b128 v[188:191], v213 offset:63488
	s_waitcnt lgkmcnt(4)
	v_mfma_f32_16x16x32_bf16 v[12:15], v[80:83], v[196:199], v[12:15]
	v_mfma_f32_16x16x32_bf16 v[44:47], v[84:87], v[196:199], v[44:47]
	v_mfma_f32_16x16x32_bf16 v[208:211], v[88:91], v[196:199], v[208:211]
	v_mfma_f32_16x16x32_bf16 v[108:111], v[92:95], v[196:199], v[108:111]
	s_waitcnt lgkmcnt(3)
	v_mfma_f32_16x16x32_bf16 v[16:19], v[80:83], v[160:163], v[16:19]
	v_mfma_f32_16x16x32_bf16 v[48:51], v[84:87], v[160:163], v[48:51]
	v_mfma_f32_16x16x32_bf16 v[232:235], v[88:91], v[160:163], v[232:235]
	v_mfma_f32_16x16x32_bf16 v[112:115], v[92:95], v[160:163], v[112:115]
	s_waitcnt lgkmcnt(2)
	v_mfma_f32_16x16x32_bf16 v[20:23], v[80:83], v[176:179], v[20:23]
	v_mfma_f32_16x16x32_bf16 v[52:55], v[84:87], v[176:179], v[52:55]
	v_mfma_f32_16x16x32_bf16 v[236:239], v[88:91], v[176:179], v[236:239]
	v_mfma_f32_16x16x32_bf16 v[116:119], v[92:95], v[176:179], v[116:119]
	s_waitcnt lgkmcnt(1)
	v_mfma_f32_16x16x32_bf16 v[24:27], v[80:83], v[180:183], v[24:27]
	v_mfma_f32_16x16x32_bf16 v[56:59], v[84:87], v[180:183], v[56:59]
	v_mfma_f32_16x16x32_bf16 v[240:243], v[88:91], v[180:183], v[240:243]
	v_mfma_f32_16x16x32_bf16 v[120:123], v[92:95], v[180:183], v[120:123]
	s_waitcnt lgkmcnt(0)
	v_mfma_f32_16x16x32_bf16 v[28:31], v[80:83], v[188:191], v[28:31]
	v_mfma_f32_16x16x32_bf16 v[60:63], v[84:87], v[188:191], v[60:63]
	v_mfma_f32_16x16x32_bf16 v[248:251], v[88:91], v[188:191], v[248:251]
	v_mfma_f32_16x16x32_bf16 v[124:127], v[92:95], v[188:191], v[124:127]
	s_nop 7
	s_nop 7
	s_waitcnt vmcnt(0) lgkmcnt(0)
	s_setprio 0
	s_barrier
	v_mov_b32_e32 v150, v100
	v_mov_b32_e32 v151, v101
	v_mov_b32_e32 v156, v102
	v_mov_b32_e32 v158, v103
	v_mov_b32_e32 v159, v104
	v_mov_b32_e32 v160, v105
	v_mov_b32_e32 v183, v106
	v_mov_b32_e32 v188, v107
	v_mov_b32_e32 v189, v108
	v_mov_b32_e32 v212, v109
	v_mov_b32_e32 v213, v110
	v_mov_b32_e32 v214, v111
	v_mov_b32_e32 v216, v112
	v_mov_b32_e32 v218, v113
	v_mov_b32_e32 v220, v114
	v_mov_b32_e32 v222, v115
	v_mov_b32_e32 v224, v116
	v_mov_b32_e32 v226, v117
	v_mov_b32_e32 v228, v118
	v_mov_b32_e32 v230, v119
	v_mov_b32_e32 v231, v120
	v_mov_b32_e32 v244, v121
	v_mov_b32_e32 v245, v122
	ds_write_b32 v140, v123 offset:40960
	ds_write_b32 v140, v124 offset:41984
	ds_write_b32 v140, v125 offset:43008
	ds_write_b32 v140, v126 offset:44032
	ds_write_b32 v140, v127 offset:45056
	v_lshlrev_b32_e32 v64, 13, v135
	v_lshl_add_u32 v65, v134, 3, v138
	v_lshl_or_b32 v66, v134, 11, v64
	v_lshlrev_b32_e32 v68, 5, v138
	v_or3_b32 v161, v64, v137, v68
	v_lshl_or_b32 v162, v65, 2, v66
	v_add_u32_e32 v68, 0x60, v65
	v_add_u32_e32 v65, 0x70, v65
	v_and_b32_e32 v68, 0x7f, v68
	v_and_b32_e32 v65, 0x7f, v65
	v_lshl_or_b32 v163, v68, 2, v66
	v_lshl_or_b32 v164, v65, 2, v66
	v_add_u32_e32 v66, 8, v133
	v_and_b32_e32 v66, 0x78, v66
	v_lshlrev_b32_e32 v65, 9, v136
	v_lshlrev_b32_e32 v66, 2, v66
	v_or3_b32 v166, v64, v65, v66
	v_add_u32_e32 v66, 16, v133
	v_and_b32_e32 v66, 0x78, v66
	v_lshlrev_b32_e32 v65, 9, v132
	v_lshlrev_b32_e32 v66, 2, v66
	v_or3_b32 v168, v64, v65, v66
	v_add_u32_e32 v66, 24, v133
	v_and_b32_e32 v66, 0x78, v66
	v_lshlrev_b32_e32 v67, 5, v135
	v_lshlrev_b32_e32 v65, 9, v130
	v_lshlrev_b32_e32 v66, 2, v66
	v_or3_b32 v170, v64, v65, v66
	v_or_b32_e32 v64, 16, v67
	v_add_u32_e32 v68, 0x100, v131
	v_add_u32_e32 v69, 0x200, v131
	v_add_u32_e32 v70, 0x300, v131
	v_add_u32_e32 v71, 0x500, v131
	v_add_u32_e32 v72, 0x600, v131
	v_add_u32_e32 v73, 0x700, v131
	v_or_b32_e32 v172, v64, v134
	v_or_b32_e32 v173, v136, v64
	v_or_b32_e32 v174, v132, v64
	v_or_b32_e32 v175, v130, v64
	v_and_b32_e32 v64, 24, v153
	s_movk_i32 s90, 0x3c0
	v_lshrrev_b32_e32 v176, 4, v68
	v_lshrrev_b32_e32 v177, 4, v69
	v_lshrrev_b32_e32 v178, 4, v70
	v_lshrrev_b32_e32 v180, 4, v71
	v_lshrrev_b32_e32 v181, 4, v72
	v_lshrrev_b32_e32 v182, 4, v73
	v_or_b32_e32 v165, v134, v67
	v_or_b32_e32 v167, v136, v67
	v_or_b32_e32 v169, v132, v67
	v_or_b32_e32 v171, v130, v67
	v_and_or_b32 v64, v131, s90, v64
	v_mul_u32_u24_e32 v65, 0x110, v138
	v_lshlrev_b32_e32 v66, 4, v138
	v_mul_u32_u24_e32 v67, 0x110, v128
	v_mul_u32_u24_e32 v68, 0x110, v176
	v_mul_u32_u24_e32 v69, 0x110, v177
	v_mul_u32_u24_e32 v70, 0x110, v178
	v_mul_u32_u24_e32 v71, 0x110, v180
	v_mul_u32_u24_e32 v72, 0x110, v181
	v_mul_u32_u24_e32 v73, 0x110, v182
	v_or_b32_e32 v179, 64, v128
	v_lshlrev_b32_e32 v190, 2, v138
	v_add_u32_e32 v191, v64, v65
	v_add_u32_e32 v192, v66, v67
	v_add_u32_e32 v193, v66, v68
	v_add_u32_e32 v194, v66, v69
	v_add_u32_e32 v195, v66, v70
	v_add_u32_e32 v196, v66, v71
	v_add_u32_e32 v197, v66, v72
	v_add_u32_e32 v198, v66, v73
	v_mbcnt_hi_u32_b32 v199, -1, v155
	s_waitcnt lgkmcnt(0)
	s_mov_b64 s[6:7], -1
	s_cmp_lt_i32 s77, 5
	s_branch .Lmy_ip0_epi

.LBB0_430:
	s_lshr_b32 s90, s64, 3
	s_lshl_b32 s90, s90, 4
	s_and_b32 s91, s64, 7
	s_or_b32 s90, s90, s91
	s_lshl_b32 s91, s89, 3
	s_add_i32 s90, s90, s91
	s_lshr_b32 s91, s90, 3
	s_xor_b32 s91, s91, s90
	s_bfe_u32 s91, s91, 0x10006
	s_mul_i32 s91, s91, 0x240
	s_xor_b32 s90, s90, s91
	s_ashr_i32 s1, s90, 31
	s_lshr_b32 s1, s1, 23
	s_add_i32 s1, s90, s1
	s_ashr_i32 s1, s1, 9
	s_and_b32 s0, s90, 7
	s_lshl_b32 s1, s1, 3
	s_or_b32 s38, s1, s0
	s_mul_hi_i32 s66, s38, 0x2aaaaaab
	s_lshr_b32 s0, s66, 31
	s_add_i32 s66, s66, s0
	s_lshl_b32 s0, s66, 3
	s_bfe_u32 s1, s90, 0x30003
	s_or_b32 s0, s0, s1
	s_mul_i32 s1, s66, 6
	s_sub_i32 s65, s38, s1
	s_lshl_b32 s1, s65, 3
	s_bfe_u32 s33, s90, 0x30006
	s_or_b32 s4, s1, s33
	s_ashr_i32 s1, s0, 31
	s_ashr_i32 s5, s4, 31
	s_lshl_b64 s[54:55], s[4:5], 18
	s_lshl_b64 s[56:57], s[0:1], 18
	s_cmp_lg_u32 s89, 0
	s_cbranch_scc1 .Lmy_ip1_pass2
	s_barrier
	s_setprio 2
	s_add_u32 s84, s50, 0x3a00000
	s_addc_u32 s85, s51, 0
	s_add_u32 s84, s84, s56
	s_addc_u32 s85, s85, s57
	s_add_u32 s92, s84, 0x40000
	s_addc_u32 s93, s85, 0
	s_add_u32 s86, s50, s54
	s_addc_u32 s87, s51, s55
	s_lshl_b64 s[54:55], s[0:1], 17
	v_readfirstlane_b32 s88, v129
	v_and_b32_e32 v200, 15, v131
	v_bfe_u32 v201, v131, 4, 2
	v_and_b32_e32 v202, 63, v131
	v_lshlrev_b32_e32 v202, 4, v202
	v_lshrrev_b32_e32 v203, 6, v131
	v_lshl_add_u32 v66, v203, 16, v202
	v_add_u32_e32 v67, 0x8000, v66
	v_bfe_u32 v202, v131, 1, 3
	v_xor_b32_e32 v202, v201, v202
	v_lshlrev_b32_e32 v202, 4, v202
	v_lshl_or_b32 v75, v200, 7, v202
	v_xor_b32_e32 v212, 64, v75
	v_bfe_u32 v200, v131, 4, 3
	v_and_b32_e32 v201, 7, v131
	v_xor_b32_e32 v200, v200, v201
	v_lshlrev_b32_e32 v200, 4, v200
	v_lshrrev_b32_e32 v201, 3, v131
	v_lshl_or_b32 v68, v201, 11, v200
	v_add_u32_e32 v69, 65536, v68
	v_add_u32_e32 v71, 131072, v68
	v_add_u32_e32 v74, 196608, v68
	s_add_u32 m0, s88, 0
	v_mov_b32_e32 v32, 0
	v_mov_b32_e32 v33, 0
	global_load_lds_dwordx4 v68, s[86:87]
	v_mov_b32_e32 v34, 0
	v_mov_b32_e32 v35, 0
	v_mov_b32_e32 v36, 0
	s_add_u32 m0, s88, 4096
	v_mov_b32_e32 v37, 0
	v_mov_b32_e32 v38, 0
	global_load_lds_dwordx4 v69, s[86:87]
	v_mov_b32_e32 v39, 0
	v_mov_b32_e32 v40, 0
	v_mov_b32_e32 v41, 0
	s_add_u32 m0, s88, 8192
	v_mov_b32_e32 v42, 0
	v_mov_b32_e32 v43, 0
	global_load_lds_dwordx4 v71, s[86:87]
	v_mov_b32_e32 v44, 0
	v_mov_b32_e32 v45, 0
	v_mov_b32_e32 v46, 0
	s_add_u32 m0, s88, 12288
	v_mov_b32_e32 v47, 0
	v_mov_b32_e32 v48, 0
	global_load_lds_dwordx4 v74, s[86:87]
	s_add_u32 s86, s86, 128
	s_addc_u32 s87, s87, 0
	v_mov_b32_e32 v49, 0
	v_mov_b32_e32 v50, 0
	v_mov_b32_e32 v51, 0
	global_load_dwordx4 v[76:79], v66, s[84:85] offset:0
	v_mov_b32_e32 v52, 0
	v_mov_b32_e32 v53, 0
	v_mov_b32_e32 v54, 0
	global_load_dwordx4 v[80:83], v67, s[84:85] offset:0
	v_mov_b32_e32 v55, 0
	v_mov_b32_e32 v56, 0
	v_mov_b32_e32 v57, 0
	global_load_dwordx4 v[84:87], v66, s[92:93] offset:0
	v_mov_b32_e32 v58, 0
	v_mov_b32_e32 v59, 0
	v_mov_b32_e32 v60, 0
	global_load_dwordx4 v[88:91], v67, s[92:93] offset:0
	v_mov_b32_e32 v61, 0
	v_mov_b32_e32 v62, 0
	v_mov_b32_e32 v63, 0
	global_load_dwordx4 v[140:143], v66, s[84:85] offset:1024
	v_mov_b32_e32 v4, 0
	v_mov_b32_e32 v5, 0
	v_mov_b32_e32 v6, 0
	global_load_dwordx4 v[144:147], v67, s[84:85] offset:1024
	v_mov_b32_e32 v7, 0
	v_mov_b32_e32 v12, 0
	v_mov_b32_e32 v13, 0
	global_load_dwordx4 v[148:151], v66, s[92:93] offset:1024
	v_mov_b32_e32 v14, 0
	v_mov_b32_e32 v15, 0
	v_mov_b32_e32 v16, 0
	global_load_dwordx4 v[204:207], v67, s[92:93] offset:1024
	s_add_u32 s84, s84, 0x800
	s_addc_u32 s85, s85, 0
	s_add_u32 s92, s92, 0x800
	s_addc_u32 s93, s93, 0
	v_mov_b32_e32 v17, 0
	v_mov_b32_e32 v18, 0
	v_mov_b32_e32 v19, 0
	s_add_u32 m0, s88, 16384
	v_mov_b32_e32 v20, 0
	v_mov_b32_e32 v21, 0
	global_load_lds_dwordx4 v68, s[86:87]
	v_mov_b32_e32 v22, 0
	v_mov_b32_e32 v23, 0
	v_mov_b32_e32 v0, 0
	s_add_u32 m0, s88, 20480
	v_mov_b32_e32 v1, 0
	v_mov_b32_e32 v2, 0
	global_load_lds_dwordx4 v69, s[86:87]
	v_mov_b32_e32 v3, 0
	v_mov_b32_e32 v8, 0
	v_mov_b32_e32 v9, 0
	s_add_u32 m0, s88, 24576
	v_mov_b32_e32 v10, 0
	v_mov_b32_e32 v11, 0
	global_load_lds_dwordx4 v71, s[86:87]
	v_mov_b32_e32 v24, 0
	v_mov_b32_e32 v25, 0
	v_mov_b32_e32 v26, 0
	s_add_u32 m0, s88, 28672
	v_mov_b32_e32 v27, 0
	v_mov_b32_e32 v28, 0
	global_load_lds_dwordx4 v74, s[86:87]
	s_add_u32 s86, s86, 128
	s_addc_u32 s87, s87, 0
	v_mov_b32_e32 v29, 0
	v_mov_b32_e32 v30, 0
	v_mov_b32_e32 v31, 0
	s_add_u32 m0, s88, 32768
	v_mov_b32_e32 v188, 0
	v_mov_b32_e32 v189, 0
	global_load_lds_dwordx4 v68, s[86:87]
	v_mov_b32_e32 v190, 0
	v_mov_b32_e32 v191, 0
	v_mov_b32_e32 v208, 0
	s_add_u32 m0, s88, 36864
	v_mov_b32_e32 v209, 0
	v_mov_b32_e32 v210, 0
	global_load_lds_dwordx4 v69, s[86:87]
	v_mov_b32_e32 v211, 0
	v_mov_b32_e32 v232, 0
	v_mov_b32_e32 v233, 0
	s_add_u32 m0, s88, 40960
	v_mov_b32_e32 v234, 0
	v_mov_b32_e32 v235, 0
	global_load_lds_dwordx4 v71, s[86:87]
	v_mov_b32_e32 v236, 0
	v_mov_b32_e32 v237, 0
	v_mov_b32_e32 v238, 0
	s_add_u32 m0, s88, 45056
	v_mov_b32_e32 v239, 0
	v_mov_b32_e32 v240, 0
	global_load_lds_dwordx4 v74, s[86:87]
	s_add_u32 s86, s86, 128
	s_addc_u32 s87, s87, 0
	v_mov_b32_e32 v241, 0
	v_mov_b32_e32 v242, 0
	v_mov_b32_e32 v243, 0
	v_mov_b32_e32 v248, 0
	v_mov_b32_e32 v249, 0
	v_mov_b32_e32 v250, 0
	v_mov_b32_e32 v251, 0
	v_mov_b32_e32 v252, 0
	v_mov_b32_e32 v253, 0
	v_mov_b32_e32 v254, 0
	v_mov_b32_e32 v255, 0
	v_mov_b32_e32 v92, 0
	v_mov_b32_e32 v93, 0
	v_mov_b32_e32 v94, 0
	v_mov_b32_e32 v95, 0
	v_mov_b32_e32 v96, 0
	v_mov_b32_e32 v97, 0
	v_mov_b32_e32 v98, 0
	v_mov_b32_e32 v99, 0
	v_mov_b32_e32 v100, 0
	v_mov_b32_e32 v101, 0
	v_mov_b32_e32 v102, 0
	v_mov_b32_e32 v103, 0
	v_mov_b32_e32 v104, 0
	v_mov_b32_e32 v105, 0
	v_mov_b32_e32 v106, 0
	v_mov_b32_e32 v107, 0
	v_mov_b32_e32 v108, 0
	v_mov_b32_e32 v109, 0
	v_mov_b32_e32 v110, 0
	v_mov_b32_e32 v111, 0
	v_mov_b32_e32 v112, 0
	v_mov_b32_e32 v113, 0
	v_mov_b32_e32 v114, 0
	v_mov_b32_e32 v115, 0
	v_mov_b32_e32 v116, 0
	v_mov_b32_e32 v117, 0
	v_mov_b32_e32 v118, 0
	v_mov_b32_e32 v119, 0
	v_mov_b32_e32 v120, 0
	v_mov_b32_e32 v121, 0
	v_mov_b32_e32 v122, 0
	v_mov_b32_e32 v123, 0
	v_mov_b32_e32 v124, 0
	v_mov_b32_e32 v125, 0
	v_mov_b32_e32 v126, 0
	v_mov_b32_e32 v127, 0
	s_waitcnt vmcnt(12)
	s_barrier
	ds_read_b128 v[176:179], v75 offset:0
	ds_read_b128 v[180:183], v75 offset:2048
	ds_read_b128 v[184:187], v75 offset:4096
	ds_read_b128 v[192:195], v75 offset:6144
	ds_read_b128 v[196:199], v75 offset:8192
	global_load_dwordx4 v[160:163], v66, s[84:85] offset:0
	s_waitcnt lgkmcnt(4)
	v_mfma_f32_16x16x32_bf16 v[32:35], v[76:79], v[176:179], v[32:35]
	v_mfma_f32_16x16x32_bf16 v[4:7], v[80:83], v[176:179], v[4:7]
	v_mfma_f32_16x16x32_bf16 v[188:191], v[84:87], v[176:179], v[188:191]
	v_mfma_f32_16x16x32_bf16 v[96:99], v[88:91], v[176:179], v[96:99]
	ds_read_b128 v[200:203], v75 offset:10240
	global_load_dwordx4 v[164:167], v67, s[84:85] offset:0
	s_waitcnt lgkmcnt(4)
	v_mfma_f32_16x16x32_bf16 v[36:39], v[76:79], v[180:183], v[36:39]
	v_mfma_f32_16x16x32_bf16 v[12:15], v[80:83], v[180:183], v[12:15]
	v_mfma_f32_16x16x32_bf16 v[208:211], v[84:87], v[180:183], v[208:211]
	v_mfma_f32_16x16x32_bf16 v[100:103], v[88:91], v[180:183], v[100:103]
	ds_read_b128 v[176:179], v75 offset:12288
	global_load_dwordx4 v[168:171], v66, s[92:93] offset:0
	s_waitcnt lgkmcnt(4)
	v_mfma_f32_16x16x32_bf16 v[40:43], v[76:79], v[184:187], v[40:43]
	v_mfma_f32_16x16x32_bf16 v[16:19], v[80:83], v[184:187], v[16:19]
	v_mfma_f32_16x16x32_bf16 v[232:235], v[84:87], v[184:187], v[232:235]
	v_mfma_f32_16x16x32_bf16 v[104:107], v[88:91], v[184:187], v[104:107]
	ds_read_b128 v[180:183], v75 offset:14336
	global_load_dwordx4 v[172:175], v67, s[92:93] offset:0
	s_waitcnt lgkmcnt(4)
	v_mfma_f32_16x16x32_bf16 v[44:47], v[76:79], v[192:195], v[44:47]
	v_mfma_f32_16x16x32_bf16 v[20:23], v[80:83], v[192:195], v[20:23]
	v_mfma_f32_16x16x32_bf16 v[236:239], v[84:87], v[192:195], v[236:239]
	v_mfma_f32_16x16x32_bf16 v[108:111], v[88:91], v[192:195], v[108:111]
	ds_read_b128 v[184:187], v212 offset:0
	s_waitcnt lgkmcnt(4)
	v_mfma_f32_16x16x32_bf16 v[48:51], v[76:79], v[196:199], v[48:51]
	v_mfma_f32_16x16x32_bf16 v[0:3], v[80:83], v[196:199], v[0:3]
	v_mfma_f32_16x16x32_bf16 v[240:243], v[84:87], v[196:199], v[240:243]
	v_mfma_f32_16x16x32_bf16 v[112:115], v[88:91], v[196:199], v[112:115]
	ds_read_b128 v[192:195], v212 offset:2048
	s_waitcnt lgkmcnt(4)
	v_mfma_f32_16x16x32_bf16 v[52:55], v[76:79], v[200:203], v[52:55]
	v_mfma_f32_16x16x32_bf16 v[8:11], v[80:83], v[200:203], v[8:11]
	v_mfma_f32_16x16x32_bf16 v[248:251], v[84:87], v[200:203], v[248:251]
	v_mfma_f32_16x16x32_bf16 v[116:119], v[88:91], v[200:203], v[116:119]
	ds_read_b128 v[196:199], v212 offset:4096
	s_waitcnt lgkmcnt(4)
	v_mfma_f32_16x16x32_bf16 v[56:59], v[76:79], v[176:179], v[56:59]
	v_mfma_f32_16x16x32_bf16 v[24:27], v[80:83], v[176:179], v[24:27]
	v_mfma_f32_16x16x32_bf16 v[252:255], v[84:87], v[176:179], v[252:255]
	v_mfma_f32_16x16x32_bf16 v[120:123], v[88:91], v[176:179], v[120:123]
	ds_read_b128 v[200:203], v212 offset:6144
	s_waitcnt lgkmcnt(4)
	v_mfma_f32_16x16x32_bf16 v[60:63], v[76:79], v[180:183], v[60:63]
	v_mfma_f32_16x16x32_bf16 v[28:31], v[80:83], v[180:183], v[28:31]
	v_mfma_f32_16x16x32_bf16 v[92:95], v[84:87], v[180:183], v[92:95]
	v_mfma_f32_16x16x32_bf16 v[124:127], v[88:91], v[180:183], v[124:127]
	s_waitcnt vmcnt(8)
	s_barrier
	s_waitcnt vmcnt(12)
	ds_read_b128 v[176:179], v212 offset:8192
	global_load_dwordx4 v[76:79], v66, s[84:85] offset:1024
	s_waitcnt lgkmcnt(4)
	v_mfma_f32_16x16x32_bf16 v[32:35], v[140:143], v[184:187], v[32:35]
	v_mfma_f32_16x16x32_bf16 v[4:7], v[144:147], v[184:187], v[4:7]
	v_mfma_f32_16x16x32_bf16 v[188:191], v[148:151], v[184:187], v[188:191]
	v_mfma_f32_16x16x32_bf16 v[96:99], v[204:207], v[184:187], v[96:99]
	ds_read_b128 v[180:183], v212 offset:10240
	global_load_dwordx4 v[80:83], v67, s[84:85] offset:1024
	s_waitcnt lgkmcnt(4)
	v_mfma_f32_16x16x32_bf16 v[36:39], v[140:143], v[192:195], v[36:39]
	v_mfma_f32_16x16x32_bf16 v[12:15], v[144:147], v[192:195], v[12:15]
	v_mfma_f32_16x16x32_bf16 v[208:211], v[148:151], v[192:195], v[208:211]
	v_mfma_f32_16x16x32_bf16 v[100:103], v[204:207], v[192:195], v[100:103]
	ds_read_b128 v[184:187], v212 offset:12288
	global_load_dwordx4 v[84:87], v66, s[92:93] offset:1024
	s_waitcnt lgkmcnt(4)
	v_mfma_f32_16x16x32_bf16 v[40:43], v[140:143], v[196:199], v[40:43]
	v_mfma_f32_16x16x32_bf16 v[16:19], v[144:147], v[196:199], v[16:19]
	v_mfma_f32_16x16x32_bf16 v[232:235], v[148:151], v[196:199], v[232:235]
	v_mfma_f32_16x16x32_bf16 v[104:107], v[204:207], v[196:199], v[104:107]
	ds_read_b128 v[192:195], v212 offset:14336
	global_load_dwordx4 v[88:91], v67, s[92:93] offset:1024
	s_add_u32 s84, s84, 0x800
	s_addc_u32 s85, s85, 0
	s_add_u32 s92, s92, 0x800
	s_addc_u32 s93, s93, 0
	s_waitcnt lgkmcnt(4)
	v_mfma_f32_16x16x32_bf16 v[44:47], v[140:143], v[200:203], v[44:47]
	v_mfma_f32_16x16x32_bf16 v[20:23], v[144:147], v[200:203], v[20:23]
	v_mfma_f32_16x16x32_bf16 v[236:239], v[148:151], v[200:203], v[236:239]
	v_mfma_f32_16x16x32_bf16 v[108:111], v[204:207], v[200:203], v[108:111]
	ds_read_b128 v[196:199], v75 offset:16384
	s_add_u32 m0, s88, 49152
	s_nop 0
	global_load_lds_dwordx4 v68, s[86:87]
	s_waitcnt lgkmcnt(4)
	v_mfma_f32_16x16x32_bf16 v[48:51], v[140:143], v[176:179], v[48:51]
	v_mfma_f32_16x16x32_bf16 v[0:3], v[144:147], v[176:179], v[0:3]
	v_mfma_f32_16x16x32_bf16 v[240:243], v[148:151], v[176:179], v[240:243]
	v_mfma_f32_16x16x32_bf16 v[112:115], v[204:207], v[176:179], v[112:115]
	ds_read_b128 v[200:203], v75 offset:18432
	s_add_u32 m0, s88, 53248
	s_nop 0
	global_load_lds_dwordx4 v69, s[86:87]
	s_waitcnt lgkmcnt(4)
	v_mfma_f32_16x16x32_bf16 v[52:55], v[140:143], v[180:183], v[52:55]
	v_mfma_f32_16x16x32_bf16 v[8:11], v[144:147], v[180:183], v[8:11]
	v_mfma_f32_16x16x32_bf16 v[248:251], v[148:151], v[180:183], v[248:251]
	v_mfma_f32_16x16x32_bf16 v[116:119], v[204:207], v[180:183], v[116:119]
	ds_read_b128 v[176:179], v75 offset:20480
	s_add_u32 m0, s88, 57344
	s_nop 0
	global_load_lds_dwordx4 v71, s[86:87]
	s_waitcnt lgkmcnt(4)
	v_mfma_f32_16x16x32_bf16 v[56:59], v[140:143], v[184:187], v[56:59]
	v_mfma_f32_16x16x32_bf16 v[24:27], v[144:147], v[184:187], v[24:27]
	v_mfma_f32_16x16x32_bf16 v[252:255], v[148:151], v[184:187], v[252:255]
	v_mfma_f32_16x16x32_bf16 v[120:123], v[204:207], v[184:187], v[120:123]
	ds_read_b128 v[180:183], v75 offset:22528
	s_add_u32 m0, s88, 61440
	s_nop 0
	global_load_lds_dwordx4 v74, s[86:87]
	s_add_u32 s86, s86, 128
	s_addc_u32 s87, s87, 0
	s_waitcnt lgkmcnt(4)
	v_mfma_f32_16x16x32_bf16 v[60:63], v[140:143], v[192:195], v[60:63]
	v_mfma_f32_16x16x32_bf16 v[28:31], v[144:147], v[192:195], v[28:31]
	v_mfma_f32_16x16x32_bf16 v[92:95], v[148:151], v[192:195], v[92:95]
	v_mfma_f32_16x16x32_bf16 v[124:127], v[204:207], v[192:195], v[124:127]
	s_waitcnt vmcnt(8)
	ds_read_b128 v[184:187], v75 offset:24576
	global_load_dwordx4 v[140:143], v66, s[84:85] offset:0
	s_waitcnt lgkmcnt(4)
	v_mfma_f32_16x16x32_bf16 v[32:35], v[160:163], v[196:199], v[32:35]
	v_mfma_f32_16x16x32_bf16 v[4:7], v[164:167], v[196:199], v[4:7]
	v_mfma_f32_16x16x32_bf16 v[188:191], v[168:171], v[196:199], v[188:191]
	v_mfma_f32_16x16x32_bf16 v[96:99], v[172:175], v[196:199], v[96:99]
	ds_read_b128 v[192:195], v75 offset:26624
	global_load_dwordx4 v[144:147], v67, s[84:85] offset:0
	s_waitcnt lgkmcnt(4)
	v_mfma_f32_16x16x32_bf16 v[36:39], v[160:163], v[200:203], v[36:39]
	v_mfma_f32_16x16x32_bf16 v[12:15], v[164:167], v[200:203], v[12:15]
	v_mfma_f32_16x16x32_bf16 v[208:211], v[168:171], v[200:203], v[208:211]
	v_mfma_f32_16x16x32_bf16 v[100:103], v[172:175], v[200:203], v[100:103]
	ds_read_b128 v[196:199], v75 offset:28672
	global_load_dwordx4 v[148:151], v66, s[92:93] offset:0
	s_waitcnt lgkmcnt(4)
	v_mfma_f32_16x16x32_bf16 v[40:43], v[160:163], v[176:179], v[40:43]
	v_mfma_f32_16x16x32_bf16 v[16:19], v[164:167], v[176:179], v[16:19]
	v_mfma_f32_16x16x32_bf16 v[232:235], v[168:171], v[176:179], v[232:235]
	v_mfma_f32_16x16x32_bf16 v[104:107], v[172:175], v[176:179], v[104:107]
	ds_read_b128 v[200:203], v75 offset:30720
	global_load_dwordx4 v[204:207], v67, s[92:93] offset:0
	s_waitcnt lgkmcnt(4)
	v_mfma_f32_16x16x32_bf16 v[44:47], v[160:163], v[180:183], v[44:47]
	v_mfma_f32_16x16x32_bf16 v[20:23], v[164:167], v[180:183], v[20:23]
	v_mfma_f32_16x16x32_bf16 v[236:239], v[168:171], v[180:183], v[236:239]
	v_mfma_f32_16x16x32_bf16 v[108:111], v[172:175], v[180:183], v[108:111]
	ds_read_b128 v[176:179], v212 offset:16384
	s_waitcnt lgkmcnt(4)
	v_mfma_f32_16x16x32_bf16 v[48:51], v[160:163], v[184:187], v[48:51]
	v_mfma_f32_16x16x32_bf16 v[0:3], v[164:167], v[184:187], v[0:3]
	v_mfma_f32_16x16x32_bf16 v[240:243], v[168:171], v[184:187], v[240:243]
	v_mfma_f32_16x16x32_bf16 v[112:115], v[172:175], v[184:187], v[112:115]
	ds_read_b128 v[180:183], v212 offset:18432
	s_waitcnt lgkmcnt(4)
	v_mfma_f32_16x16x32_bf16 v[52:55], v[160:163], v[192:195], v[52:55]
	v_mfma_f32_16x16x32_bf16 v[8:11], v[164:167], v[192:195], v[8:11]
	v_mfma_f32_16x16x32_bf16 v[248:251], v[168:171], v[192:195], v[248:251]
	v_mfma_f32_16x16x32_bf16 v[116:119], v[172:175], v[192:195], v[116:119]
	ds_read_b128 v[184:187], v212 offset:20480
	s_waitcnt lgkmcnt(4)
	v_mfma_f32_16x16x32_bf16 v[56:59], v[160:163], v[196:199], v[56:59]
	v_mfma_f32_16x16x32_bf16 v[24:27], v[164:167], v[196:199], v[24:27]
	v_mfma_f32_16x16x32_bf16 v[252:255], v[168:171], v[196:199], v[252:255]
	v_mfma_f32_16x16x32_bf16 v[120:123], v[172:175], v[196:199], v[120:123]
	ds_read_b128 v[192:195], v212 offset:22528
	s_waitcnt lgkmcnt(4)
	v_mfma_f32_16x16x32_bf16 v[60:63], v[160:163], v[200:203], v[60:63]
	v_mfma_f32_16x16x32_bf16 v[28:31], v[164:167], v[200:203], v[28:31]
	v_mfma_f32_16x16x32_bf16 v[92:95], v[168:171], v[200:203], v[92:95]
	v_mfma_f32_16x16x32_bf16 v[124:127], v[172:175], v[200:203], v[124:127]
	s_waitcnt vmcnt(16)
	s_barrier
	s_waitcnt vmcnt(8)
	ds_read_b128 v[196:199], v212 offset:24576
	global_load_dwordx4 v[160:163], v66, s[84:85] offset:1024
	s_waitcnt lgkmcnt(4)
	v_mfma_f32_16x16x32_bf16 v[32:35], v[76:79], v[176:179], v[32:35]
	v_mfma_f32_16x16x32_bf16 v[4:7], v[80:83], v[176:179], v[4:7]
	v_mfma_f32_16x16x32_bf16 v[188:191], v[84:87], v[176:179], v[188:191]
	v_mfma_f32_16x16x32_bf16 v[96:99], v[88:91], v[176:179], v[96:99]
	ds_read_b128 v[200:203], v212 offset:26624
	global_load_dwordx4 v[164:167], v67, s[84:85] offset:1024
	s_waitcnt lgkmcnt(4)
	v_mfma_f32_16x16x32_bf16 v[36:39], v[76:79], v[180:183], v[36:39]
	v_mfma_f32_16x16x32_bf16 v[12:15], v[80:83], v[180:183], v[12:15]
	v_mfma_f32_16x16x32_bf16 v[208:211], v[84:87], v[180:183], v[208:211]
	v_mfma_f32_16x16x32_bf16 v[100:103], v[88:91], v[180:183], v[100:103]
	ds_read_b128 v[176:179], v212 offset:28672
	global_load_dwordx4 v[168:171], v66, s[92:93] offset:1024
	s_waitcnt lgkmcnt(4)
	v_mfma_f32_16x16x32_bf16 v[40:43], v[76:79], v[184:187], v[40:43]
	v_mfma_f32_16x16x32_bf16 v[16:19], v[80:83], v[184:187], v[16:19]
	v_mfma_f32_16x16x32_bf16 v[232:235], v[84:87], v[184:187], v[232:235]
	v_mfma_f32_16x16x32_bf16 v[104:107], v[88:91], v[184:187], v[104:107]
	ds_read_b128 v[180:183], v212 offset:30720
	global_load_dwordx4 v[172:175], v67, s[92:93] offset:1024
	s_add_u32 s84, s84, 0x800
	s_addc_u32 s85, s85, 0
	s_add_u32 s92, s92, 0x800
	s_addc_u32 s93, s93, 0
	s_waitcnt lgkmcnt(4)
	v_mfma_f32_16x16x32_bf16 v[44:47], v[76:79], v[192:195], v[44:47]
	v_mfma_f32_16x16x32_bf16 v[20:23], v[80:83], v[192:195], v[20:23]
	v_mfma_f32_16x16x32_bf16 v[236:239], v[84:87], v[192:195], v[236:239]
	v_mfma_f32_16x16x32_bf16 v[108:111], v[88:91], v[192:195], v[108:111]
	ds_read_b128 v[184:187], v75 offset:32768
	s_add_u32 m0, s88, 0
	s_nop 0
	global_load_lds_dwordx4 v68, s[86:87]
	s_waitcnt lgkmcnt(4)
	v_mfma_f32_16x16x32_bf16 v[48:51], v[76:79], v[196:199], v[48:51]
	v_mfma_f32_16x16x32_bf16 v[0:3], v[80:83], v[196:199], v[0:3]
	v_mfma_f32_16x16x32_bf16 v[240:243], v[84:87], v[196:199], v[240:243]
	v_mfma_f32_16x16x32_bf16 v[112:115], v[88:91], v[196:199], v[112:115]
	ds_read_b128 v[192:195], v75 offset:34816
	s_add_u32 m0, s88, 4096
	s_nop 0
	global_load_lds_dwordx4 v69, s[86:87]
	s_waitcnt lgkmcnt(4)
	v_mfma_f32_16x16x32_bf16 v[52:55], v[76:79], v[200:203], v[52:55]
	v_mfma_f32_16x16x32_bf16 v[8:11], v[80:83], v[200:203], v[8:11]
	v_mfma_f32_16x16x32_bf16 v[248:251], v[84:87], v[200:203], v[248:251]
	v_mfma_f32_16x16x32_bf16 v[116:119], v[88:91], v[200:203], v[116:119]
	ds_read_b128 v[196:199], v75 offset:36864
	s_add_u32 m0, s88, 8192
	s_nop 0
	global_load_lds_dwordx4 v71, s[86:87]
	s_waitcnt lgkmcnt(4)
	v_mfma_f32_16x16x32_bf16 v[56:59], v[76:79], v[176:179], v[56:59]
	v_mfma_f32_16x16x32_bf16 v[24:27], v[80:83], v[176:179], v[24:27]
	v_mfma_f32_16x16x32_bf16 v[252:255], v[84:87], v[176:179], v[252:255]
	v_mfma_f32_16x16x32_bf16 v[120:123], v[88:91], v[176:179], v[120:123]
	ds_read_b128 v[200:203], v75 offset:38912
	s_add_u32 m0, s88, 12288
	s_nop 0
	global_load_lds_dwordx4 v74, s[86:87]
	s_add_u32 s86, s86, 128
	s_addc_u32 s87, s87, 0
	s_waitcnt lgkmcnt(4)
	v_mfma_f32_16x16x32_bf16 v[60:63], v[76:79], v[180:183], v[60:63]
	v_mfma_f32_16x16x32_bf16 v[28:31], v[80:83], v[180:183], v[28:31]
	v_mfma_f32_16x16x32_bf16 v[92:95], v[84:87], v[180:183], v[92:95]
	v_mfma_f32_16x16x32_bf16 v[124:127], v[88:91], v[180:183], v[124:127]
	s_waitcnt vmcnt(8)
	ds_read_b128 v[176:179], v75 offset:40960
	global_load_dwordx4 v[76:79], v66, s[84:85] offset:0
	s_waitcnt lgkmcnt(4)
	v_mfma_f32_16x16x32_bf16 v[32:35], v[140:143], v[184:187], v[32:35]
	v_mfma_f32_16x16x32_bf16 v[4:7], v[144:147], v[184:187], v[4:7]
	v_mfma_f32_16x16x32_bf16 v[188:191], v[148:151], v[184:187], v[188:191]
	v_mfma_f32_16x16x32_bf16 v[96:99], v[204:207], v[184:187], v[96:99]
	ds_read_b128 v[180:183], v75 offset:43008
	global_load_dwordx4 v[80:83], v67, s[84:85] offset:0
	s_waitcnt lgkmcnt(4)
	v_mfma_f32_16x16x32_bf16 v[36:39], v[140:143], v[192:195], v[36:39]
	v_mfma_f32_16x16x32_bf16 v[12:15], v[144:147], v[192:195], v[12:15]
	v_mfma_f32_16x16x32_bf16 v[208:211], v[148:151], v[192:195], v[208:211]
	v_mfma_f32_16x16x32_bf16 v[100:103], v[204:207], v[192:195], v[100:103]
	ds_read_b128 v[184:187], v75 offset:45056
	global_load_dwordx4 v[84:87], v66, s[92:93] offset:0
	s_waitcnt lgkmcnt(4)
	v_mfma_f32_16x16x32_bf16 v[40:43], v[140:143], v[196:199], v[40:43]
	v_mfma_f32_16x16x32_bf16 v[16:19], v[144:147], v[196:199], v[16:19]
	v_mfma_f32_16x16x32_bf16 v[232:235], v[148:151], v[196:199], v[232:235]
	v_mfma_f32_16x16x32_bf16 v[104:107], v[204:207], v[196:199], v[104:107]
	ds_read_b128 v[192:195], v75 offset:47104
	global_load_dwordx4 v[88:91], v67, s[92:93] offset:0
	s_waitcnt lgkmcnt(4)
	v_mfma_f32_16x16x32_bf16 v[44:47], v[140:143], v[200:203], v[44:47]
	v_mfma_f32_16x16x32_bf16 v[20:23], v[144:147], v[200:203], v[20:23]
	v_mfma_f32_16x16x32_bf16 v[236:239], v[148:151], v[200:203], v[236:239]
	v_mfma_f32_16x16x32_bf16 v[108:111], v[204:207], v[200:203], v[108:111]
	ds_read_b128 v[196:199], v212 offset:32768
	s_waitcnt lgkmcnt(4)
	v_mfma_f32_16x16x32_bf16 v[48:51], v[140:143], v[176:179], v[48:51]
	v_mfma_f32_16x16x32_bf16 v[0:3], v[144:147], v[176:179], v[0:3]
	v_mfma_f32_16x16x32_bf16 v[240:243], v[148:151], v[176:179], v[240:243]
	v_mfma_f32_16x16x32_bf16 v[112:115], v[204:207], v[176:179], v[112:115]
	ds_read_b128 v[200:203], v212 offset:34816
	s_waitcnt lgkmcnt(4)
	v_mfma_f32_16x16x32_bf16 v[52:55], v[140:143], v[180:183], v[52:55]
	v_mfma_f32_16x16x32_bf16 v[8:11], v[144:147], v[180:183], v[8:11]
	v_mfma_f32_16x16x32_bf16 v[248:251], v[148:151], v[180:183], v[248:251]
	v_mfma_f32_16x16x32_bf16 v[116:119], v[204:207], v[180:183], v[116:119]
	ds_read_b128 v[176:179], v212 offset:36864
	s_waitcnt lgkmcnt(4)
	v_mfma_f32_16x16x32_bf16 v[56:59], v[140:143], v[184:187], v[56:59]
	v_mfma_f32_16x16x32_bf16 v[24:27], v[144:147], v[184:187], v[24:27]
	v_mfma_f32_16x16x32_bf16 v[252:255], v[148:151], v[184:187], v[252:255]
	v_mfma_f32_16x16x32_bf16 v[120:123], v[204:207], v[184:187], v[120:123]
	ds_read_b128 v[180:183], v212 offset:38912
	s_waitcnt lgkmcnt(4)
	v_mfma_f32_16x16x32_bf16 v[60:63], v[140:143], v[192:195], v[60:63]
	v_mfma_f32_16x16x32_bf16 v[28:31], v[144:147], v[192:195], v[28:31]
	v_mfma_f32_16x16x32_bf16 v[92:95], v[148:151], v[192:195], v[92:95]
	v_mfma_f32_16x16x32_bf16 v[124:127], v[204:207], v[192:195], v[124:127]
	s_waitcnt vmcnt(16)
	s_barrier
	s_waitcnt vmcnt(8)
	ds_read_b128 v[184:187], v212 offset:40960
	global_load_dwordx4 v[140:143], v66, s[84:85] offset:1024
	s_waitcnt lgkmcnt(4)
	v_mfma_f32_16x16x32_bf16 v[32:35], v[160:163], v[196:199], v[32:35]
	v_mfma_f32_16x16x32_bf16 v[4:7], v[164:167], v[196:199], v[4:7]
	v_mfma_f32_16x16x32_bf16 v[188:191], v[168:171], v[196:199], v[188:191]
	v_mfma_f32_16x16x32_bf16 v[96:99], v[172:175], v[196:199], v[96:99]
	ds_read_b128 v[192:195], v212 offset:43008
	global_load_dwordx4 v[144:147], v67, s[84:85] offset:1024
	s_waitcnt lgkmcnt(4)
	v_mfma_f32_16x16x32_bf16 v[36:39], v[160:163], v[200:203], v[36:39]
	v_mfma_f32_16x16x32_bf16 v[12:15], v[164:167], v[200:203], v[12:15]
	v_mfma_f32_16x16x32_bf16 v[208:211], v[168:171], v[200:203], v[208:211]
	v_mfma_f32_16x16x32_bf16 v[100:103], v[172:175], v[200:203], v[100:103]
	ds_read_b128 v[196:199], v212 offset:45056
	global_load_dwordx4 v[148:151], v66, s[92:93] offset:1024
	s_waitcnt lgkmcnt(4)
	v_mfma_f32_16x16x32_bf16 v[40:43], v[160:163], v[176:179], v[40:43]
	v_mfma_f32_16x16x32_bf16 v[16:19], v[164:167], v[176:179], v[16:19]
	v_mfma_f32_16x16x32_bf16 v[232:235], v[168:171], v[176:179], v[232:235]
	v_mfma_f32_16x16x32_bf16 v[104:107], v[172:175], v[176:179], v[104:107]
	ds_read_b128 v[200:203], v212 offset:47104
	global_load_dwordx4 v[204:207], v67, s[92:93] offset:1024
	s_add_u32 s84, s84, 0x800
	s_addc_u32 s85, s85, 0
	s_add_u32 s92, s92, 0x800
	s_addc_u32 s93, s93, 0
	s_waitcnt lgkmcnt(4)
	v_mfma_f32_16x16x32_bf16 v[44:47], v[160:163], v[180:183], v[44:47]
	v_mfma_f32_16x16x32_bf16 v[20:23], v[164:167], v[180:183], v[20:23]
	v_mfma_f32_16x16x32_bf16 v[236:239], v[168:171], v[180:183], v[236:239]
	v_mfma_f32_16x16x32_bf16 v[108:111], v[172:175], v[180:183], v[108:111]
	ds_read_b128 v[176:179], v75 offset:49152
	s_add_u32 m0, s88, 16384
	s_nop 0
	global_load_lds_dwordx4 v68, s[86:87]
	s_waitcnt lgkmcnt(4)
	v_mfma_f32_16x16x32_bf16 v[48:51], v[160:163], v[184:187], v[48:51]
	v_mfma_f32_16x16x32_bf16 v[0:3], v[164:167], v[184:187], v[0:3]
	v_mfma_f32_16x16x32_bf16 v[240:243], v[168:171], v[184:187], v[240:243]
	v_mfma_f32_16x16x32_bf16 v[112:115], v[172:175], v[184:187], v[112:115]
	ds_read_b128 v[180:183], v75 offset:51200
	s_add_u32 m0, s88, 20480
	s_nop 0
	global_load_lds_dwordx4 v69, s[86:87]
	s_waitcnt lgkmcnt(4)
	v_mfma_f32_16x16x32_bf16 v[52:55], v[160:163], v[192:195], v[52:55]
	v_mfma_f32_16x16x32_bf16 v[8:11], v[164:167], v[192:195], v[8:11]
	v_mfma_f32_16x16x32_bf16 v[248:251], v[168:171], v[192:195], v[248:251]
	v_mfma_f32_16x16x32_bf16 v[116:119], v[172:175], v[192:195], v[116:119]
	ds_read_b128 v[184:187], v75 offset:53248
	s_add_u32 m0, s88, 24576
	s_nop 0
	global_load_lds_dwordx4 v71, s[86:87]
	s_waitcnt lgkmcnt(4)
	v_mfma_f32_16x16x32_bf16 v[56:59], v[160:163], v[196:199], v[56:59]
	v_mfma_f32_16x16x32_bf16 v[24:27], v[164:167], v[196:199], v[24:27]
	v_mfma_f32_16x16x32_bf16 v[252:255], v[168:171], v[196:199], v[252:255]
	v_mfma_f32_16x16x32_bf16 v[120:123], v[172:175], v[196:199], v[120:123]
	ds_read_b128 v[192:195], v75 offset:55296
	s_add_u32 m0, s88, 28672
	s_nop 0
	global_load_lds_dwordx4 v74, s[86:87]
	s_add_u32 s86, s86, 128
	s_addc_u32 s87, s87, 0
	s_waitcnt lgkmcnt(4)
	v_mfma_f32_16x16x32_bf16 v[60:63], v[160:163], v[200:203], v[60:63]
	v_mfma_f32_16x16x32_bf16 v[28:31], v[164:167], v[200:203], v[28:31]
	v_mfma_f32_16x16x32_bf16 v[92:95], v[168:171], v[200:203], v[92:95]
	v_mfma_f32_16x16x32_bf16 v[124:127], v[172:175], v[200:203], v[124:127]
	s_waitcnt vmcnt(8)
	ds_read_b128 v[196:199], v75 offset:57344
	global_load_dwordx4 v[160:163], v66, s[84:85] offset:0
	s_waitcnt lgkmcnt(4)
	v_mfma_f32_16x16x32_bf16 v[32:35], v[76:79], v[176:179], v[32:35]
	v_mfma_f32_16x16x32_bf16 v[4:7], v[80:83], v[176:179], v[4:7]
	v_mfma_f32_16x16x32_bf16 v[188:191], v[84:87], v[176:179], v[188:191]
	v_mfma_f32_16x16x32_bf16 v[96:99], v[88:91], v[176:179], v[96:99]
	ds_read_b128 v[200:203], v75 offset:59392
	global_load_dwordx4 v[164:167], v67, s[84:85] offset:0
	s_waitcnt lgkmcnt(4)
	v_mfma_f32_16x16x32_bf16 v[36:39], v[76:79], v[180:183], v[36:39]
	v_mfma_f32_16x16x32_bf16 v[12:15], v[80:83], v[180:183], v[12:15]
	v_mfma_f32_16x16x32_bf16 v[208:211], v[84:87], v[180:183], v[208:211]
	v_mfma_f32_16x16x32_bf16 v[100:103], v[88:91], v[180:183], v[100:103]
	ds_read_b128 v[176:179], v75 offset:61440
	global_load_dwordx4 v[168:171], v66, s[92:93] offset:0
	s_waitcnt lgkmcnt(4)
	v_mfma_f32_16x16x32_bf16 v[40:43], v[76:79], v[184:187], v[40:43]
	v_mfma_f32_16x16x32_bf16 v[16:19], v[80:83], v[184:187], v[16:19]
	v_mfma_f32_16x16x32_bf16 v[232:235], v[84:87], v[184:187], v[232:235]
	v_mfma_f32_16x16x32_bf16 v[104:107], v[88:91], v[184:187], v[104:107]
	ds_read_b128 v[180:183], v75 offset:63488
	global_load_dwordx4 v[172:175], v67, s[92:93] offset:0
	s_waitcnt lgkmcnt(4)
	v_mfma_f32_16x16x32_bf16 v[44:47], v[76:79], v[192:195], v[44:47]
	v_mfma_f32_16x16x32_bf16 v[20:23], v[80:83], v[192:195], v[20:23]
	v_mfma_f32_16x16x32_bf16 v[236:239], v[84:87], v[192:195], v[236:239]
	v_mfma_f32_16x16x32_bf16 v[108:111], v[88:91], v[192:195], v[108:111]
	ds_read_b128 v[184:187], v212 offset:49152
	s_waitcnt lgkmcnt(4)
	v_mfma_f32_16x16x32_bf16 v[48:51], v[76:79], v[196:199], v[48:51]
	v_mfma_f32_16x16x32_bf16 v[0:3], v[80:83], v[196:199], v[0:3]
	v_mfma_f32_16x16x32_bf16 v[240:243], v[84:87], v[196:199], v[240:243]
	v_mfma_f32_16x16x32_bf16 v[112:115], v[88:91], v[196:199], v[112:115]
	ds_read_b128 v[192:195], v212 offset:51200
	s_waitcnt lgkmcnt(4)
	v_mfma_f32_16x16x32_bf16 v[52:55], v[76:79], v[200:203], v[52:55]
	v_mfma_f32_16x16x32_bf16 v[8:11], v[80:83], v[200:203], v[8:11]
	v_mfma_f32_16x16x32_bf16 v[248:251], v[84:87], v[200:203], v[248:251]
	v_mfma_f32_16x16x32_bf16 v[116:119], v[88:91], v[200:203], v[116:119]
	ds_read_b128 v[196:199], v212 offset:53248
	s_waitcnt lgkmcnt(4)
	v_mfma_f32_16x16x32_bf16 v[56:59], v[76:79], v[176:179], v[56:59]
	v_mfma_f32_16x16x32_bf16 v[24:27], v[80:83], v[176:179], v[24:27]
	v_mfma_f32_16x16x32_bf16 v[252:255], v[84:87], v[176:179], v[252:255]
	v_mfma_f32_16x16x32_bf16 v[120:123], v[88:91], v[176:179], v[120:123]
	ds_read_b128 v[200:203], v212 offset:55296
	s_waitcnt lgkmcnt(4)
	v_mfma_f32_16x16x32_bf16 v[60:63], v[76:79], v[180:183], v[60:63]
	v_mfma_f32_16x16x32_bf16 v[28:31], v[80:83], v[180:183], v[28:31]
	v_mfma_f32_16x16x32_bf16 v[92:95], v[84:87], v[180:183], v[92:95]
	v_mfma_f32_16x16x32_bf16 v[124:127], v[88:91], v[180:183], v[124:127]
	s_waitcnt vmcnt(16)
	s_barrier
	s_waitcnt vmcnt(8)
	ds_read_b128 v[176:179], v212 offset:57344
	global_load_dwordx4 v[76:79], v66, s[84:85] offset:1024
	s_waitcnt lgkmcnt(4)
	v_mfma_f32_16x16x32_bf16 v[32:35], v[140:143], v[184:187], v[32:35]
	v_mfma_f32_16x16x32_bf16 v[4:7], v[144:147], v[184:187], v[4:7]
	v_mfma_f32_16x16x32_bf16 v[188:191], v[148:151], v[184:187], v[188:191]
	v_mfma_f32_16x16x32_bf16 v[96:99], v[204:207], v[184:187], v[96:99]
	ds_read_b128 v[180:183], v212 offset:59392
	global_load_dwordx4 v[80:83], v67, s[84:85] offset:1024
	s_waitcnt lgkmcnt(4)
	v_mfma_f32_16x16x32_bf16 v[36:39], v[140:143], v[192:195], v[36:39]
	v_mfma_f32_16x16x32_bf16 v[12:15], v[144:147], v[192:195], v[12:15]
	v_mfma_f32_16x16x32_bf16 v[208:211], v[148:151], v[192:195], v[208:211]
	v_mfma_f32_16x16x32_bf16 v[100:103], v[204:207], v[192:195], v[100:103]
	ds_read_b128 v[184:187], v212 offset:61440
	global_load_dwordx4 v[84:87], v66, s[92:93] offset:1024
	s_waitcnt lgkmcnt(4)
	v_mfma_f32_16x16x32_bf16 v[40:43], v[140:143], v[196:199], v[40:43]
	v_mfma_f32_16x16x32_bf16 v[16:19], v[144:147], v[196:199], v[16:19]
	v_mfma_f32_16x16x32_bf16 v[232:235], v[148:151], v[196:199], v[232:235]
	v_mfma_f32_16x16x32_bf16 v[104:107], v[204:207], v[196:199], v[104:107]
	ds_read_b128 v[192:195], v212 offset:63488
	global_load_dwordx4 v[88:91], v67, s[92:93] offset:1024
	s_add_u32 s84, s84, 0x800
	s_addc_u32 s85, s85, 0
	s_add_u32 s92, s92, 0x800
	s_addc_u32 s93, s93, 0
	s_waitcnt lgkmcnt(4)
	v_mfma_f32_16x16x32_bf16 v[44:47], v[140:143], v[200:203], v[44:47]
	v_mfma_f32_16x16x32_bf16 v[20:23], v[144:147], v[200:203], v[20:23]
	v_mfma_f32_16x16x32_bf16 v[236:239], v[148:151], v[200:203], v[236:239]
	v_mfma_f32_16x16x32_bf16 v[108:111], v[204:207], v[200:203], v[108:111]
	ds_read_b128 v[196:199], v75 offset:0
	s_add_u32 m0, s88, 32768
	s_nop 0
	global_load_lds_dwordx4 v68, s[86:87]
	s_waitcnt lgkmcnt(4)
	v_mfma_f32_16x16x32_bf16 v[48:51], v[140:143], v[176:179], v[48:51]
	v_mfma_f32_16x16x32_bf16 v[0:3], v[144:147], v[176:179], v[0:3]
	v_mfma_f32_16x16x32_bf16 v[240:243], v[148:151], v[176:179], v[240:243]
	v_mfma_f32_16x16x32_bf16 v[112:115], v[204:207], v[176:179], v[112:115]
	ds_read_b128 v[200:203], v75 offset:2048
	s_add_u32 m0, s88, 36864
	s_nop 0
	global_load_lds_dwordx4 v69, s[86:87]
	s_waitcnt lgkmcnt(4)
	v_mfma_f32_16x16x32_bf16 v[52:55], v[140:143], v[180:183], v[52:55]
	v_mfma_f32_16x16x32_bf16 v[8:11], v[144:147], v[180:183], v[8:11]
	v_mfma_f32_16x16x32_bf16 v[248:251], v[148:151], v[180:183], v[248:251]
	v_mfma_f32_16x16x32_bf16 v[116:119], v[204:207], v[180:183], v[116:119]
	ds_read_b128 v[176:179], v75 offset:4096
	s_add_u32 m0, s88, 40960
	s_nop 0
	global_load_lds_dwordx4 v71, s[86:87]
	s_waitcnt lgkmcnt(4)
	v_mfma_f32_16x16x32_bf16 v[56:59], v[140:143], v[184:187], v[56:59]
	v_mfma_f32_16x16x32_bf16 v[24:27], v[144:147], v[184:187], v[24:27]
	v_mfma_f32_16x16x32_bf16 v[252:255], v[148:151], v[184:187], v[252:255]
	v_mfma_f32_16x16x32_bf16 v[120:123], v[204:207], v[184:187], v[120:123]
	ds_read_b128 v[180:183], v75 offset:6144
	s_add_u32 m0, s88, 45056
	s_nop 0
	global_load_lds_dwordx4 v74, s[86:87]
	s_add_u32 s86, s86, 128
	s_addc_u32 s87, s87, 0
	s_waitcnt lgkmcnt(4)
	v_mfma_f32_16x16x32_bf16 v[60:63], v[140:143], v[192:195], v[60:63]
	v_mfma_f32_16x16x32_bf16 v[28:31], v[144:147], v[192:195], v[28:31]
	v_mfma_f32_16x16x32_bf16 v[92:95], v[148:151], v[192:195], v[92:95]
	v_mfma_f32_16x16x32_bf16 v[124:127], v[204:207], v[192:195], v[124:127]
	s_waitcnt vmcnt(8)
	ds_read_b128 v[184:187], v75 offset:8192
	global_load_dwordx4 v[140:143], v66, s[84:85] offset:0
	s_waitcnt lgkmcnt(4)
	v_mfma_f32_16x16x32_bf16 v[32:35], v[160:163], v[196:199], v[32:35]
	v_mfma_f32_16x16x32_bf16 v[4:7], v[164:167], v[196:199], v[4:7]
	v_mfma_f32_16x16x32_bf16 v[188:191], v[168:171], v[196:199], v[188:191]
	v_mfma_f32_16x16x32_bf16 v[96:99], v[172:175], v[196:199], v[96:99]
	ds_read_b128 v[192:195], v75 offset:10240
	global_load_dwordx4 v[144:147], v67, s[84:85] offset:0
	s_waitcnt lgkmcnt(4)
	v_mfma_f32_16x16x32_bf16 v[36:39], v[160:163], v[200:203], v[36:39]
	v_mfma_f32_16x16x32_bf16 v[12:15], v[164:167], v[200:203], v[12:15]
	v_mfma_f32_16x16x32_bf16 v[208:211], v[168:171], v[200:203], v[208:211]
	v_mfma_f32_16x16x32_bf16 v[100:103], v[172:175], v[200:203], v[100:103]
	ds_read_b128 v[196:199], v75 offset:12288
	global_load_dwordx4 v[148:151], v66, s[92:93] offset:0
	s_waitcnt lgkmcnt(4)
	v_mfma_f32_16x16x32_bf16 v[40:43], v[160:163], v[176:179], v[40:43]
	v_mfma_f32_16x16x32_bf16 v[16:19], v[164:167], v[176:179], v[16:19]
	v_mfma_f32_16x16x32_bf16 v[232:235], v[168:171], v[176:179], v[232:235]
	v_mfma_f32_16x16x32_bf16 v[104:107], v[172:175], v[176:179], v[104:107]
	ds_read_b128 v[200:203], v75 offset:14336
	global_load_dwordx4 v[204:207], v67, s[92:93] offset:0
	s_waitcnt lgkmcnt(4)
	v_mfma_f32_16x16x32_bf16 v[44:47], v[160:163], v[180:183], v[44:47]
	v_mfma_f32_16x16x32_bf16 v[20:23], v[164:167], v[180:183], v[20:23]
	v_mfma_f32_16x16x32_bf16 v[236:239], v[168:171], v[180:183], v[236:239]
	v_mfma_f32_16x16x32_bf16 v[108:111], v[172:175], v[180:183], v[108:111]
	ds_read_b128 v[176:179], v212 offset:0
	s_waitcnt lgkmcnt(4)
	v_mfma_f32_16x16x32_bf16 v[48:51], v[160:163], v[184:187], v[48:51]
	v_mfma_f32_16x16x32_bf16 v[0:3], v[164:167], v[184:187], v[0:3]
	v_mfma_f32_16x16x32_bf16 v[240:243], v[168:171], v[184:187], v[240:243]
	v_mfma_f32_16x16x32_bf16 v[112:115], v[172:175], v[184:187], v[112:115]
	ds_read_b128 v[180:183], v212 offset:2048
	s_waitcnt lgkmcnt(4)
	v_mfma_f32_16x16x32_bf16 v[52:55], v[160:163], v[192:195], v[52:55]
	v_mfma_f32_16x16x32_bf16 v[8:11], v[164:167], v[192:195], v[8:11]
	v_mfma_f32_16x16x32_bf16 v[248:251], v[168:171], v[192:195], v[248:251]
	v_mfma_f32_16x16x32_bf16 v[116:119], v[172:175], v[192:195], v[116:119]
	ds_read_b128 v[184:187], v212 offset:4096
	s_waitcnt lgkmcnt(4)
	v_mfma_f32_16x16x32_bf16 v[56:59], v[160:163], v[196:199], v[56:59]
	v_mfma_f32_16x16x32_bf16 v[24:27], v[164:167], v[196:199], v[24:27]
	v_mfma_f32_16x16x32_bf16 v[252:255], v[168:171], v[196:199], v[252:255]
	v_mfma_f32_16x16x32_bf16 v[120:123], v[172:175], v[196:199], v[120:123]
	ds_read_b128 v[192:195], v212 offset:6144
	s_waitcnt lgkmcnt(4)
	v_mfma_f32_16x16x32_bf16 v[60:63], v[160:163], v[200:203], v[60:63]
	v_mfma_f32_16x16x32_bf16 v[28:31], v[164:167], v[200:203], v[28:31]
	v_mfma_f32_16x16x32_bf16 v[92:95], v[168:171], v[200:203], v[92:95]
	v_mfma_f32_16x16x32_bf16 v[124:127], v[172:175], v[200:203], v[124:127]
	s_waitcnt vmcnt(16)
	s_barrier
	s_waitcnt vmcnt(8)
	ds_read_b128 v[196:199], v212 offset:8192
	global_load_dwordx4 v[160:163], v66, s[84:85] offset:1024
	s_waitcnt lgkmcnt(4)
	v_mfma_f32_16x16x32_bf16 v[32:35], v[76:79], v[176:179], v[32:35]
	v_mfma_f32_16x16x32_bf16 v[4:7], v[80:83], v[176:179], v[4:7]
	v_mfma_f32_16x16x32_bf16 v[188:191], v[84:87], v[176:179], v[188:191]
	v_mfma_f32_16x16x32_bf16 v[96:99], v[88:91], v[176:179], v[96:99]
	ds_read_b128 v[200:203], v212 offset:10240
	global_load_dwordx4 v[164:167], v67, s[84:85] offset:1024
	s_waitcnt lgkmcnt(4)
	v_mfma_f32_16x16x32_bf16 v[36:39], v[76:79], v[180:183], v[36:39]
	v_mfma_f32_16x16x32_bf16 v[12:15], v[80:83], v[180:183], v[12:15]
	v_mfma_f32_16x16x32_bf16 v[208:211], v[84:87], v[180:183], v[208:211]
	v_mfma_f32_16x16x32_bf16 v[100:103], v[88:91], v[180:183], v[100:103]
	ds_read_b128 v[176:179], v212 offset:12288
	global_load_dwordx4 v[168:171], v66, s[92:93] offset:1024
	s_waitcnt lgkmcnt(4)
	v_mfma_f32_16x16x32_bf16 v[40:43], v[76:79], v[184:187], v[40:43]
	v_mfma_f32_16x16x32_bf16 v[16:19], v[80:83], v[184:187], v[16:19]
	v_mfma_f32_16x16x32_bf16 v[232:235], v[84:87], v[184:187], v[232:235]
	v_mfma_f32_16x16x32_bf16 v[104:107], v[88:91], v[184:187], v[104:107]
	ds_read_b128 v[180:183], v212 offset:14336
	global_load_dwordx4 v[172:175], v67, s[92:93] offset:1024
	s_add_u32 s84, s84, 0x800
	s_addc_u32 s85, s85, 0
	s_add_u32 s92, s92, 0x800
	s_addc_u32 s93, s93, 0
	s_waitcnt lgkmcnt(4)
	v_mfma_f32_16x16x32_bf16 v[44:47], v[76:79], v[192:195], v[44:47]
	v_mfma_f32_16x16x32_bf16 v[20:23], v[80:83], v[192:195], v[20:23]
	v_mfma_f32_16x16x32_bf16 v[236:239], v[84:87], v[192:195], v[236:239]
	v_mfma_f32_16x16x32_bf16 v[108:111], v[88:91], v[192:195], v[108:111]
	ds_read_b128 v[184:187], v75 offset:16384
	s_add_u32 m0, s88, 49152
	s_nop 0
	global_load_lds_dwordx4 v68, s[86:87]
	s_waitcnt lgkmcnt(4)
	v_mfma_f32_16x16x32_bf16 v[48:51], v[76:79], v[196:199], v[48:51]
	v_mfma_f32_16x16x32_bf16 v[0:3], v[80:83], v[196:199], v[0:3]
	v_mfma_f32_16x16x32_bf16 v[240:243], v[84:87], v[196:199], v[240:243]
	v_mfma_f32_16x16x32_bf16 v[112:115], v[88:91], v[196:199], v[112:115]
	ds_read_b128 v[192:195], v75 offset:18432
	s_add_u32 m0, s88, 53248
	s_nop 0
	global_load_lds_dwordx4 v69, s[86:87]
	s_waitcnt lgkmcnt(4)
	v_mfma_f32_16x16x32_bf16 v[52:55], v[76:79], v[200:203], v[52:55]
	v_mfma_f32_16x16x32_bf16 v[8:11], v[80:83], v[200:203], v[8:11]
	v_mfma_f32_16x16x32_bf16 v[248:251], v[84:87], v[200:203], v[248:251]
	v_mfma_f32_16x16x32_bf16 v[116:119], v[88:91], v[200:203], v[116:119]
	ds_read_b128 v[196:199], v75 offset:20480
	s_add_u32 m0, s88, 57344
	s_nop 0
	global_load_lds_dwordx4 v71, s[86:87]
	s_waitcnt lgkmcnt(4)
	v_mfma_f32_16x16x32_bf16 v[56:59], v[76:79], v[176:179], v[56:59]
	v_mfma_f32_16x16x32_bf16 v[24:27], v[80:83], v[176:179], v[24:27]
	v_mfma_f32_16x16x32_bf16 v[252:255], v[84:87], v[176:179], v[252:255]
	v_mfma_f32_16x16x32_bf16 v[120:123], v[88:91], v[176:179], v[120:123]
	ds_read_b128 v[200:203], v75 offset:22528
	s_add_u32 m0, s88, 61440
	s_nop 0
	global_load_lds_dwordx4 v74, s[86:87]
	s_add_u32 s86, s86, 128
	s_addc_u32 s87, s87, 0
	s_waitcnt lgkmcnt(4)
	v_mfma_f32_16x16x32_bf16 v[60:63], v[76:79], v[180:183], v[60:63]
	v_mfma_f32_16x16x32_bf16 v[28:31], v[80:83], v[180:183], v[28:31]
	v_mfma_f32_16x16x32_bf16 v[92:95], v[84:87], v[180:183], v[92:95]
	v_mfma_f32_16x16x32_bf16 v[124:127], v[88:91], v[180:183], v[124:127]
	s_waitcnt vmcnt(8)
	ds_read_b128 v[176:179], v75 offset:24576
	global_load_dwordx4 v[76:79], v66, s[84:85] offset:0
	s_waitcnt lgkmcnt(4)
	v_mfma_f32_16x16x32_bf16 v[32:35], v[140:143], v[184:187], v[32:35]
	v_mfma_f32_16x16x32_bf16 v[4:7], v[144:147], v[184:187], v[4:7]
	v_mfma_f32_16x16x32_bf16 v[188:191], v[148:151], v[184:187], v[188:191]
	v_mfma_f32_16x16x32_bf16 v[96:99], v[204:207], v[184:187], v[96:99]
	ds_read_b128 v[180:183], v75 offset:26624
	global_load_dwordx4 v[80:83], v67, s[84:85] offset:0
	s_waitcnt lgkmcnt(4)
	v_mfma_f32_16x16x32_bf16 v[36:39], v[140:143], v[192:195], v[36:39]
	v_mfma_f32_16x16x32_bf16 v[12:15], v[144:147], v[192:195], v[12:15]
	v_mfma_f32_16x16x32_bf16 v[208:211], v[148:151], v[192:195], v[208:211]
	v_mfma_f32_16x16x32_bf16 v[100:103], v[204:207], v[192:195], v[100:103]
	ds_read_b128 v[184:187], v75 offset:28672
	global_load_dwordx4 v[84:87], v66, s[92:93] offset:0
	s_waitcnt lgkmcnt(4)
	v_mfma_f32_16x16x32_bf16 v[40:43], v[140:143], v[196:199], v[40:43]
	v_mfma_f32_16x16x32_bf16 v[16:19], v[144:147], v[196:199], v[16:19]
	v_mfma_f32_16x16x32_bf16 v[232:235], v[148:151], v[196:199], v[232:235]
	v_mfma_f32_16x16x32_bf16 v[104:107], v[204:207], v[196:199], v[104:107]
	ds_read_b128 v[192:195], v75 offset:30720
	global_load_dwordx4 v[88:91], v67, s[92:93] offset:0
	s_waitcnt lgkmcnt(4)
	v_mfma_f32_16x16x32_bf16 v[44:47], v[140:143], v[200:203], v[44:47]
	v_mfma_f32_16x16x32_bf16 v[20:23], v[144:147], v[200:203], v[20:23]
	v_mfma_f32_16x16x32_bf16 v[236:239], v[148:151], v[200:203], v[236:239]
	v_mfma_f32_16x16x32_bf16 v[108:111], v[204:207], v[200:203], v[108:111]
	ds_read_b128 v[196:199], v212 offset:16384
	s_waitcnt lgkmcnt(4)
	v_mfma_f32_16x16x32_bf16 v[48:51], v[140:143], v[176:179], v[48:51]
	v_mfma_f32_16x16x32_bf16 v[0:3], v[144:147], v[176:179], v[0:3]
	v_mfma_f32_16x16x32_bf16 v[240:243], v[148:151], v[176:179], v[240:243]
	v_mfma_f32_16x16x32_bf16 v[112:115], v[204:207], v[176:179], v[112:115]
	ds_read_b128 v[200:203], v212 offset:18432
	s_waitcnt lgkmcnt(4)
	v_mfma_f32_16x16x32_bf16 v[52:55], v[140:143], v[180:183], v[52:55]
	v_mfma_f32_16x16x32_bf16 v[8:11], v[144:147], v[180:183], v[8:11]
	v_mfma_f32_16x16x32_bf16 v[248:251], v[148:151], v[180:183], v[248:251]
	v_mfma_f32_16x16x32_bf16 v[116:119], v[204:207], v[180:183], v[116:119]
	ds_read_b128 v[176:179], v212 offset:20480
	s_waitcnt lgkmcnt(4)
	v_mfma_f32_16x16x32_bf16 v[56:59], v[140:143], v[184:187], v[56:59]
	v_mfma_f32_16x16x32_bf16 v[24:27], v[144:147], v[184:187], v[24:27]
	v_mfma_f32_16x16x32_bf16 v[252:255], v[148:151], v[184:187], v[252:255]
	v_mfma_f32_16x16x32_bf16 v[120:123], v[204:207], v[184:187], v[120:123]
	ds_read_b128 v[180:183], v212 offset:22528
	s_waitcnt lgkmcnt(4)
	v_mfma_f32_16x16x32_bf16 v[60:63], v[140:143], v[192:195], v[60:63]
	v_mfma_f32_16x16x32_bf16 v[28:31], v[144:147], v[192:195], v[28:31]
	v_mfma_f32_16x16x32_bf16 v[92:95], v[148:151], v[192:195], v[92:95]
	v_mfma_f32_16x16x32_bf16 v[124:127], v[204:207], v[192:195], v[124:127]
	s_waitcnt vmcnt(16)
	s_barrier
	s_waitcnt vmcnt(8)
	ds_read_b128 v[184:187], v212 offset:24576
	global_load_dwordx4 v[140:143], v66, s[84:85] offset:1024
	s_waitcnt lgkmcnt(4)
	v_mfma_f32_16x16x32_bf16 v[32:35], v[160:163], v[196:199], v[32:35]
	v_mfma_f32_16x16x32_bf16 v[4:7], v[164:167], v[196:199], v[4:7]
	v_mfma_f32_16x16x32_bf16 v[188:191], v[168:171], v[196:199], v[188:191]
	v_mfma_f32_16x16x32_bf16 v[96:99], v[172:175], v[196:199], v[96:99]
	ds_read_b128 v[192:195], v212 offset:26624
	global_load_dwordx4 v[144:147], v67, s[84:85] offset:1024
	s_waitcnt lgkmcnt(4)
	v_mfma_f32_16x16x32_bf16 v[36:39], v[160:163], v[200:203], v[36:39]
	v_mfma_f32_16x16x32_bf16 v[12:15], v[164:167], v[200:203], v[12:15]
	v_mfma_f32_16x16x32_bf16 v[208:211], v[168:171], v[200:203], v[208:211]
	v_mfma_f32_16x16x32_bf16 v[100:103], v[172:175], v[200:203], v[100:103]
	ds_read_b128 v[196:199], v212 offset:28672
	global_load_dwordx4 v[148:151], v66, s[92:93] offset:1024
	s_waitcnt lgkmcnt(4)
	v_mfma_f32_16x16x32_bf16 v[40:43], v[160:163], v[176:179], v[40:43]
	v_mfma_f32_16x16x32_bf16 v[16:19], v[164:167], v[176:179], v[16:19]
	v_mfma_f32_16x16x32_bf16 v[232:235], v[168:171], v[176:179], v[232:235]
	v_mfma_f32_16x16x32_bf16 v[104:107], v[172:175], v[176:179], v[104:107]
	ds_read_b128 v[200:203], v212 offset:30720
	global_load_dwordx4 v[204:207], v67, s[92:93] offset:1024
	s_add_u32 s84, s84, 0x800
	s_addc_u32 s85, s85, 0
	s_add_u32 s92, s92, 0x800
	s_addc_u32 s93, s93, 0
	s_waitcnt lgkmcnt(4)
	v_mfma_f32_16x16x32_bf16 v[44:47], v[160:163], v[180:183], v[44:47]
	v_mfma_f32_16x16x32_bf16 v[20:23], v[164:167], v[180:183], v[20:23]
	v_mfma_f32_16x16x32_bf16 v[236:239], v[168:171], v[180:183], v[236:239]
	v_mfma_f32_16x16x32_bf16 v[108:111], v[172:175], v[180:183], v[108:111]
	ds_read_b128 v[176:179], v75 offset:32768
	s_add_u32 m0, s88, 0
	s_nop 0
	global_load_lds_dwordx4 v68, s[86:87]
	s_waitcnt lgkmcnt(4)
	v_mfma_f32_16x16x32_bf16 v[48:51], v[160:163], v[184:187], v[48:51]
	v_mfma_f32_16x16x32_bf16 v[0:3], v[164:167], v[184:187], v[0:3]
	v_mfma_f32_16x16x32_bf16 v[240:243], v[168:171], v[184:187], v[240:243]
	v_mfma_f32_16x16x32_bf16 v[112:115], v[172:175], v[184:187], v[112:115]
	ds_read_b128 v[180:183], v75 offset:34816
	s_add_u32 m0, s88, 4096
	s_nop 0
	global_load_lds_dwordx4 v69, s[86:87]
	s_waitcnt lgkmcnt(4)
	v_mfma_f32_16x16x32_bf16 v[52:55], v[160:163], v[192:195], v[52:55]
	v_mfma_f32_16x16x32_bf16 v[8:11], v[164:167], v[192:195], v[8:11]
	v_mfma_f32_16x16x32_bf16 v[248:251], v[168:171], v[192:195], v[248:251]
	v_mfma_f32_16x16x32_bf16 v[116:119], v[172:175], v[192:195], v[116:119]
	ds_read_b128 v[184:187], v75 offset:36864
	s_add_u32 m0, s88, 8192
	s_nop 0
	global_load_lds_dwordx4 v71, s[86:87]
	s_waitcnt lgkmcnt(4)
	v_mfma_f32_16x16x32_bf16 v[56:59], v[160:163], v[196:199], v[56:59]
	v_mfma_f32_16x16x32_bf16 v[24:27], v[164:167], v[196:199], v[24:27]
	v_mfma_f32_16x16x32_bf16 v[252:255], v[168:171], v[196:199], v[252:255]
	v_mfma_f32_16x16x32_bf16 v[120:123], v[172:175], v[196:199], v[120:123]
	ds_read_b128 v[192:195], v75 offset:38912
	s_add_u32 m0, s88, 12288
	s_nop 0
	global_load_lds_dwordx4 v74, s[86:87]
	s_add_u32 s86, s86, 128
	s_addc_u32 s87, s87, 0
	s_waitcnt lgkmcnt(4)
	v_mfma_f32_16x16x32_bf16 v[60:63], v[160:163], v[200:203], v[60:63]
	v_mfma_f32_16x16x32_bf16 v[28:31], v[164:167], v[200:203], v[28:31]
	v_mfma_f32_16x16x32_bf16 v[92:95], v[168:171], v[200:203], v[92:95]
	v_mfma_f32_16x16x32_bf16 v[124:127], v[172:175], v[200:203], v[124:127]
	s_waitcnt vmcnt(8)
	ds_read_b128 v[196:199], v75 offset:40960
	global_load_dwordx4 v[160:163], v66, s[84:85] offset:0
	s_waitcnt lgkmcnt(4)
	v_mfma_f32_16x16x32_bf16 v[32:35], v[76:79], v[176:179], v[32:35]
	v_mfma_f32_16x16x32_bf16 v[4:7], v[80:83], v[176:179], v[4:7]
	v_mfma_f32_16x16x32_bf16 v[188:191], v[84:87], v[176:179], v[188:191]
	v_mfma_f32_16x16x32_bf16 v[96:99], v[88:91], v[176:179], v[96:99]
	ds_read_b128 v[200:203], v75 offset:43008
	global_load_dwordx4 v[164:167], v67, s[84:85] offset:0
	s_waitcnt lgkmcnt(4)
	v_mfma_f32_16x16x32_bf16 v[36:39], v[76:79], v[180:183], v[36:39]
	v_mfma_f32_16x16x32_bf16 v[12:15], v[80:83], v[180:183], v[12:15]
	v_mfma_f32_16x16x32_bf16 v[208:211], v[84:87], v[180:183], v[208:211]
	v_mfma_f32_16x16x32_bf16 v[100:103], v[88:91], v[180:183], v[100:103]
	ds_read_b128 v[176:179], v75 offset:45056
	global_load_dwordx4 v[168:171], v66, s[92:93] offset:0
	s_waitcnt lgkmcnt(4)
	v_mfma_f32_16x16x32_bf16 v[40:43], v[76:79], v[184:187], v[40:43]
	v_mfma_f32_16x16x32_bf16 v[16:19], v[80:83], v[184:187], v[16:19]
	v_mfma_f32_16x16x32_bf16 v[232:235], v[84:87], v[184:187], v[232:235]
	v_mfma_f32_16x16x32_bf16 v[104:107], v[88:91], v[184:187], v[104:107]
	ds_read_b128 v[180:183], v75 offset:47104
	global_load_dwordx4 v[172:175], v67, s[92:93] offset:0
	s_waitcnt lgkmcnt(4)
	v_mfma_f32_16x16x32_bf16 v[44:47], v[76:79], v[192:195], v[44:47]
	v_mfma_f32_16x16x32_bf16 v[20:23], v[80:83], v[192:195], v[20:23]
	v_mfma_f32_16x16x32_bf16 v[236:239], v[84:87], v[192:195], v[236:239]
	v_mfma_f32_16x16x32_bf16 v[108:111], v[88:91], v[192:195], v[108:111]
	ds_read_b128 v[184:187], v212 offset:32768
	s_waitcnt lgkmcnt(4)
	v_mfma_f32_16x16x32_bf16 v[48:51], v[76:79], v[196:199], v[48:51]
	v_mfma_f32_16x16x32_bf16 v[0:3], v[80:83], v[196:199], v[0:3]
	v_mfma_f32_16x16x32_bf16 v[240:243], v[84:87], v[196:199], v[240:243]
	v_mfma_f32_16x16x32_bf16 v[112:115], v[88:91], v[196:199], v[112:115]
	ds_read_b128 v[192:195], v212 offset:34816
	s_waitcnt lgkmcnt(4)
	v_mfma_f32_16x16x32_bf16 v[52:55], v[76:79], v[200:203], v[52:55]
	v_mfma_f32_16x16x32_bf16 v[8:11], v[80:83], v[200:203], v[8:11]
	v_mfma_f32_16x16x32_bf16 v[248:251], v[84:87], v[200:203], v[248:251]
	v_mfma_f32_16x16x32_bf16 v[116:119], v[88:91], v[200:203], v[116:119]
	ds_read_b128 v[196:199], v212 offset:36864
	s_waitcnt lgkmcnt(4)
	v_mfma_f32_16x16x32_bf16 v[56:59], v[76:79], v[176:179], v[56:59]
	v_mfma_f32_16x16x32_bf16 v[24:27], v[80:83], v[176:179], v[24:27]
	v_mfma_f32_16x16x32_bf16 v[252:255], v[84:87], v[176:179], v[252:255]
	v_mfma_f32_16x16x32_bf16 v[120:123], v[88:91], v[176:179], v[120:123]
	ds_read_b128 v[200:203], v212 offset:38912
	s_waitcnt lgkmcnt(4)
	v_mfma_f32_16x16x32_bf16 v[60:63], v[76:79], v[180:183], v[60:63]
	v_mfma_f32_16x16x32_bf16 v[28:31], v[80:83], v[180:183], v[28:31]
	v_mfma_f32_16x16x32_bf16 v[92:95], v[84:87], v[180:183], v[92:95]
	v_mfma_f32_16x16x32_bf16 v[124:127], v[88:91], v[180:183], v[124:127]
	s_waitcnt vmcnt(16)
	s_barrier
	s_waitcnt vmcnt(8)
	ds_read_b128 v[176:179], v212 offset:40960
	global_load_dwordx4 v[76:79], v66, s[84:85] offset:1024
	s_waitcnt lgkmcnt(4)
	v_mfma_f32_16x16x32_bf16 v[32:35], v[140:143], v[184:187], v[32:35]
	v_mfma_f32_16x16x32_bf16 v[4:7], v[144:147], v[184:187], v[4:7]
	v_mfma_f32_16x16x32_bf16 v[188:191], v[148:151], v[184:187], v[188:191]
	v_mfma_f32_16x16x32_bf16 v[96:99], v[204:207], v[184:187], v[96:99]
	ds_read_b128 v[180:183], v212 offset:43008
	global_load_dwordx4 v[80:83], v67, s[84:85] offset:1024
	s_waitcnt lgkmcnt(4)
	v_mfma_f32_16x16x32_bf16 v[36:39], v[140:143], v[192:195], v[36:39]
	v_mfma_f32_16x16x32_bf16 v[12:15], v[144:147], v[192:195], v[12:15]
	v_mfma_f32_16x16x32_bf16 v[208:211], v[148:151], v[192:195], v[208:211]
	v_mfma_f32_16x16x32_bf16 v[100:103], v[204:207], v[192:195], v[100:103]
	ds_read_b128 v[184:187], v212 offset:45056
	global_load_dwordx4 v[84:87], v66, s[92:93] offset:1024
	s_waitcnt lgkmcnt(4)
	v_mfma_f32_16x16x32_bf16 v[40:43], v[140:143], v[196:199], v[40:43]
	v_mfma_f32_16x16x32_bf16 v[16:19], v[144:147], v[196:199], v[16:19]
	v_mfma_f32_16x16x32_bf16 v[232:235], v[148:151], v[196:199], v[232:235]
	v_mfma_f32_16x16x32_bf16 v[104:107], v[204:207], v[196:199], v[104:107]
	ds_read_b128 v[192:195], v212 offset:47104
	global_load_dwordx4 v[88:91], v67, s[92:93] offset:1024
	s_add_u32 s84, s84, 0x800
	s_addc_u32 s85, s85, 0
	s_add_u32 s92, s92, 0x800
	s_addc_u32 s93, s93, 0
	s_waitcnt lgkmcnt(4)
	v_mfma_f32_16x16x32_bf16 v[44:47], v[140:143], v[200:203], v[44:47]
	v_mfma_f32_16x16x32_bf16 v[20:23], v[144:147], v[200:203], v[20:23]
	v_mfma_f32_16x16x32_bf16 v[236:239], v[148:151], v[200:203], v[236:239]
	v_mfma_f32_16x16x32_bf16 v[108:111], v[204:207], v[200:203], v[108:111]
	ds_read_b128 v[196:199], v75 offset:49152
	s_add_u32 m0, s88, 16384
	s_nop 0
	global_load_lds_dwordx4 v68, s[86:87]
	s_waitcnt lgkmcnt(4)
	v_mfma_f32_16x16x32_bf16 v[48:51], v[140:143], v[176:179], v[48:51]
	v_mfma_f32_16x16x32_bf16 v[0:3], v[144:147], v[176:179], v[0:3]
	v_mfma_f32_16x16x32_bf16 v[240:243], v[148:151], v[176:179], v[240:243]
	v_mfma_f32_16x16x32_bf16 v[112:115], v[204:207], v[176:179], v[112:115]
	ds_read_b128 v[200:203], v75 offset:51200
	s_add_u32 m0, s88, 20480
	s_nop 0
	global_load_lds_dwordx4 v69, s[86:87]
	s_waitcnt lgkmcnt(4)
	v_mfma_f32_16x16x32_bf16 v[52:55], v[140:143], v[180:183], v[52:55]
	v_mfma_f32_16x16x32_bf16 v[8:11], v[144:147], v[180:183], v[8:11]
	v_mfma_f32_16x16x32_bf16 v[248:251], v[148:151], v[180:183], v[248:251]
	v_mfma_f32_16x16x32_bf16 v[116:119], v[204:207], v[180:183], v[116:119]
	ds_read_b128 v[176:179], v75 offset:53248
	s_add_u32 m0, s88, 24576
	s_nop 0
	global_load_lds_dwordx4 v71, s[86:87]
	s_waitcnt lgkmcnt(4)
	v_mfma_f32_16x16x32_bf16 v[56:59], v[140:143], v[184:187], v[56:59]
	v_mfma_f32_16x16x32_bf16 v[24:27], v[144:147], v[184:187], v[24:27]
	v_mfma_f32_16x16x32_bf16 v[252:255], v[148:151], v[184:187], v[252:255]
	v_mfma_f32_16x16x32_bf16 v[120:123], v[204:207], v[184:187], v[120:123]
	ds_read_b128 v[180:183], v75 offset:55296
	s_add_u32 m0, s88, 28672
	s_nop 0
	global_load_lds_dwordx4 v74, s[86:87]
	s_add_u32 s86, s86, 128
	s_addc_u32 s87, s87, 0
	s_waitcnt lgkmcnt(4)
	v_mfma_f32_16x16x32_bf16 v[60:63], v[140:143], v[192:195], v[60:63]
	v_mfma_f32_16x16x32_bf16 v[28:31], v[144:147], v[192:195], v[28:31]
	v_mfma_f32_16x16x32_bf16 v[92:95], v[148:151], v[192:195], v[92:95]
	v_mfma_f32_16x16x32_bf16 v[124:127], v[204:207], v[192:195], v[124:127]
	s_waitcnt vmcnt(8)
	ds_read_b128 v[184:187], v75 offset:57344
	global_load_dwordx4 v[140:143], v66, s[84:85] offset:0
	s_waitcnt lgkmcnt(4)
	v_mfma_f32_16x16x32_bf16 v[32:35], v[160:163], v[196:199], v[32:35]
	v_mfma_f32_16x16x32_bf16 v[4:7], v[164:167], v[196:199], v[4:7]
	v_mfma_f32_16x16x32_bf16 v[188:191], v[168:171], v[196:199], v[188:191]
	v_mfma_f32_16x16x32_bf16 v[96:99], v[172:175], v[196:199], v[96:99]
	ds_read_b128 v[192:195], v75 offset:59392
	global_load_dwordx4 v[144:147], v67, s[84:85] offset:0
	s_waitcnt lgkmcnt(4)
	v_mfma_f32_16x16x32_bf16 v[36:39], v[160:163], v[200:203], v[36:39]
	v_mfma_f32_16x16x32_bf16 v[12:15], v[164:167], v[200:203], v[12:15]
	v_mfma_f32_16x16x32_bf16 v[208:211], v[168:171], v[200:203], v[208:211]
	v_mfma_f32_16x16x32_bf16 v[100:103], v[172:175], v[200:203], v[100:103]
	ds_read_b128 v[196:199], v75 offset:61440
	global_load_dwordx4 v[148:151], v66, s[92:93] offset:0
	s_waitcnt lgkmcnt(4)
	v_mfma_f32_16x16x32_bf16 v[40:43], v[160:163], v[176:179], v[40:43]
	v_mfma_f32_16x16x32_bf16 v[16:19], v[164:167], v[176:179], v[16:19]
	v_mfma_f32_16x16x32_bf16 v[232:235], v[168:171], v[176:179], v[232:235]
	v_mfma_f32_16x16x32_bf16 v[104:107], v[172:175], v[176:179], v[104:107]
	ds_read_b128 v[200:203], v75 offset:63488
	global_load_dwordx4 v[204:207], v67, s[92:93] offset:0
	s_waitcnt lgkmcnt(4)
	v_mfma_f32_16x16x32_bf16 v[44:47], v[160:163], v[180:183], v[44:47]
	v_mfma_f32_16x16x32_bf16 v[20:23], v[164:167], v[180:183], v[20:23]
	v_mfma_f32_16x16x32_bf16 v[236:239], v[168:171], v[180:183], v[236:239]
	v_mfma_f32_16x16x32_bf16 v[108:111], v[172:175], v[180:183], v[108:111]
	ds_read_b128 v[176:179], v212 offset:49152
	s_waitcnt lgkmcnt(4)
	v_mfma_f32_16x16x32_bf16 v[48:51], v[160:163], v[184:187], v[48:51]
	v_mfma_f32_16x16x32_bf16 v[0:3], v[164:167], v[184:187], v[0:3]
	v_mfma_f32_16x16x32_bf16 v[240:243], v[168:171], v[184:187], v[240:243]
	v_mfma_f32_16x16x32_bf16 v[112:115], v[172:175], v[184:187], v[112:115]
	ds_read_b128 v[180:183], v212 offset:51200
	s_waitcnt lgkmcnt(4)
	v_mfma_f32_16x16x32_bf16 v[52:55], v[160:163], v[192:195], v[52:55]
	v_mfma_f32_16x16x32_bf16 v[8:11], v[164:167], v[192:195], v[8:11]
	v_mfma_f32_16x16x32_bf16 v[248:251], v[168:171], v[192:195], v[248:251]
	v_mfma_f32_16x16x32_bf16 v[116:119], v[172:175], v[192:195], v[116:119]
	ds_read_b128 v[184:187], v212 offset:53248
	s_waitcnt lgkmcnt(4)
	v_mfma_f32_16x16x32_bf16 v[56:59], v[160:163], v[196:199], v[56:59]
	v_mfma_f32_16x16x32_bf16 v[24:27], v[164:167], v[196:199], v[24:27]
	v_mfma_f32_16x16x32_bf16 v[252:255], v[168:171], v[196:199], v[252:255]
	v_mfma_f32_16x16x32_bf16 v[120:123], v[172:175], v[196:199], v[120:123]
	ds_read_b128 v[192:195], v212 offset:55296
	s_waitcnt lgkmcnt(4)
	v_mfma_f32_16x16x32_bf16 v[60:63], v[160:163], v[200:203], v[60:63]
	v_mfma_f32_16x16x32_bf16 v[28:31], v[164:167], v[200:203], v[28:31]
	v_mfma_f32_16x16x32_bf16 v[92:95], v[168:171], v[200:203], v[92:95]
	v_mfma_f32_16x16x32_bf16 v[124:127], v[172:175], v[200:203], v[124:127]
	s_waitcnt vmcnt(16)
	s_barrier
	s_waitcnt vmcnt(8)
	ds_read_b128 v[196:199], v212 offset:57344
	global_load_dwordx4 v[160:163], v66, s[84:85] offset:1024
	s_waitcnt lgkmcnt(4)
	v_mfma_f32_16x16x32_bf16 v[32:35], v[76:79], v[176:179], v[32:35]
	v_mfma_f32_16x16x32_bf16 v[4:7], v[80:83], v[176:179], v[4:7]
	v_mfma_f32_16x16x32_bf16 v[188:191], v[84:87], v[176:179], v[188:191]
	v_mfma_f32_16x16x32_bf16 v[96:99], v[88:91], v[176:179], v[96:99]
	ds_read_b128 v[200:203], v212 offset:59392
	global_load_dwordx4 v[164:167], v67, s[84:85] offset:1024
	s_waitcnt lgkmcnt(4)
	v_mfma_f32_16x16x32_bf16 v[36:39], v[76:79], v[180:183], v[36:39]
	v_mfma_f32_16x16x32_bf16 v[12:15], v[80:83], v[180:183], v[12:15]
	v_mfma_f32_16x16x32_bf16 v[208:211], v[84:87], v[180:183], v[208:211]
	v_mfma_f32_16x16x32_bf16 v[100:103], v[88:91], v[180:183], v[100:103]
	ds_read_b128 v[176:179], v212 offset:61440
	global_load_dwordx4 v[168:171], v66, s[92:93] offset:1024
	s_waitcnt lgkmcnt(4)
	v_mfma_f32_16x16x32_bf16 v[40:43], v[76:79], v[184:187], v[40:43]
	v_mfma_f32_16x16x32_bf16 v[16:19], v[80:83], v[184:187], v[16:19]
	v_mfma_f32_16x16x32_bf16 v[232:235], v[84:87], v[184:187], v[232:235]
	v_mfma_f32_16x16x32_bf16 v[104:107], v[88:91], v[184:187], v[104:107]
	ds_read_b128 v[180:183], v212 offset:63488
	global_load_dwordx4 v[172:175], v67, s[92:93] offset:1024
	s_add_u32 s84, s84, 0x800
	s_addc_u32 s85, s85, 0
	s_add_u32 s92, s92, 0x800
	s_addc_u32 s93, s93, 0
	s_waitcnt lgkmcnt(4)
	v_mfma_f32_16x16x32_bf16 v[44:47], v[76:79], v[192:195], v[44:47]
	v_mfma_f32_16x16x32_bf16 v[20:23], v[80:83], v[192:195], v[20:23]
	v_mfma_f32_16x16x32_bf16 v[236:239], v[84:87], v[192:195], v[236:239]
	v_mfma_f32_16x16x32_bf16 v[108:111], v[88:91], v[192:195], v[108:111]
	ds_read_b128 v[184:187], v75 offset:0
	s_add_u32 m0, s88, 32768
	s_nop 0
	global_load_lds_dwordx4 v68, s[86:87]
	s_waitcnt lgkmcnt(4)
	v_mfma_f32_16x16x32_bf16 v[48:51], v[76:79], v[196:199], v[48:51]
	v_mfma_f32_16x16x32_bf16 v[0:3], v[80:83], v[196:199], v[0:3]
	v_mfma_f32_16x16x32_bf16 v[240:243], v[84:87], v[196:199], v[240:243]
	v_mfma_f32_16x16x32_bf16 v[112:115], v[88:91], v[196:199], v[112:115]
	ds_read_b128 v[192:195], v75 offset:2048
	s_add_u32 m0, s88, 36864
	s_nop 0
	global_load_lds_dwordx4 v69, s[86:87]
	s_waitcnt lgkmcnt(4)
	v_mfma_f32_16x16x32_bf16 v[52:55], v[76:79], v[200:203], v[52:55]
	v_mfma_f32_16x16x32_bf16 v[8:11], v[80:83], v[200:203], v[8:11]
	v_mfma_f32_16x16x32_bf16 v[248:251], v[84:87], v[200:203], v[248:251]
	v_mfma_f32_16x16x32_bf16 v[116:119], v[88:91], v[200:203], v[116:119]
	ds_read_b128 v[196:199], v75 offset:4096
	s_add_u32 m0, s88, 40960
	s_nop 0
	global_load_lds_dwordx4 v71, s[86:87]
	s_waitcnt lgkmcnt(4)
	v_mfma_f32_16x16x32_bf16 v[56:59], v[76:79], v[176:179], v[56:59]
	v_mfma_f32_16x16x32_bf16 v[24:27], v[80:83], v[176:179], v[24:27]
	v_mfma_f32_16x16x32_bf16 v[252:255], v[84:87], v[176:179], v[252:255]
	v_mfma_f32_16x16x32_bf16 v[120:123], v[88:91], v[176:179], v[120:123]
	ds_read_b128 v[200:203], v75 offset:6144
	s_add_u32 m0, s88, 45056
	s_nop 0
	global_load_lds_dwordx4 v74, s[86:87]
	s_add_u32 s86, s86, 128
	s_addc_u32 s87, s87, 0
	s_waitcnt lgkmcnt(4)
	v_mfma_f32_16x16x32_bf16 v[60:63], v[76:79], v[180:183], v[60:63]
	v_mfma_f32_16x16x32_bf16 v[28:31], v[80:83], v[180:183], v[28:31]
	v_mfma_f32_16x16x32_bf16 v[92:95], v[84:87], v[180:183], v[92:95]
	v_mfma_f32_16x16x32_bf16 v[124:127], v[88:91], v[180:183], v[124:127]
	s_waitcnt vmcnt(8)
	ds_read_b128 v[176:179], v75 offset:8192
	global_load_dwordx4 v[76:79], v66, s[84:85] offset:0
	s_waitcnt lgkmcnt(4)
	v_mfma_f32_16x16x32_bf16 v[32:35], v[140:143], v[184:187], v[32:35]
	v_mfma_f32_16x16x32_bf16 v[4:7], v[144:147], v[184:187], v[4:7]
	v_mfma_f32_16x16x32_bf16 v[188:191], v[148:151], v[184:187], v[188:191]
	v_mfma_f32_16x16x32_bf16 v[96:99], v[204:207], v[184:187], v[96:99]
	ds_read_b128 v[180:183], v75 offset:10240
	global_load_dwordx4 v[80:83], v67, s[84:85] offset:0
	s_waitcnt lgkmcnt(4)
	v_mfma_f32_16x16x32_bf16 v[36:39], v[140:143], v[192:195], v[36:39]
	v_mfma_f32_16x16x32_bf16 v[12:15], v[144:147], v[192:195], v[12:15]
	v_mfma_f32_16x16x32_bf16 v[208:211], v[148:151], v[192:195], v[208:211]
	v_mfma_f32_16x16x32_bf16 v[100:103], v[204:207], v[192:195], v[100:103]
	ds_read_b128 v[184:187], v75 offset:12288
	global_load_dwordx4 v[84:87], v66, s[92:93] offset:0
	s_waitcnt lgkmcnt(4)
	v_mfma_f32_16x16x32_bf16 v[40:43], v[140:143], v[196:199], v[40:43]
	v_mfma_f32_16x16x32_bf16 v[16:19], v[144:147], v[196:199], v[16:19]
	v_mfma_f32_16x16x32_bf16 v[232:235], v[148:151], v[196:199], v[232:235]
	v_mfma_f32_16x16x32_bf16 v[104:107], v[204:207], v[196:199], v[104:107]
	ds_read_b128 v[192:195], v75 offset:14336
	global_load_dwordx4 v[88:91], v67, s[92:93] offset:0
	s_waitcnt lgkmcnt(4)
	v_mfma_f32_16x16x32_bf16 v[44:47], v[140:143], v[200:203], v[44:47]
	v_mfma_f32_16x16x32_bf16 v[20:23], v[144:147], v[200:203], v[20:23]
	v_mfma_f32_16x16x32_bf16 v[236:239], v[148:151], v[200:203], v[236:239]
	v_mfma_f32_16x16x32_bf16 v[108:111], v[204:207], v[200:203], v[108:111]
	ds_read_b128 v[196:199], v212 offset:0
	s_waitcnt lgkmcnt(4)
	v_mfma_f32_16x16x32_bf16 v[48:51], v[140:143], v[176:179], v[48:51]
	v_mfma_f32_16x16x32_bf16 v[0:3], v[144:147], v[176:179], v[0:3]
	v_mfma_f32_16x16x32_bf16 v[240:243], v[148:151], v[176:179], v[240:243]
	v_mfma_f32_16x16x32_bf16 v[112:115], v[204:207], v[176:179], v[112:115]
	ds_read_b128 v[200:203], v212 offset:2048
	s_waitcnt lgkmcnt(4)
	v_mfma_f32_16x16x32_bf16 v[52:55], v[140:143], v[180:183], v[52:55]
	v_mfma_f32_16x16x32_bf16 v[8:11], v[144:147], v[180:183], v[8:11]
	v_mfma_f32_16x16x32_bf16 v[248:251], v[148:151], v[180:183], v[248:251]
	v_mfma_f32_16x16x32_bf16 v[116:119], v[204:207], v[180:183], v[116:119]
	ds_read_b128 v[176:179], v212 offset:4096
	s_waitcnt lgkmcnt(4)
	v_mfma_f32_16x16x32_bf16 v[56:59], v[140:143], v[184:187], v[56:59]
	v_mfma_f32_16x16x32_bf16 v[24:27], v[144:147], v[184:187], v[24:27]
	v_mfma_f32_16x16x32_bf16 v[252:255], v[148:151], v[184:187], v[252:255]
	v_mfma_f32_16x16x32_bf16 v[120:123], v[204:207], v[184:187], v[120:123]
	ds_read_b128 v[180:183], v212 offset:6144
	s_waitcnt lgkmcnt(4)
	v_mfma_f32_16x16x32_bf16 v[60:63], v[140:143], v[192:195], v[60:63]
	v_mfma_f32_16x16x32_bf16 v[28:31], v[144:147], v[192:195], v[28:31]
	v_mfma_f32_16x16x32_bf16 v[92:95], v[148:151], v[192:195], v[92:95]
	v_mfma_f32_16x16x32_bf16 v[124:127], v[204:207], v[192:195], v[124:127]
	s_waitcnt vmcnt(16)
	s_barrier
	s_waitcnt vmcnt(8)
	ds_read_b128 v[184:187], v212 offset:8192
	global_load_dwordx4 v[140:143], v66, s[84:85] offset:1024
	s_waitcnt lgkmcnt(4)
	v_mfma_f32_16x16x32_bf16 v[32:35], v[160:163], v[196:199], v[32:35]
	v_mfma_f32_16x16x32_bf16 v[4:7], v[164:167], v[196:199], v[4:7]
	v_mfma_f32_16x16x32_bf16 v[188:191], v[168:171], v[196:199], v[188:191]
	v_mfma_f32_16x16x32_bf16 v[96:99], v[172:175], v[196:199], v[96:99]
	ds_read_b128 v[192:195], v212 offset:10240
	global_load_dwordx4 v[144:147], v67, s[84:85] offset:1024
	s_waitcnt lgkmcnt(4)
	v_mfma_f32_16x16x32_bf16 v[36:39], v[160:163], v[200:203], v[36:39]
	v_mfma_f32_16x16x32_bf16 v[12:15], v[164:167], v[200:203], v[12:15]
	v_mfma_f32_16x16x32_bf16 v[208:211], v[168:171], v[200:203], v[208:211]
	v_mfma_f32_16x16x32_bf16 v[100:103], v[172:175], v[200:203], v[100:103]
	ds_read_b128 v[196:199], v212 offset:12288
	global_load_dwordx4 v[148:151], v66, s[92:93] offset:1024
	s_waitcnt lgkmcnt(4)
	v_mfma_f32_16x16x32_bf16 v[40:43], v[160:163], v[176:179], v[40:43]
	v_mfma_f32_16x16x32_bf16 v[16:19], v[164:167], v[176:179], v[16:19]
	v_mfma_f32_16x16x32_bf16 v[232:235], v[168:171], v[176:179], v[232:235]
	v_mfma_f32_16x16x32_bf16 v[104:107], v[172:175], v[176:179], v[104:107]
	ds_read_b128 v[200:203], v212 offset:14336
	global_load_dwordx4 v[204:207], v67, s[92:93] offset:1024
	s_add_u32 s84, s84, 0x800
	s_addc_u32 s85, s85, 0
	s_add_u32 s92, s92, 0x800
	s_addc_u32 s93, s93, 0
	s_waitcnt lgkmcnt(4)
	v_mfma_f32_16x16x32_bf16 v[44:47], v[160:163], v[180:183], v[44:47]
	v_mfma_f32_16x16x32_bf16 v[20:23], v[164:167], v[180:183], v[20:23]
	v_mfma_f32_16x16x32_bf16 v[236:239], v[168:171], v[180:183], v[236:239]
	v_mfma_f32_16x16x32_bf16 v[108:111], v[172:175], v[180:183], v[108:111]
	ds_read_b128 v[176:179], v75 offset:16384
	s_add_u32 m0, s88, 49152
	s_nop 0
	global_load_lds_dwordx4 v68, s[86:87]
	s_waitcnt lgkmcnt(4)
	v_mfma_f32_16x16x32_bf16 v[48:51], v[160:163], v[184:187], v[48:51]
	v_mfma_f32_16x16x32_bf16 v[0:3], v[164:167], v[184:187], v[0:3]
	v_mfma_f32_16x16x32_bf16 v[240:243], v[168:171], v[184:187], v[240:243]
	v_mfma_f32_16x16x32_bf16 v[112:115], v[172:175], v[184:187], v[112:115]
	ds_read_b128 v[180:183], v75 offset:18432
	s_add_u32 m0, s88, 53248
	s_nop 0
	global_load_lds_dwordx4 v69, s[86:87]
	s_waitcnt lgkmcnt(4)
	v_mfma_f32_16x16x32_bf16 v[52:55], v[160:163], v[192:195], v[52:55]
	v_mfma_f32_16x16x32_bf16 v[8:11], v[164:167], v[192:195], v[8:11]
	v_mfma_f32_16x16x32_bf16 v[248:251], v[168:171], v[192:195], v[248:251]
	v_mfma_f32_16x16x32_bf16 v[116:119], v[172:175], v[192:195], v[116:119]
	ds_read_b128 v[184:187], v75 offset:20480
	s_add_u32 m0, s88, 57344
	s_nop 0
	global_load_lds_dwordx4 v71, s[86:87]
	s_waitcnt lgkmcnt(4)
	v_mfma_f32_16x16x32_bf16 v[56:59], v[160:163], v[196:199], v[56:59]
	v_mfma_f32_16x16x32_bf16 v[24:27], v[164:167], v[196:199], v[24:27]
	v_mfma_f32_16x16x32_bf16 v[252:255], v[168:171], v[196:199], v[252:255]
	v_mfma_f32_16x16x32_bf16 v[120:123], v[172:175], v[196:199], v[120:123]
	ds_read_b128 v[192:195], v75 offset:22528
	s_add_u32 m0, s88, 61440
	s_nop 0
	global_load_lds_dwordx4 v74, s[86:87]
	s_add_u32 s86, s86, 128
	s_addc_u32 s87, s87, 0
	s_waitcnt lgkmcnt(4)
	v_mfma_f32_16x16x32_bf16 v[60:63], v[160:163], v[200:203], v[60:63]
	v_mfma_f32_16x16x32_bf16 v[28:31], v[164:167], v[200:203], v[28:31]
	v_mfma_f32_16x16x32_bf16 v[92:95], v[168:171], v[200:203], v[92:95]
	v_mfma_f32_16x16x32_bf16 v[124:127], v[172:175], v[200:203], v[124:127]
	s_waitcnt vmcnt(8)
	ds_read_b128 v[196:199], v75 offset:24576
	global_load_dwordx4 v[160:163], v66, s[84:85] offset:0
	s_waitcnt lgkmcnt(4)
	v_mfma_f32_16x16x32_bf16 v[32:35], v[76:79], v[176:179], v[32:35]
	v_mfma_f32_16x16x32_bf16 v[4:7], v[80:83], v[176:179], v[4:7]
	v_mfma_f32_16x16x32_bf16 v[188:191], v[84:87], v[176:179], v[188:191]
	v_mfma_f32_16x16x32_bf16 v[96:99], v[88:91], v[176:179], v[96:99]
	ds_read_b128 v[200:203], v75 offset:26624
	global_load_dwordx4 v[164:167], v67, s[84:85] offset:0
	s_waitcnt lgkmcnt(4)
	v_mfma_f32_16x16x32_bf16 v[36:39], v[76:79], v[180:183], v[36:39]
	v_mfma_f32_16x16x32_bf16 v[12:15], v[80:83], v[180:183], v[12:15]
	v_mfma_f32_16x16x32_bf16 v[208:211], v[84:87], v[180:183], v[208:211]
	v_mfma_f32_16x16x32_bf16 v[100:103], v[88:91], v[180:183], v[100:103]
	ds_read_b128 v[176:179], v75 offset:28672
	global_load_dwordx4 v[168:171], v66, s[92:93] offset:0
	s_waitcnt lgkmcnt(4)
	v_mfma_f32_16x16x32_bf16 v[40:43], v[76:79], v[184:187], v[40:43]
	v_mfma_f32_16x16x32_bf16 v[16:19], v[80:83], v[184:187], v[16:19]
	v_mfma_f32_16x16x32_bf16 v[232:235], v[84:87], v[184:187], v[232:235]
	v_mfma_f32_16x16x32_bf16 v[104:107], v[88:91], v[184:187], v[104:107]
	ds_read_b128 v[180:183], v75 offset:30720
	global_load_dwordx4 v[172:175], v67, s[92:93] offset:0
	s_waitcnt lgkmcnt(4)
	v_mfma_f32_16x16x32_bf16 v[44:47], v[76:79], v[192:195], v[44:47]
	v_mfma_f32_16x16x32_bf16 v[20:23], v[80:83], v[192:195], v[20:23]
	v_mfma_f32_16x16x32_bf16 v[236:239], v[84:87], v[192:195], v[236:239]
	v_mfma_f32_16x16x32_bf16 v[108:111], v[88:91], v[192:195], v[108:111]
	ds_read_b128 v[184:187], v212 offset:16384
	s_waitcnt lgkmcnt(4)
	v_mfma_f32_16x16x32_bf16 v[48:51], v[76:79], v[196:199], v[48:51]
	v_mfma_f32_16x16x32_bf16 v[0:3], v[80:83], v[196:199], v[0:3]
	v_mfma_f32_16x16x32_bf16 v[240:243], v[84:87], v[196:199], v[240:243]
	v_mfma_f32_16x16x32_bf16 v[112:115], v[88:91], v[196:199], v[112:115]
	ds_read_b128 v[192:195], v212 offset:18432
	s_waitcnt lgkmcnt(4)
	v_mfma_f32_16x16x32_bf16 v[52:55], v[76:79], v[200:203], v[52:55]
	v_mfma_f32_16x16x32_bf16 v[8:11], v[80:83], v[200:203], v[8:11]
	v_mfma_f32_16x16x32_bf16 v[248:251], v[84:87], v[200:203], v[248:251]
	v_mfma_f32_16x16x32_bf16 v[116:119], v[88:91], v[200:203], v[116:119]
	ds_read_b128 v[196:199], v212 offset:20480
	s_waitcnt lgkmcnt(4)
	v_mfma_f32_16x16x32_bf16 v[56:59], v[76:79], v[176:179], v[56:59]
	v_mfma_f32_16x16x32_bf16 v[24:27], v[80:83], v[176:179], v[24:27]
	v_mfma_f32_16x16x32_bf16 v[252:255], v[84:87], v[176:179], v[252:255]
	v_mfma_f32_16x16x32_bf16 v[120:123], v[88:91], v[176:179], v[120:123]
	ds_read_b128 v[200:203], v212 offset:22528
	s_waitcnt lgkmcnt(4)
	v_mfma_f32_16x16x32_bf16 v[60:63], v[76:79], v[180:183], v[60:63]
	v_mfma_f32_16x16x32_bf16 v[28:31], v[80:83], v[180:183], v[28:31]
	v_mfma_f32_16x16x32_bf16 v[92:95], v[84:87], v[180:183], v[92:95]
	v_mfma_f32_16x16x32_bf16 v[124:127], v[88:91], v[180:183], v[124:127]
	s_waitcnt vmcnt(16)
	s_barrier
	s_waitcnt vmcnt(8)
	ds_read_b128 v[176:179], v212 offset:24576
	global_load_dwordx4 v[76:79], v66, s[84:85] offset:1024
	s_waitcnt lgkmcnt(4)
	v_mfma_f32_16x16x32_bf16 v[32:35], v[140:143], v[184:187], v[32:35]
	v_mfma_f32_16x16x32_bf16 v[4:7], v[144:147], v[184:187], v[4:7]
	v_mfma_f32_16x16x32_bf16 v[188:191], v[148:151], v[184:187], v[188:191]
	v_mfma_f32_16x16x32_bf16 v[96:99], v[204:207], v[184:187], v[96:99]
	ds_read_b128 v[180:183], v212 offset:26624
	global_load_dwordx4 v[80:83], v67, s[84:85] offset:1024
	s_waitcnt lgkmcnt(4)
	v_mfma_f32_16x16x32_bf16 v[36:39], v[140:143], v[192:195], v[36:39]
	v_mfma_f32_16x16x32_bf16 v[12:15], v[144:147], v[192:195], v[12:15]
	v_mfma_f32_16x16x32_bf16 v[208:211], v[148:151], v[192:195], v[208:211]
	v_mfma_f32_16x16x32_bf16 v[100:103], v[204:207], v[192:195], v[100:103]
	ds_read_b128 v[184:187], v212 offset:28672
	global_load_dwordx4 v[84:87], v66, s[92:93] offset:1024
	s_waitcnt lgkmcnt(4)
	v_mfma_f32_16x16x32_bf16 v[40:43], v[140:143], v[196:199], v[40:43]
	v_mfma_f32_16x16x32_bf16 v[16:19], v[144:147], v[196:199], v[16:19]
	v_mfma_f32_16x16x32_bf16 v[232:235], v[148:151], v[196:199], v[232:235]
	v_mfma_f32_16x16x32_bf16 v[104:107], v[204:207], v[196:199], v[104:107]
	ds_read_b128 v[192:195], v212 offset:30720
	global_load_dwordx4 v[88:91], v67, s[92:93] offset:1024
	s_add_u32 s84, s84, 0x800
	s_addc_u32 s85, s85, 0
	s_add_u32 s92, s92, 0x800
	s_addc_u32 s93, s93, 0
	s_waitcnt lgkmcnt(4)
	v_mfma_f32_16x16x32_bf16 v[44:47], v[140:143], v[200:203], v[44:47]
	v_mfma_f32_16x16x32_bf16 v[20:23], v[144:147], v[200:203], v[20:23]
	v_mfma_f32_16x16x32_bf16 v[236:239], v[148:151], v[200:203], v[236:239]
	v_mfma_f32_16x16x32_bf16 v[108:111], v[204:207], v[200:203], v[108:111]
	ds_read_b128 v[196:199], v75 offset:32768
	s_add_u32 m0, s88, 0
	s_nop 0
	global_load_lds_dwordx4 v68, s[86:87]
	s_waitcnt lgkmcnt(4)
	v_mfma_f32_16x16x32_bf16 v[48:51], v[140:143], v[176:179], v[48:51]
	v_mfma_f32_16x16x32_bf16 v[0:3], v[144:147], v[176:179], v[0:3]
	v_mfma_f32_16x16x32_bf16 v[240:243], v[148:151], v[176:179], v[240:243]
	v_mfma_f32_16x16x32_bf16 v[112:115], v[204:207], v[176:179], v[112:115]
	ds_read_b128 v[200:203], v75 offset:34816
	s_add_u32 m0, s88, 4096
	s_nop 0
	global_load_lds_dwordx4 v69, s[86:87]
	s_waitcnt lgkmcnt(4)
	v_mfma_f32_16x16x32_bf16 v[52:55], v[140:143], v[180:183], v[52:55]
	v_mfma_f32_16x16x32_bf16 v[8:11], v[144:147], v[180:183], v[8:11]
	v_mfma_f32_16x16x32_bf16 v[248:251], v[148:151], v[180:183], v[248:251]
	v_mfma_f32_16x16x32_bf16 v[116:119], v[204:207], v[180:183], v[116:119]
	ds_read_b128 v[176:179], v75 offset:36864
	s_add_u32 m0, s88, 8192
	s_nop 0
	global_load_lds_dwordx4 v71, s[86:87]
	s_waitcnt lgkmcnt(4)
	v_mfma_f32_16x16x32_bf16 v[56:59], v[140:143], v[184:187], v[56:59]
	v_mfma_f32_16x16x32_bf16 v[24:27], v[144:147], v[184:187], v[24:27]
	v_mfma_f32_16x16x32_bf16 v[252:255], v[148:151], v[184:187], v[252:255]
	v_mfma_f32_16x16x32_bf16 v[120:123], v[204:207], v[184:187], v[120:123]
	ds_read_b128 v[180:183], v75 offset:38912
	s_add_u32 m0, s88, 12288
	s_nop 0
	global_load_lds_dwordx4 v74, s[86:87]
	s_add_u32 s86, s86, 128
	s_addc_u32 s87, s87, 0
	s_waitcnt lgkmcnt(4)
	v_mfma_f32_16x16x32_bf16 v[60:63], v[140:143], v[192:195], v[60:63]
	v_mfma_f32_16x16x32_bf16 v[28:31], v[144:147], v[192:195], v[28:31]
	v_mfma_f32_16x16x32_bf16 v[92:95], v[148:151], v[192:195], v[92:95]
	v_mfma_f32_16x16x32_bf16 v[124:127], v[204:207], v[192:195], v[124:127]
	s_waitcnt vmcnt(8)
	ds_read_b128 v[184:187], v75 offset:40960
	global_load_dwordx4 v[140:143], v66, s[84:85] offset:0
	s_waitcnt lgkmcnt(4)
	v_mfma_f32_16x16x32_bf16 v[32:35], v[160:163], v[196:199], v[32:35]
	v_mfma_f32_16x16x32_bf16 v[4:7], v[164:167], v[196:199], v[4:7]
	v_mfma_f32_16x16x32_bf16 v[188:191], v[168:171], v[196:199], v[188:191]
	v_mfma_f32_16x16x32_bf16 v[96:99], v[172:175], v[196:199], v[96:99]
	ds_read_b128 v[192:195], v75 offset:43008
	global_load_dwordx4 v[144:147], v67, s[84:85] offset:0
	s_waitcnt lgkmcnt(4)
	v_mfma_f32_16x16x32_bf16 v[36:39], v[160:163], v[200:203], v[36:39]
	v_mfma_f32_16x16x32_bf16 v[12:15], v[164:167], v[200:203], v[12:15]
	v_mfma_f32_16x16x32_bf16 v[208:211], v[168:171], v[200:203], v[208:211]
	v_mfma_f32_16x16x32_bf16 v[100:103], v[172:175], v[200:203], v[100:103]
	ds_read_b128 v[196:199], v75 offset:45056
	global_load_dwordx4 v[148:151], v66, s[92:93] offset:0
	s_waitcnt lgkmcnt(4)
	v_mfma_f32_16x16x32_bf16 v[40:43], v[160:163], v[176:179], v[40:43]
	v_mfma_f32_16x16x32_bf16 v[16:19], v[164:167], v[176:179], v[16:19]
	v_mfma_f32_16x16x32_bf16 v[232:235], v[168:171], v[176:179], v[232:235]
	v_mfma_f32_16x16x32_bf16 v[104:107], v[172:175], v[176:179], v[104:107]
	ds_read_b128 v[200:203], v75 offset:47104
	global_load_dwordx4 v[204:207], v67, s[92:93] offset:0
	s_waitcnt lgkmcnt(4)
	v_mfma_f32_16x16x32_bf16 v[44:47], v[160:163], v[180:183], v[44:47]
	v_mfma_f32_16x16x32_bf16 v[20:23], v[164:167], v[180:183], v[20:23]
	v_mfma_f32_16x16x32_bf16 v[236:239], v[168:171], v[180:183], v[236:239]
	v_mfma_f32_16x16x32_bf16 v[108:111], v[172:175], v[180:183], v[108:111]
	ds_read_b128 v[176:179], v212 offset:32768
	s_waitcnt lgkmcnt(4)
	v_mfma_f32_16x16x32_bf16 v[48:51], v[160:163], v[184:187], v[48:51]
	v_mfma_f32_16x16x32_bf16 v[0:3], v[164:167], v[184:187], v[0:3]
	v_mfma_f32_16x16x32_bf16 v[240:243], v[168:171], v[184:187], v[240:243]
	v_mfma_f32_16x16x32_bf16 v[112:115], v[172:175], v[184:187], v[112:115]
	ds_read_b128 v[180:183], v212 offset:34816
	s_waitcnt lgkmcnt(4)
	v_mfma_f32_16x16x32_bf16 v[52:55], v[160:163], v[192:195], v[52:55]
	v_mfma_f32_16x16x32_bf16 v[8:11], v[164:167], v[192:195], v[8:11]
	v_mfma_f32_16x16x32_bf16 v[248:251], v[168:171], v[192:195], v[248:251]
	v_mfma_f32_16x16x32_bf16 v[116:119], v[172:175], v[192:195], v[116:119]
	ds_read_b128 v[184:187], v212 offset:36864
	s_waitcnt lgkmcnt(4)
	v_mfma_f32_16x16x32_bf16 v[56:59], v[160:163], v[196:199], v[56:59]
	v_mfma_f32_16x16x32_bf16 v[24:27], v[164:167], v[196:199], v[24:27]
	v_mfma_f32_16x16x32_bf16 v[252:255], v[168:171], v[196:199], v[252:255]
	v_mfma_f32_16x16x32_bf16 v[120:123], v[172:175], v[196:199], v[120:123]
	ds_read_b128 v[192:195], v212 offset:38912
	s_waitcnt lgkmcnt(4)
	v_mfma_f32_16x16x32_bf16 v[60:63], v[160:163], v[200:203], v[60:63]
	v_mfma_f32_16x16x32_bf16 v[28:31], v[164:167], v[200:203], v[28:31]
	v_mfma_f32_16x16x32_bf16 v[92:95], v[168:171], v[200:203], v[92:95]
	v_mfma_f32_16x16x32_bf16 v[124:127], v[172:175], v[200:203], v[124:127]
	s_waitcnt vmcnt(16)
	s_barrier
	s_waitcnt vmcnt(8)
	ds_read_b128 v[196:199], v212 offset:40960
	global_load_dwordx4 v[160:163], v66, s[84:85] offset:1024
	s_waitcnt lgkmcnt(4)
	v_mfma_f32_16x16x32_bf16 v[32:35], v[76:79], v[176:179], v[32:35]
	v_mfma_f32_16x16x32_bf16 v[4:7], v[80:83], v[176:179], v[4:7]
	v_mfma_f32_16x16x32_bf16 v[188:191], v[84:87], v[176:179], v[188:191]
	v_mfma_f32_16x16x32_bf16 v[96:99], v[88:91], v[176:179], v[96:99]
	ds_read_b128 v[200:203], v212 offset:43008
	global_load_dwordx4 v[164:167], v67, s[84:85] offset:1024
	s_waitcnt lgkmcnt(4)
	v_mfma_f32_16x16x32_bf16 v[36:39], v[76:79], v[180:183], v[36:39]
	v_mfma_f32_16x16x32_bf16 v[12:15], v[80:83], v[180:183], v[12:15]
	v_mfma_f32_16x16x32_bf16 v[208:211], v[84:87], v[180:183], v[208:211]
	v_mfma_f32_16x16x32_bf16 v[100:103], v[88:91], v[180:183], v[100:103]
	ds_read_b128 v[176:179], v212 offset:45056
	global_load_dwordx4 v[168:171], v66, s[92:93] offset:1024
	s_waitcnt lgkmcnt(4)
	v_mfma_f32_16x16x32_bf16 v[40:43], v[76:79], v[184:187], v[40:43]
	v_mfma_f32_16x16x32_bf16 v[16:19], v[80:83], v[184:187], v[16:19]
	v_mfma_f32_16x16x32_bf16 v[232:235], v[84:87], v[184:187], v[232:235]
	v_mfma_f32_16x16x32_bf16 v[104:107], v[88:91], v[184:187], v[104:107]
	ds_read_b128 v[180:183], v212 offset:47104
	global_load_dwordx4 v[172:175], v67, s[92:93] offset:1024
	s_add_u32 s84, s84, 0x800
	s_addc_u32 s85, s85, 0
	s_add_u32 s92, s92, 0x800
	s_addc_u32 s93, s93, 0
	s_waitcnt lgkmcnt(4)
	v_mfma_f32_16x16x32_bf16 v[44:47], v[76:79], v[192:195], v[44:47]
	v_mfma_f32_16x16x32_bf16 v[20:23], v[80:83], v[192:195], v[20:23]
	v_mfma_f32_16x16x32_bf16 v[236:239], v[84:87], v[192:195], v[236:239]
	v_mfma_f32_16x16x32_bf16 v[108:111], v[88:91], v[192:195], v[108:111]
	ds_read_b128 v[184:187], v75 offset:49152
	s_add_u32 m0, s88, 16384
	s_nop 0
	global_load_lds_dwordx4 v68, s[86:87]
	s_waitcnt lgkmcnt(4)
	v_mfma_f32_16x16x32_bf16 v[48:51], v[76:79], v[196:199], v[48:51]
	v_mfma_f32_16x16x32_bf16 v[0:3], v[80:83], v[196:199], v[0:3]
	v_mfma_f32_16x16x32_bf16 v[240:243], v[84:87], v[196:199], v[240:243]
	v_mfma_f32_16x16x32_bf16 v[112:115], v[88:91], v[196:199], v[112:115]
	ds_read_b128 v[192:195], v75 offset:51200
	s_add_u32 m0, s88, 20480
	s_nop 0
	global_load_lds_dwordx4 v69, s[86:87]
	s_waitcnt lgkmcnt(4)
	v_mfma_f32_16x16x32_bf16 v[52:55], v[76:79], v[200:203], v[52:55]
	v_mfma_f32_16x16x32_bf16 v[8:11], v[80:83], v[200:203], v[8:11]
	v_mfma_f32_16x16x32_bf16 v[248:251], v[84:87], v[200:203], v[248:251]
	v_mfma_f32_16x16x32_bf16 v[116:119], v[88:91], v[200:203], v[116:119]
	ds_read_b128 v[196:199], v75 offset:53248
	s_add_u32 m0, s88, 24576
	s_nop 0
	global_load_lds_dwordx4 v71, s[86:87]
	s_waitcnt lgkmcnt(4)
	v_mfma_f32_16x16x32_bf16 v[56:59], v[76:79], v[176:179], v[56:59]
	v_mfma_f32_16x16x32_bf16 v[24:27], v[80:83], v[176:179], v[24:27]
	v_mfma_f32_16x16x32_bf16 v[252:255], v[84:87], v[176:179], v[252:255]
	v_mfma_f32_16x16x32_bf16 v[120:123], v[88:91], v[176:179], v[120:123]
	ds_read_b128 v[200:203], v75 offset:55296
	s_add_u32 m0, s88, 28672
	s_nop 0
	global_load_lds_dwordx4 v74, s[86:87]
	s_add_u32 s86, s86, 128
	s_addc_u32 s87, s87, 0
	s_waitcnt lgkmcnt(4)
	v_mfma_f32_16x16x32_bf16 v[60:63], v[76:79], v[180:183], v[60:63]
	v_mfma_f32_16x16x32_bf16 v[28:31], v[80:83], v[180:183], v[28:31]
	v_mfma_f32_16x16x32_bf16 v[92:95], v[84:87], v[180:183], v[92:95]
	v_mfma_f32_16x16x32_bf16 v[124:127], v[88:91], v[180:183], v[124:127]
	s_waitcnt vmcnt(8)
	ds_read_b128 v[176:179], v75 offset:57344
	global_load_dwordx4 v[76:79], v66, s[84:85] offset:0
	s_waitcnt lgkmcnt(4)
	v_mfma_f32_16x16x32_bf16 v[32:35], v[140:143], v[184:187], v[32:35]
	v_mfma_f32_16x16x32_bf16 v[4:7], v[144:147], v[184:187], v[4:7]
	v_mfma_f32_16x16x32_bf16 v[188:191], v[148:151], v[184:187], v[188:191]
	v_mfma_f32_16x16x32_bf16 v[96:99], v[204:207], v[184:187], v[96:99]
	ds_read_b128 v[180:183], v75 offset:59392
	global_load_dwordx4 v[80:83], v67, s[84:85] offset:0
	s_waitcnt lgkmcnt(4)
	v_mfma_f32_16x16x32_bf16 v[36:39], v[140:143], v[192:195], v[36:39]
	v_mfma_f32_16x16x32_bf16 v[12:15], v[144:147], v[192:195], v[12:15]
	v_mfma_f32_16x16x32_bf16 v[208:211], v[148:151], v[192:195], v[208:211]
	v_mfma_f32_16x16x32_bf16 v[100:103], v[204:207], v[192:195], v[100:103]
	ds_read_b128 v[184:187], v75 offset:61440
	global_load_dwordx4 v[84:87], v66, s[92:93] offset:0
	s_waitcnt lgkmcnt(4)
	v_mfma_f32_16x16x32_bf16 v[40:43], v[140:143], v[196:199], v[40:43]
	v_mfma_f32_16x16x32_bf16 v[16:19], v[144:147], v[196:199], v[16:19]
	v_mfma_f32_16x16x32_bf16 v[232:235], v[148:151], v[196:199], v[232:235]
	v_mfma_f32_16x16x32_bf16 v[104:107], v[204:207], v[196:199], v[104:107]
	ds_read_b128 v[192:195], v75 offset:63488
	global_load_dwordx4 v[88:91], v67, s[92:93] offset:0
	s_waitcnt lgkmcnt(4)
	v_mfma_f32_16x16x32_bf16 v[44:47], v[140:143], v[200:203], v[44:47]
	v_mfma_f32_16x16x32_bf16 v[20:23], v[144:147], v[200:203], v[20:23]
	v_mfma_f32_16x16x32_bf16 v[236:239], v[148:151], v[200:203], v[236:239]
	v_mfma_f32_16x16x32_bf16 v[108:111], v[204:207], v[200:203], v[108:111]
	ds_read_b128 v[196:199], v212 offset:49152
	s_waitcnt lgkmcnt(4)
	v_mfma_f32_16x16x32_bf16 v[48:51], v[140:143], v[176:179], v[48:51]
	v_mfma_f32_16x16x32_bf16 v[0:3], v[144:147], v[176:179], v[0:3]
	v_mfma_f32_16x16x32_bf16 v[240:243], v[148:151], v[176:179], v[240:243]
	v_mfma_f32_16x16x32_bf16 v[112:115], v[204:207], v[176:179], v[112:115]
	ds_read_b128 v[200:203], v212 offset:51200
	s_waitcnt lgkmcnt(4)
	v_mfma_f32_16x16x32_bf16 v[52:55], v[140:143], v[180:183], v[52:55]
	v_mfma_f32_16x16x32_bf16 v[8:11], v[144:147], v[180:183], v[8:11]
	v_mfma_f32_16x16x32_bf16 v[248:251], v[148:151], v[180:183], v[248:251]
	v_mfma_f32_16x16x32_bf16 v[116:119], v[204:207], v[180:183], v[116:119]
	ds_read_b128 v[176:179], v212 offset:53248
	s_waitcnt lgkmcnt(4)
	v_mfma_f32_16x16x32_bf16 v[56:59], v[140:143], v[184:187], v[56:59]
	v_mfma_f32_16x16x32_bf16 v[24:27], v[144:147], v[184:187], v[24:27]
	v_mfma_f32_16x16x32_bf16 v[252:255], v[148:151], v[184:187], v[252:255]
	v_mfma_f32_16x16x32_bf16 v[120:123], v[204:207], v[184:187], v[120:123]
	ds_read_b128 v[180:183], v212 offset:55296
	s_waitcnt lgkmcnt(4)
	v_mfma_f32_16x16x32_bf16 v[60:63], v[140:143], v[192:195], v[60:63]
	v_mfma_f32_16x16x32_bf16 v[28:31], v[144:147], v[192:195], v[28:31]
	v_mfma_f32_16x16x32_bf16 v[92:95], v[148:151], v[192:195], v[92:95]
	v_mfma_f32_16x16x32_bf16 v[124:127], v[204:207], v[192:195], v[124:127]
	s_waitcnt vmcnt(16)
	s_barrier
	s_waitcnt vmcnt(8)
	ds_read_b128 v[184:187], v212 offset:57344
	global_load_dwordx4 v[140:143], v66, s[84:85] offset:1024
	s_waitcnt lgkmcnt(4)
	v_mfma_f32_16x16x32_bf16 v[32:35], v[160:163], v[196:199], v[32:35]
	v_mfma_f32_16x16x32_bf16 v[4:7], v[164:167], v[196:199], v[4:7]
	v_mfma_f32_16x16x32_bf16 v[188:191], v[168:171], v[196:199], v[188:191]
	v_mfma_f32_16x16x32_bf16 v[96:99], v[172:175], v[196:199], v[96:99]
	ds_read_b128 v[192:195], v212 offset:59392
	global_load_dwordx4 v[144:147], v67, s[84:85] offset:1024
	s_waitcnt lgkmcnt(4)
	v_mfma_f32_16x16x32_bf16 v[36:39], v[160:163], v[200:203], v[36:39]
	v_mfma_f32_16x16x32_bf16 v[12:15], v[164:167], v[200:203], v[12:15]
	v_mfma_f32_16x16x32_bf16 v[208:211], v[168:171], v[200:203], v[208:211]
	v_mfma_f32_16x16x32_bf16 v[100:103], v[172:175], v[200:203], v[100:103]
	ds_read_b128 v[196:199], v212 offset:61440
	global_load_dwordx4 v[148:151], v66, s[92:93] offset:1024
	s_waitcnt lgkmcnt(4)
	v_mfma_f32_16x16x32_bf16 v[40:43], v[160:163], v[176:179], v[40:43]
	v_mfma_f32_16x16x32_bf16 v[16:19], v[164:167], v[176:179], v[16:19]
	v_mfma_f32_16x16x32_bf16 v[232:235], v[168:171], v[176:179], v[232:235]
	v_mfma_f32_16x16x32_bf16 v[104:107], v[172:175], v[176:179], v[104:107]
	ds_read_b128 v[200:203], v212 offset:63488
	global_load_dwordx4 v[204:207], v67, s[92:93] offset:1024
	s_add_u32 s84, s84, 0x800
	s_addc_u32 s85, s85, 0
	s_add_u32 s92, s92, 0x800
	s_addc_u32 s93, s93, 0
	s_waitcnt lgkmcnt(4)
	v_mfma_f32_16x16x32_bf16 v[44:47], v[160:163], v[180:183], v[44:47]
	v_mfma_f32_16x16x32_bf16 v[20:23], v[164:167], v[180:183], v[20:23]
	v_mfma_f32_16x16x32_bf16 v[236:239], v[168:171], v[180:183], v[236:239]
	v_mfma_f32_16x16x32_bf16 v[108:111], v[172:175], v[180:183], v[108:111]
	ds_read_b128 v[176:179], v75 offset:0
	s_add_u32 m0, s88, 32768
	s_nop 0
	global_load_lds_dwordx4 v68, s[86:87]
	s_waitcnt lgkmcnt(4)
	v_mfma_f32_16x16x32_bf16 v[48:51], v[160:163], v[184:187], v[48:51]
	v_mfma_f32_16x16x32_bf16 v[0:3], v[164:167], v[184:187], v[0:3]
	v_mfma_f32_16x16x32_bf16 v[240:243], v[168:171], v[184:187], v[240:243]
	v_mfma_f32_16x16x32_bf16 v[112:115], v[172:175], v[184:187], v[112:115]
	ds_read_b128 v[180:183], v75 offset:2048
	s_add_u32 m0, s88, 36864
	s_nop 0
	global_load_lds_dwordx4 v69, s[86:87]
	s_waitcnt lgkmcnt(4)
	v_mfma_f32_16x16x32_bf16 v[52:55], v[160:163], v[192:195], v[52:55]
	v_mfma_f32_16x16x32_bf16 v[8:11], v[164:167], v[192:195], v[8:11]
	v_mfma_f32_16x16x32_bf16 v[248:251], v[168:171], v[192:195], v[248:251]
	v_mfma_f32_16x16x32_bf16 v[116:119], v[172:175], v[192:195], v[116:119]
	ds_read_b128 v[184:187], v75 offset:4096
	s_add_u32 m0, s88, 40960
	s_nop 0
	global_load_lds_dwordx4 v71, s[86:87]
	s_waitcnt lgkmcnt(4)
	v_mfma_f32_16x16x32_bf16 v[56:59], v[160:163], v[196:199], v[56:59]
	v_mfma_f32_16x16x32_bf16 v[24:27], v[164:167], v[196:199], v[24:27]
	v_mfma_f32_16x16x32_bf16 v[252:255], v[168:171], v[196:199], v[252:255]
	v_mfma_f32_16x16x32_bf16 v[120:123], v[172:175], v[196:199], v[120:123]
	ds_read_b128 v[192:195], v75 offset:6144
	s_add_u32 m0, s88, 45056
	s_nop 0
	global_load_lds_dwordx4 v74, s[86:87]
	s_add_u32 s86, s86, 128
	s_addc_u32 s87, s87, 0
	s_waitcnt lgkmcnt(4)
	v_mfma_f32_16x16x32_bf16 v[60:63], v[160:163], v[200:203], v[60:63]
	v_mfma_f32_16x16x32_bf16 v[28:31], v[164:167], v[200:203], v[28:31]
	v_mfma_f32_16x16x32_bf16 v[92:95], v[168:171], v[200:203], v[92:95]
	v_mfma_f32_16x16x32_bf16 v[124:127], v[172:175], v[200:203], v[124:127]
	s_waitcnt vmcnt(8)
	ds_read_b128 v[196:199], v75 offset:8192
	global_load_dwordx4 v[160:163], v66, s[84:85] offset:0
	s_waitcnt lgkmcnt(4)
	v_mfma_f32_16x16x32_bf16 v[32:35], v[76:79], v[176:179], v[32:35]
	v_mfma_f32_16x16x32_bf16 v[4:7], v[80:83], v[176:179], v[4:7]
	v_mfma_f32_16x16x32_bf16 v[188:191], v[84:87], v[176:179], v[188:191]
	v_mfma_f32_16x16x32_bf16 v[96:99], v[88:91], v[176:179], v[96:99]
	ds_read_b128 v[200:203], v75 offset:10240
	global_load_dwordx4 v[164:167], v67, s[84:85] offset:0
	s_waitcnt lgkmcnt(4)
	v_mfma_f32_16x16x32_bf16 v[36:39], v[76:79], v[180:183], v[36:39]
	v_mfma_f32_16x16x32_bf16 v[12:15], v[80:83], v[180:183], v[12:15]
	v_mfma_f32_16x16x32_bf16 v[208:211], v[84:87], v[180:183], v[208:211]
	v_mfma_f32_16x16x32_bf16 v[100:103], v[88:91], v[180:183], v[100:103]
	ds_read_b128 v[176:179], v75 offset:12288
	global_load_dwordx4 v[168:171], v66, s[92:93] offset:0
	s_waitcnt lgkmcnt(4)
	v_mfma_f32_16x16x32_bf16 v[40:43], v[76:79], v[184:187], v[40:43]
	v_mfma_f32_16x16x32_bf16 v[16:19], v[80:83], v[184:187], v[16:19]
	v_mfma_f32_16x16x32_bf16 v[232:235], v[84:87], v[184:187], v[232:235]
	v_mfma_f32_16x16x32_bf16 v[104:107], v[88:91], v[184:187], v[104:107]
	ds_read_b128 v[180:183], v75 offset:14336
	global_load_dwordx4 v[172:175], v67, s[92:93] offset:0
	s_waitcnt lgkmcnt(4)
	v_mfma_f32_16x16x32_bf16 v[44:47], v[76:79], v[192:195], v[44:47]
	v_mfma_f32_16x16x32_bf16 v[20:23], v[80:83], v[192:195], v[20:23]
	v_mfma_f32_16x16x32_bf16 v[236:239], v[84:87], v[192:195], v[236:239]
	v_mfma_f32_16x16x32_bf16 v[108:111], v[88:91], v[192:195], v[108:111]
	ds_read_b128 v[184:187], v212 offset:0
	s_waitcnt lgkmcnt(4)
	v_mfma_f32_16x16x32_bf16 v[48:51], v[76:79], v[196:199], v[48:51]
	v_mfma_f32_16x16x32_bf16 v[0:3], v[80:83], v[196:199], v[0:3]
	v_mfma_f32_16x16x32_bf16 v[240:243], v[84:87], v[196:199], v[240:243]
	v_mfma_f32_16x16x32_bf16 v[112:115], v[88:91], v[196:199], v[112:115]
	ds_read_b128 v[192:195], v212 offset:2048
	s_waitcnt lgkmcnt(4)
	v_mfma_f32_16x16x32_bf16 v[52:55], v[76:79], v[200:203], v[52:55]
	v_mfma_f32_16x16x32_bf16 v[8:11], v[80:83], v[200:203], v[8:11]
	v_mfma_f32_16x16x32_bf16 v[248:251], v[84:87], v[200:203], v[248:251]
	v_mfma_f32_16x16x32_bf16 v[116:119], v[88:91], v[200:203], v[116:119]
	ds_read_b128 v[196:199], v212 offset:4096
	s_waitcnt lgkmcnt(4)
	v_mfma_f32_16x16x32_bf16 v[56:59], v[76:79], v[176:179], v[56:59]
	v_mfma_f32_16x16x32_bf16 v[24:27], v[80:83], v[176:179], v[24:27]
	v_mfma_f32_16x16x32_bf16 v[252:255], v[84:87], v[176:179], v[252:255]
	v_mfma_f32_16x16x32_bf16 v[120:123], v[88:91], v[176:179], v[120:123]
	ds_read_b128 v[200:203], v212 offset:6144
	s_waitcnt lgkmcnt(4)
	v_mfma_f32_16x16x32_bf16 v[60:63], v[76:79], v[180:183], v[60:63]
	v_mfma_f32_16x16x32_bf16 v[28:31], v[80:83], v[180:183], v[28:31]
	v_mfma_f32_16x16x32_bf16 v[92:95], v[84:87], v[180:183], v[92:95]
	v_mfma_f32_16x16x32_bf16 v[124:127], v[88:91], v[180:183], v[124:127]
	s_waitcnt vmcnt(16)
	s_barrier
	s_waitcnt vmcnt(8)
	ds_read_b128 v[176:179], v212 offset:8192
	global_load_dwordx4 v[76:79], v66, s[84:85] offset:1024
	s_waitcnt lgkmcnt(4)
	v_mfma_f32_16x16x32_bf16 v[32:35], v[140:143], v[184:187], v[32:35]
	v_mfma_f32_16x16x32_bf16 v[4:7], v[144:147], v[184:187], v[4:7]
	v_mfma_f32_16x16x32_bf16 v[188:191], v[148:151], v[184:187], v[188:191]
	v_mfma_f32_16x16x32_bf16 v[96:99], v[204:207], v[184:187], v[96:99]
	ds_read_b128 v[180:183], v212 offset:10240
	global_load_dwordx4 v[80:83], v67, s[84:85] offset:1024
	s_waitcnt lgkmcnt(4)
	v_mfma_f32_16x16x32_bf16 v[36:39], v[140:143], v[192:195], v[36:39]
	v_mfma_f32_16x16x32_bf16 v[12:15], v[144:147], v[192:195], v[12:15]
	v_mfma_f32_16x16x32_bf16 v[208:211], v[148:151], v[192:195], v[208:211]
	v_mfma_f32_16x16x32_bf16 v[100:103], v[204:207], v[192:195], v[100:103]
	ds_read_b128 v[184:187], v212 offset:12288
	global_load_dwordx4 v[84:87], v66, s[92:93] offset:1024
	s_waitcnt lgkmcnt(4)
	v_mfma_f32_16x16x32_bf16 v[40:43], v[140:143], v[196:199], v[40:43]
	v_mfma_f32_16x16x32_bf16 v[16:19], v[144:147], v[196:199], v[16:19]
	v_mfma_f32_16x16x32_bf16 v[232:235], v[148:151], v[196:199], v[232:235]
	v_mfma_f32_16x16x32_bf16 v[104:107], v[204:207], v[196:199], v[104:107]
	ds_read_b128 v[192:195], v212 offset:14336
	global_load_dwordx4 v[88:91], v67, s[92:93] offset:1024
	s_add_u32 s84, s84, 0x800
	s_addc_u32 s85, s85, 0
	s_add_u32 s92, s92, 0x800
	s_addc_u32 s93, s93, 0
	s_waitcnt lgkmcnt(4)
	v_mfma_f32_16x16x32_bf16 v[44:47], v[140:143], v[200:203], v[44:47]
	v_mfma_f32_16x16x32_bf16 v[20:23], v[144:147], v[200:203], v[20:23]
	v_mfma_f32_16x16x32_bf16 v[236:239], v[148:151], v[200:203], v[236:239]
	v_mfma_f32_16x16x32_bf16 v[108:111], v[204:207], v[200:203], v[108:111]
	ds_read_b128 v[196:199], v75 offset:16384
	s_add_u32 m0, s88, 49152
	s_nop 0
	global_load_lds_dwordx4 v68, s[86:87]
	s_waitcnt lgkmcnt(4)
	v_mfma_f32_16x16x32_bf16 v[48:51], v[140:143], v[176:179], v[48:51]
	v_mfma_f32_16x16x32_bf16 v[0:3], v[144:147], v[176:179], v[0:3]
	v_mfma_f32_16x16x32_bf16 v[240:243], v[148:151], v[176:179], v[240:243]
	v_mfma_f32_16x16x32_bf16 v[112:115], v[204:207], v[176:179], v[112:115]
	ds_read_b128 v[200:203], v75 offset:18432
	s_add_u32 m0, s88, 53248
	s_nop 0
	global_load_lds_dwordx4 v69, s[86:87]
	s_waitcnt lgkmcnt(4)
	v_mfma_f32_16x16x32_bf16 v[52:55], v[140:143], v[180:183], v[52:55]
	v_mfma_f32_16x16x32_bf16 v[8:11], v[144:147], v[180:183], v[8:11]
	v_mfma_f32_16x16x32_bf16 v[248:251], v[148:151], v[180:183], v[248:251]
	v_mfma_f32_16x16x32_bf16 v[116:119], v[204:207], v[180:183], v[116:119]
	ds_read_b128 v[176:179], v75 offset:20480
	s_add_u32 m0, s88, 57344
	s_nop 0
	global_load_lds_dwordx4 v71, s[86:87]
	s_waitcnt lgkmcnt(4)
	v_mfma_f32_16x16x32_bf16 v[56:59], v[140:143], v[184:187], v[56:59]
	v_mfma_f32_16x16x32_bf16 v[24:27], v[144:147], v[184:187], v[24:27]
	v_mfma_f32_16x16x32_bf16 v[252:255], v[148:151], v[184:187], v[252:255]
	v_mfma_f32_16x16x32_bf16 v[120:123], v[204:207], v[184:187], v[120:123]
	ds_read_b128 v[180:183], v75 offset:22528
	s_add_u32 m0, s88, 61440
	s_nop 0
	global_load_lds_dwordx4 v74, s[86:87]
	s_add_u32 s86, s86, 128
	s_addc_u32 s87, s87, 0
	s_waitcnt lgkmcnt(4)
	v_mfma_f32_16x16x32_bf16 v[60:63], v[140:143], v[192:195], v[60:63]
	v_mfma_f32_16x16x32_bf16 v[28:31], v[144:147], v[192:195], v[28:31]
	v_mfma_f32_16x16x32_bf16 v[92:95], v[148:151], v[192:195], v[92:95]
	v_mfma_f32_16x16x32_bf16 v[124:127], v[204:207], v[192:195], v[124:127]
	s_waitcnt vmcnt(8)
	ds_read_b128 v[184:187], v75 offset:24576
	global_load_dwordx4 v[140:143], v66, s[84:85] offset:0
	s_waitcnt lgkmcnt(4)
	v_mfma_f32_16x16x32_bf16 v[32:35], v[160:163], v[196:199], v[32:35]
	v_mfma_f32_16x16x32_bf16 v[4:7], v[164:167], v[196:199], v[4:7]
	v_mfma_f32_16x16x32_bf16 v[188:191], v[168:171], v[196:199], v[188:191]
	v_mfma_f32_16x16x32_bf16 v[96:99], v[172:175], v[196:199], v[96:99]
	ds_read_b128 v[192:195], v75 offset:26624
	global_load_dwordx4 v[144:147], v67, s[84:85] offset:0
	s_waitcnt lgkmcnt(4)
	v_mfma_f32_16x16x32_bf16 v[36:39], v[160:163], v[200:203], v[36:39]
	v_mfma_f32_16x16x32_bf16 v[12:15], v[164:167], v[200:203], v[12:15]
	v_mfma_f32_16x16x32_bf16 v[208:211], v[168:171], v[200:203], v[208:211]
	v_mfma_f32_16x16x32_bf16 v[100:103], v[172:175], v[200:203], v[100:103]
	ds_read_b128 v[196:199], v75 offset:28672
	global_load_dwordx4 v[148:151], v66, s[92:93] offset:0
	s_waitcnt lgkmcnt(4)
	v_mfma_f32_16x16x32_bf16 v[40:43], v[160:163], v[176:179], v[40:43]
	v_mfma_f32_16x16x32_bf16 v[16:19], v[164:167], v[176:179], v[16:19]
	v_mfma_f32_16x16x32_bf16 v[232:235], v[168:171], v[176:179], v[232:235]
	v_mfma_f32_16x16x32_bf16 v[104:107], v[172:175], v[176:179], v[104:107]
	ds_read_b128 v[200:203], v75 offset:30720
	global_load_dwordx4 v[204:207], v67, s[92:93] offset:0
	s_waitcnt lgkmcnt(4)
	v_mfma_f32_16x16x32_bf16 v[44:47], v[160:163], v[180:183], v[44:47]
	v_mfma_f32_16x16x32_bf16 v[20:23], v[164:167], v[180:183], v[20:23]
	v_mfma_f32_16x16x32_bf16 v[236:239], v[168:171], v[180:183], v[236:239]
	v_mfma_f32_16x16x32_bf16 v[108:111], v[172:175], v[180:183], v[108:111]
	ds_read_b128 v[176:179], v212 offset:16384
	s_waitcnt lgkmcnt(4)
	v_mfma_f32_16x16x32_bf16 v[48:51], v[160:163], v[184:187], v[48:51]
	v_mfma_f32_16x16x32_bf16 v[0:3], v[164:167], v[184:187], v[0:3]
	v_mfma_f32_16x16x32_bf16 v[240:243], v[168:171], v[184:187], v[240:243]
	v_mfma_f32_16x16x32_bf16 v[112:115], v[172:175], v[184:187], v[112:115]
	ds_read_b128 v[180:183], v212 offset:18432
	s_waitcnt lgkmcnt(4)
	v_mfma_f32_16x16x32_bf16 v[52:55], v[160:163], v[192:195], v[52:55]
	v_mfma_f32_16x16x32_bf16 v[8:11], v[164:167], v[192:195], v[8:11]
	v_mfma_f32_16x16x32_bf16 v[248:251], v[168:171], v[192:195], v[248:251]
	v_mfma_f32_16x16x32_bf16 v[116:119], v[172:175], v[192:195], v[116:119]
	ds_read_b128 v[184:187], v212 offset:20480
	s_waitcnt lgkmcnt(4)
	v_mfma_f32_16x16x32_bf16 v[56:59], v[160:163], v[196:199], v[56:59]
	v_mfma_f32_16x16x32_bf16 v[24:27], v[164:167], v[196:199], v[24:27]
	v_mfma_f32_16x16x32_bf16 v[252:255], v[168:171], v[196:199], v[252:255]
	v_mfma_f32_16x16x32_bf16 v[120:123], v[172:175], v[196:199], v[120:123]
	ds_read_b128 v[192:195], v212 offset:22528
	s_waitcnt lgkmcnt(4)
	v_mfma_f32_16x16x32_bf16 v[60:63], v[160:163], v[200:203], v[60:63]
	v_mfma_f32_16x16x32_bf16 v[28:31], v[164:167], v[200:203], v[28:31]
	v_mfma_f32_16x16x32_bf16 v[92:95], v[168:171], v[200:203], v[92:95]
	v_mfma_f32_16x16x32_bf16 v[124:127], v[172:175], v[200:203], v[124:127]
	s_waitcnt vmcnt(16)
	s_barrier
	s_waitcnt vmcnt(8)
	ds_read_b128 v[196:199], v212 offset:24576
	global_load_dwordx4 v[160:163], v66, s[84:85] offset:1024
	s_waitcnt lgkmcnt(4)
	v_mfma_f32_16x16x32_bf16 v[32:35], v[76:79], v[176:179], v[32:35]
	v_mfma_f32_16x16x32_bf16 v[4:7], v[80:83], v[176:179], v[4:7]
	v_mfma_f32_16x16x32_bf16 v[188:191], v[84:87], v[176:179], v[188:191]
	v_mfma_f32_16x16x32_bf16 v[96:99], v[88:91], v[176:179], v[96:99]
	ds_read_b128 v[200:203], v212 offset:26624
	global_load_dwordx4 v[164:167], v67, s[84:85] offset:1024
	s_waitcnt lgkmcnt(4)
	v_mfma_f32_16x16x32_bf16 v[36:39], v[76:79], v[180:183], v[36:39]
	v_mfma_f32_16x16x32_bf16 v[12:15], v[80:83], v[180:183], v[12:15]
	v_mfma_f32_16x16x32_bf16 v[208:211], v[84:87], v[180:183], v[208:211]
	v_mfma_f32_16x16x32_bf16 v[100:103], v[88:91], v[180:183], v[100:103]
	ds_read_b128 v[176:179], v212 offset:28672
	global_load_dwordx4 v[168:171], v66, s[92:93] offset:1024
	s_waitcnt lgkmcnt(4)
	v_mfma_f32_16x16x32_bf16 v[40:43], v[76:79], v[184:187], v[40:43]
	v_mfma_f32_16x16x32_bf16 v[16:19], v[80:83], v[184:187], v[16:19]
	v_mfma_f32_16x16x32_bf16 v[232:235], v[84:87], v[184:187], v[232:235]
	v_mfma_f32_16x16x32_bf16 v[104:107], v[88:91], v[184:187], v[104:107]
	ds_read_b128 v[180:183], v212 offset:30720
	global_load_dwordx4 v[172:175], v67, s[92:93] offset:1024
	s_add_u32 s84, s84, 0x800
	s_addc_u32 s85, s85, 0
	s_add_u32 s92, s92, 0x800
	s_addc_u32 s93, s93, 0
	s_waitcnt lgkmcnt(4)
	v_mfma_f32_16x16x32_bf16 v[44:47], v[76:79], v[192:195], v[44:47]
	v_mfma_f32_16x16x32_bf16 v[20:23], v[80:83], v[192:195], v[20:23]
	v_mfma_f32_16x16x32_bf16 v[236:239], v[84:87], v[192:195], v[236:239]
	v_mfma_f32_16x16x32_bf16 v[108:111], v[88:91], v[192:195], v[108:111]
	ds_read_b128 v[184:187], v75 offset:32768
	s_waitcnt lgkmcnt(4)
	v_mfma_f32_16x16x32_bf16 v[48:51], v[76:79], v[196:199], v[48:51]
	v_mfma_f32_16x16x32_bf16 v[0:3], v[80:83], v[196:199], v[0:3]
	v_mfma_f32_16x16x32_bf16 v[240:243], v[84:87], v[196:199], v[240:243]
	v_mfma_f32_16x16x32_bf16 v[112:115], v[88:91], v[196:199], v[112:115]
	ds_read_b128 v[192:195], v75 offset:34816
	s_waitcnt lgkmcnt(4)
	v_mfma_f32_16x16x32_bf16 v[52:55], v[76:79], v[200:203], v[52:55]
	v_mfma_f32_16x16x32_bf16 v[8:11], v[80:83], v[200:203], v[8:11]
	v_mfma_f32_16x16x32_bf16 v[248:251], v[84:87], v[200:203], v[248:251]
	v_mfma_f32_16x16x32_bf16 v[116:119], v[88:91], v[200:203], v[116:119]
	ds_read_b128 v[196:199], v75 offset:36864
	s_waitcnt lgkmcnt(4)
	v_mfma_f32_16x16x32_bf16 v[56:59], v[76:79], v[176:179], v[56:59]
	v_mfma_f32_16x16x32_bf16 v[24:27], v[80:83], v[176:179], v[24:27]
	v_mfma_f32_16x16x32_bf16 v[252:255], v[84:87], v[176:179], v[252:255]
	v_mfma_f32_16x16x32_bf16 v[120:123], v[88:91], v[176:179], v[120:123]
	ds_read_b128 v[200:203], v75 offset:38912
	s_waitcnt lgkmcnt(4)
	v_mfma_f32_16x16x32_bf16 v[60:63], v[76:79], v[180:183], v[60:63]
	v_mfma_f32_16x16x32_bf16 v[28:31], v[80:83], v[180:183], v[28:31]
	v_mfma_f32_16x16x32_bf16 v[92:95], v[84:87], v[180:183], v[92:95]
	v_mfma_f32_16x16x32_bf16 v[124:127], v[88:91], v[180:183], v[124:127]
	s_waitcnt vmcnt(4)
	ds_read_b128 v[176:179], v75 offset:40960
	global_load_dwordx4 v[76:79], v66, s[84:85] offset:0
	s_waitcnt lgkmcnt(4)
	v_mfma_f32_16x16x32_bf16 v[32:35], v[140:143], v[184:187], v[32:35]
	v_mfma_f32_16x16x32_bf16 v[4:7], v[144:147], v[184:187], v[4:7]
	v_mfma_f32_16x16x32_bf16 v[188:191], v[148:151], v[184:187], v[188:191]
	v_mfma_f32_16x16x32_bf16 v[96:99], v[204:207], v[184:187], v[96:99]
	ds_read_b128 v[180:183], v75 offset:43008
	global_load_dwordx4 v[80:83], v67, s[84:85] offset:0
	s_waitcnt lgkmcnt(4)
	v_mfma_f32_16x16x32_bf16 v[36:39], v[140:143], v[192:195], v[36:39]
	v_mfma_f32_16x16x32_bf16 v[12:15], v[144:147], v[192:195], v[12:15]
	v_mfma_f32_16x16x32_bf16 v[208:211], v[148:151], v[192:195], v[208:211]
	v_mfma_f32_16x16x32_bf16 v[100:103], v[204:207], v[192:195], v[100:103]
	ds_read_b128 v[184:187], v75 offset:45056
	global_load_dwordx4 v[84:87], v66, s[92:93] offset:0
	s_waitcnt lgkmcnt(4)
	v_mfma_f32_16x16x32_bf16 v[40:43], v[140:143], v[196:199], v[40:43]
	v_mfma_f32_16x16x32_bf16 v[16:19], v[144:147], v[196:199], v[16:19]
	v_mfma_f32_16x16x32_bf16 v[232:235], v[148:151], v[196:199], v[232:235]
	v_mfma_f32_16x16x32_bf16 v[104:107], v[204:207], v[196:199], v[104:107]
	ds_read_b128 v[192:195], v75 offset:47104
	global_load_dwordx4 v[88:91], v67, s[92:93] offset:0
	s_waitcnt lgkmcnt(4)
	v_mfma_f32_16x16x32_bf16 v[44:47], v[140:143], v[200:203], v[44:47]
	v_mfma_f32_16x16x32_bf16 v[20:23], v[144:147], v[200:203], v[20:23]
	v_mfma_f32_16x16x32_bf16 v[236:239], v[148:151], v[200:203], v[236:239]
	v_mfma_f32_16x16x32_bf16 v[108:111], v[204:207], v[200:203], v[108:111]
	ds_read_b128 v[196:199], v212 offset:32768
	s_waitcnt lgkmcnt(4)
	v_mfma_f32_16x16x32_bf16 v[48:51], v[140:143], v[176:179], v[48:51]
	v_mfma_f32_16x16x32_bf16 v[0:3], v[144:147], v[176:179], v[0:3]
	v_mfma_f32_16x16x32_bf16 v[240:243], v[148:151], v[176:179], v[240:243]
	v_mfma_f32_16x16x32_bf16 v[112:115], v[204:207], v[176:179], v[112:115]
	ds_read_b128 v[200:203], v212 offset:34816
	s_waitcnt lgkmcnt(4)
	v_mfma_f32_16x16x32_bf16 v[52:55], v[140:143], v[180:183], v[52:55]
	v_mfma_f32_16x16x32_bf16 v[8:11], v[144:147], v[180:183], v[8:11]
	v_mfma_f32_16x16x32_bf16 v[248:251], v[148:151], v[180:183], v[248:251]
	v_mfma_f32_16x16x32_bf16 v[116:119], v[204:207], v[180:183], v[116:119]
	ds_read_b128 v[176:179], v212 offset:36864
	s_waitcnt lgkmcnt(4)
	v_mfma_f32_16x16x32_bf16 v[56:59], v[140:143], v[184:187], v[56:59]
	v_mfma_f32_16x16x32_bf16 v[24:27], v[144:147], v[184:187], v[24:27]
	v_mfma_f32_16x16x32_bf16 v[252:255], v[148:151], v[184:187], v[252:255]
	v_mfma_f32_16x16x32_bf16 v[120:123], v[204:207], v[184:187], v[120:123]
	ds_read_b128 v[180:183], v212 offset:38912
	s_waitcnt lgkmcnt(4)
	v_mfma_f32_16x16x32_bf16 v[60:63], v[140:143], v[192:195], v[60:63]
	v_mfma_f32_16x16x32_bf16 v[28:31], v[144:147], v[192:195], v[28:31]
	v_mfma_f32_16x16x32_bf16 v[92:95], v[148:151], v[192:195], v[92:95]
	v_mfma_f32_16x16x32_bf16 v[124:127], v[204:207], v[192:195], v[124:127]
	s_waitcnt vmcnt(12)
	s_barrier
	s_waitcnt vmcnt(4)
	ds_read_b128 v[184:187], v212 offset:40960
	global_load_dwordx4 v[140:143], v66, s[84:85] offset:1024
	s_waitcnt lgkmcnt(4)
	v_mfma_f32_16x16x32_bf16 v[32:35], v[160:163], v[196:199], v[32:35]
	v_mfma_f32_16x16x32_bf16 v[4:7], v[164:167], v[196:199], v[4:7]
	v_mfma_f32_16x16x32_bf16 v[188:191], v[168:171], v[196:199], v[188:191]
	v_mfma_f32_16x16x32_bf16 v[96:99], v[172:175], v[196:199], v[96:99]
	ds_read_b128 v[192:195], v212 offset:43008
	global_load_dwordx4 v[144:147], v67, s[84:85] offset:1024
	s_waitcnt lgkmcnt(4)
	v_mfma_f32_16x16x32_bf16 v[36:39], v[160:163], v[200:203], v[36:39]
	v_mfma_f32_16x16x32_bf16 v[12:15], v[164:167], v[200:203], v[12:15]
	v_mfma_f32_16x16x32_bf16 v[208:211], v[168:171], v[200:203], v[208:211]
	v_mfma_f32_16x16x32_bf16 v[100:103], v[172:175], v[200:203], v[100:103]
	ds_read_b128 v[196:199], v212 offset:45056
	global_load_dwordx4 v[148:151], v66, s[92:93] offset:1024
	s_waitcnt lgkmcnt(4)
	v_mfma_f32_16x16x32_bf16 v[40:43], v[160:163], v[176:179], v[40:43]
	v_mfma_f32_16x16x32_bf16 v[16:19], v[164:167], v[176:179], v[16:19]
	v_mfma_f32_16x16x32_bf16 v[232:235], v[168:171], v[176:179], v[232:235]
	v_mfma_f32_16x16x32_bf16 v[104:107], v[172:175], v[176:179], v[104:107]
	ds_read_b128 v[200:203], v212 offset:47104
	global_load_dwordx4 v[204:207], v67, s[92:93] offset:1024
	s_add_u32 s84, s84, 0x800
	s_addc_u32 s85, s85, 0
	s_add_u32 s92, s92, 0x800
	s_addc_u32 s93, s93, 0
	s_waitcnt lgkmcnt(4)
	v_mfma_f32_16x16x32_bf16 v[44:47], v[160:163], v[180:183], v[44:47]
	v_mfma_f32_16x16x32_bf16 v[20:23], v[164:167], v[180:183], v[20:23]
	v_mfma_f32_16x16x32_bf16 v[236:239], v[168:171], v[180:183], v[236:239]
	v_mfma_f32_16x16x32_bf16 v[108:111], v[172:175], v[180:183], v[108:111]
	ds_read_b128 v[176:179], v75 offset:49152
	s_waitcnt lgkmcnt(4)
	v_mfma_f32_16x16x32_bf16 v[48:51], v[160:163], v[184:187], v[48:51]
	v_mfma_f32_16x16x32_bf16 v[0:3], v[164:167], v[184:187], v[0:3]
	v_mfma_f32_16x16x32_bf16 v[240:243], v[168:171], v[184:187], v[240:243]
	v_mfma_f32_16x16x32_bf16 v[112:115], v[172:175], v[184:187], v[112:115]
	ds_read_b128 v[180:183], v75 offset:51200
	s_waitcnt lgkmcnt(4)
	v_mfma_f32_16x16x32_bf16 v[52:55], v[160:163], v[192:195], v[52:55]
	v_mfma_f32_16x16x32_bf16 v[8:11], v[164:167], v[192:195], v[8:11]
	v_mfma_f32_16x16x32_bf16 v[248:251], v[168:171], v[192:195], v[248:251]
	v_mfma_f32_16x16x32_bf16 v[116:119], v[172:175], v[192:195], v[116:119]
	ds_read_b128 v[184:187], v75 offset:53248
	s_waitcnt lgkmcnt(4)
	v_mfma_f32_16x16x32_bf16 v[56:59], v[160:163], v[196:199], v[56:59]
	v_mfma_f32_16x16x32_bf16 v[24:27], v[164:167], v[196:199], v[24:27]
	v_mfma_f32_16x16x32_bf16 v[252:255], v[168:171], v[196:199], v[252:255]
	v_mfma_f32_16x16x32_bf16 v[120:123], v[172:175], v[196:199], v[120:123]
	ds_read_b128 v[192:195], v75 offset:55296
	s_waitcnt lgkmcnt(4)
	v_mfma_f32_16x16x32_bf16 v[60:63], v[160:163], v[200:203], v[60:63]
	v_mfma_f32_16x16x32_bf16 v[28:31], v[164:167], v[200:203], v[28:31]
	v_mfma_f32_16x16x32_bf16 v[92:95], v[168:171], v[200:203], v[92:95]
	v_mfma_f32_16x16x32_bf16 v[124:127], v[172:175], v[200:203], v[124:127]
	s_waitcnt vmcnt(4)
	ds_read_b128 v[196:199], v75 offset:57344
	s_waitcnt lgkmcnt(4)
	v_mfma_f32_16x16x32_bf16 v[32:35], v[76:79], v[176:179], v[32:35]
	v_mfma_f32_16x16x32_bf16 v[4:7], v[80:83], v[176:179], v[4:7]
	v_mfma_f32_16x16x32_bf16 v[188:191], v[84:87], v[176:179], v[188:191]
	v_mfma_f32_16x16x32_bf16 v[96:99], v[88:91], v[176:179], v[96:99]
	ds_read_b128 v[200:203], v75 offset:59392
	s_waitcnt lgkmcnt(4)
	v_mfma_f32_16x16x32_bf16 v[36:39], v[76:79], v[180:183], v[36:39]
	v_mfma_f32_16x16x32_bf16 v[12:15], v[80:83], v[180:183], v[12:15]
	v_mfma_f32_16x16x32_bf16 v[208:211], v[84:87], v[180:183], v[208:211]
	v_mfma_f32_16x16x32_bf16 v[100:103], v[88:91], v[180:183], v[100:103]
	ds_read_b128 v[176:179], v75 offset:61440
	s_waitcnt lgkmcnt(4)
	v_mfma_f32_16x16x32_bf16 v[40:43], v[76:79], v[184:187], v[40:43]
	v_mfma_f32_16x16x32_bf16 v[16:19], v[80:83], v[184:187], v[16:19]
	v_mfma_f32_16x16x32_bf16 v[232:235], v[84:87], v[184:187], v[232:235]
	v_mfma_f32_16x16x32_bf16 v[104:107], v[88:91], v[184:187], v[104:107]
	ds_read_b128 v[180:183], v75 offset:63488
	s_waitcnt lgkmcnt(4)
	v_mfma_f32_16x16x32_bf16 v[44:47], v[76:79], v[192:195], v[44:47]
	v_mfma_f32_16x16x32_bf16 v[20:23], v[80:83], v[192:195], v[20:23]
	v_mfma_f32_16x16x32_bf16 v[236:239], v[84:87], v[192:195], v[236:239]
	v_mfma_f32_16x16x32_bf16 v[108:111], v[88:91], v[192:195], v[108:111]
	ds_read_b128 v[184:187], v212 offset:49152
	s_waitcnt lgkmcnt(4)
	v_mfma_f32_16x16x32_bf16 v[48:51], v[76:79], v[196:199], v[48:51]
	v_mfma_f32_16x16x32_bf16 v[0:3], v[80:83], v[196:199], v[0:3]
	v_mfma_f32_16x16x32_bf16 v[240:243], v[84:87], v[196:199], v[240:243]
	v_mfma_f32_16x16x32_bf16 v[112:115], v[88:91], v[196:199], v[112:115]
	ds_read_b128 v[192:195], v212 offset:51200
	s_waitcnt lgkmcnt(4)
	v_mfma_f32_16x16x32_bf16 v[52:55], v[76:79], v[200:203], v[52:55]
	v_mfma_f32_16x16x32_bf16 v[8:11], v[80:83], v[200:203], v[8:11]
	v_mfma_f32_16x16x32_bf16 v[248:251], v[84:87], v[200:203], v[248:251]
	v_mfma_f32_16x16x32_bf16 v[116:119], v[88:91], v[200:203], v[116:119]
	ds_read_b128 v[196:199], v212 offset:53248
	s_waitcnt lgkmcnt(4)
	v_mfma_f32_16x16x32_bf16 v[56:59], v[76:79], v[176:179], v[56:59]
	v_mfma_f32_16x16x32_bf16 v[24:27], v[80:83], v[176:179], v[24:27]
	v_mfma_f32_16x16x32_bf16 v[252:255], v[84:87], v[176:179], v[252:255]
	v_mfma_f32_16x16x32_bf16 v[120:123], v[88:91], v[176:179], v[120:123]
	ds_read_b128 v[200:203], v212 offset:55296
	s_waitcnt lgkmcnt(4)
	v_mfma_f32_16x16x32_bf16 v[60:63], v[76:79], v[180:183], v[60:63]
	v_mfma_f32_16x16x32_bf16 v[28:31], v[80:83], v[180:183], v[28:31]
	v_mfma_f32_16x16x32_bf16 v[92:95], v[84:87], v[180:183], v[92:95]
	v_mfma_f32_16x16x32_bf16 v[124:127], v[88:91], v[180:183], v[124:127]
	s_waitcnt vmcnt(0)
	ds_read_b128 v[176:179], v212 offset:57344
	s_waitcnt lgkmcnt(4)
	v_mfma_f32_16x16x32_bf16 v[32:35], v[140:143], v[184:187], v[32:35]
	v_mfma_f32_16x16x32_bf16 v[4:7], v[144:147], v[184:187], v[4:7]
	v_mfma_f32_16x16x32_bf16 v[188:191], v[148:151], v[184:187], v[188:191]
	v_mfma_f32_16x16x32_bf16 v[96:99], v[204:207], v[184:187], v[96:99]
	ds_read_b128 v[180:183], v212 offset:59392
	s_waitcnt lgkmcnt(4)
	v_mfma_f32_16x16x32_bf16 v[36:39], v[140:143], v[192:195], v[36:39]
	v_mfma_f32_16x16x32_bf16 v[12:15], v[144:147], v[192:195], v[12:15]
	v_mfma_f32_16x16x32_bf16 v[208:211], v[148:151], v[192:195], v[208:211]
	v_mfma_f32_16x16x32_bf16 v[100:103], v[204:207], v[192:195], v[100:103]
	ds_read_b128 v[184:187], v212 offset:61440
	s_waitcnt lgkmcnt(4)
	v_mfma_f32_16x16x32_bf16 v[40:43], v[140:143], v[196:199], v[40:43]
	v_mfma_f32_16x16x32_bf16 v[16:19], v[144:147], v[196:199], v[16:19]
	v_mfma_f32_16x16x32_bf16 v[232:235], v[148:151], v[196:199], v[232:235]
	v_mfma_f32_16x16x32_bf16 v[104:107], v[204:207], v[196:199], v[104:107]
	ds_read_b128 v[192:195], v212 offset:63488
	s_waitcnt lgkmcnt(4)
	v_mfma_f32_16x16x32_bf16 v[44:47], v[140:143], v[200:203], v[44:47]
	v_mfma_f32_16x16x32_bf16 v[20:23], v[144:147], v[200:203], v[20:23]
	v_mfma_f32_16x16x32_bf16 v[236:239], v[148:151], v[200:203], v[236:239]
	v_mfma_f32_16x16x32_bf16 v[108:111], v[204:207], v[200:203], v[108:111]
	s_waitcnt lgkmcnt(3)
	v_mfma_f32_16x16x32_bf16 v[48:51], v[140:143], v[176:179], v[48:51]
	v_mfma_f32_16x16x32_bf16 v[0:3], v[144:147], v[176:179], v[0:3]
	v_mfma_f32_16x16x32_bf16 v[240:243], v[148:151], v[176:179], v[240:243]
	v_mfma_f32_16x16x32_bf16 v[112:115], v[204:207], v[176:179], v[112:115]
	s_waitcnt lgkmcnt(2)
	v_mfma_f32_16x16x32_bf16 v[52:55], v[140:143], v[180:183], v[52:55]
	v_mfma_f32_16x16x32_bf16 v[8:11], v[144:147], v[180:183], v[8:11]
	v_mfma_f32_16x16x32_bf16 v[248:251], v[148:151], v[180:183], v[248:251]
	v_mfma_f32_16x16x32_bf16 v[116:119], v[204:207], v[180:183], v[116:119]
	s_waitcnt lgkmcnt(1)
	v_mfma_f32_16x16x32_bf16 v[56:59], v[140:143], v[184:187], v[56:59]
	v_mfma_f32_16x16x32_bf16 v[24:27], v[144:147], v[184:187], v[24:27]
	v_mfma_f32_16x16x32_bf16 v[252:255], v[148:151], v[184:187], v[252:255]
	v_mfma_f32_16x16x32_bf16 v[120:123], v[204:207], v[184:187], v[120:123]
	s_waitcnt lgkmcnt(0)
	v_mfma_f32_16x16x32_bf16 v[60:63], v[140:143], v[192:195], v[60:63]
	v_mfma_f32_16x16x32_bf16 v[28:31], v[144:147], v[192:195], v[28:31]
	v_mfma_f32_16x16x32_bf16 v[92:95], v[148:151], v[192:195], v[92:95]
	v_mfma_f32_16x16x32_bf16 v[124:127], v[204:207], v[192:195], v[124:127]
	s_nop 7
	s_nop 7
	s_waitcnt vmcnt(0) lgkmcnt(0)
	s_setprio 0
	s_barrier
	v_mov_b32_e32 v66, v92
	v_mov_b32_e32 v67, v93
	v_mov_b32_e32 v68, v94
	v_mov_b32_e32 v69, v95
	v_mov_b32_e32 v71, v96
	v_mov_b32_e32 v74, v97
	v_mov_b32_e32 v75, v98
	v_mov_b32_e32 v160, v99
	v_mov_b32_e32 v161, v100
	v_mov_b32_e32 v162, v101
	v_mov_b32_e32 v185, v102
	v_mov_b32_e32 v186, v103
	v_mov_b32_e32 v187, v104
	v_mov_b32_e32 v207, v105
	v_mov_b32_e32 v212, v106
	v_mov_b32_e32 v213, v107
	v_mov_b32_e32 v214, v108
	v_mov_b32_e32 v216, v109
	v_mov_b32_e32 v218, v110
	v_mov_b32_e32 v220, v111
	v_mov_b32_e32 v222, v112
	v_mov_b32_e32 v224, v113
	v_mov_b32_e32 v226, v114
	v_mov_b32_e32 v228, v115
	v_mov_b32_e32 v230, v116
	v_mov_b32_e32 v231, v117
	v_mov_b32_e32 v244, v118
	v_mov_b32_e32 v245, v119
	ds_write_b128 v129, v[120:123] offset:36864
	ds_write_b128 v129, v[124:127] offset:40960
	v_lshlrev_b32_e32 v77, 13, v135
	v_lshl_add_u32 v78, v134, 3, v138
	v_lshl_or_b32 v79, v134, 11, v77
	v_lshlrev_b32_e32 v81, 5, v138
	v_or3_b32 v163, v77, v137, v81
	v_lshl_or_b32 v164, v78, 2, v79
	v_add_u32_e32 v81, 0x60, v78
	v_add_u32_e32 v78, 0x70, v78
	v_and_b32_e32 v81, 0x7f, v81
	v_and_b32_e32 v78, 0x7f, v78
	v_lshl_or_b32 v165, v81, 2, v79
	v_lshl_or_b32 v166, v78, 2, v79
	v_add_u32_e32 v79, 8, v133
	v_and_b32_e32 v79, 0x78, v79
	v_lshlrev_b32_e32 v78, 9, v136
	v_lshlrev_b32_e32 v79, 2, v79
	v_or3_b32 v168, v77, v78, v79
	v_add_u32_e32 v79, 16, v133
	v_and_b32_e32 v79, 0x78, v79
	v_lshlrev_b32_e32 v78, 9, v132
	v_lshlrev_b32_e32 v79, 2, v79
	v_or3_b32 v170, v77, v78, v79
	v_add_u32_e32 v79, 24, v133
	v_and_b32_e32 v79, 0x78, v79
	v_lshlrev_b32_e32 v80, 5, v135
	v_lshlrev_b32_e32 v78, 9, v130
	v_lshlrev_b32_e32 v79, 2, v79
	v_or3_b32 v172, v77, v78, v79
	v_or_b32_e32 v77, 16, v80
	v_add_u32_e32 v81, 0x100, v131
	v_add_u32_e32 v82, 0x200, v131
	v_add_u32_e32 v83, 0x300, v131
	v_add_u32_e32 v84, 0x500, v131
	v_add_u32_e32 v85, 0x600, v131
	v_add_u32_e32 v86, 0x700, v131
	v_or_b32_e32 v174, v77, v134
	v_or_b32_e32 v175, v136, v77
	v_or_b32_e32 v176, v132, v77
	v_or_b32_e32 v177, v130, v77
	v_and_b32_e32 v77, 24, v153
	s_movk_i32 s94, 0x3c0
	v_lshrrev_b32_e32 v178, 4, v81
	v_lshrrev_b32_e32 v179, 4, v82
	v_lshrrev_b32_e32 v180, 4, v83
	v_lshrrev_b32_e32 v182, 4, v84
	v_lshrrev_b32_e32 v183, 4, v85
	v_lshrrev_b32_e32 v184, 4, v86
	v_or_b32_e32 v167, v134, v80
	v_or_b32_e32 v169, v136, v80
	v_or_b32_e32 v171, v132, v80
	v_or_b32_e32 v173, v130, v80
	v_and_or_b32 v77, v131, s94, v77
	v_mul_u32_u24_e32 v78, 0x110, v138
	v_lshlrev_b32_e32 v79, 4, v138
	v_mul_u32_u24_e32 v80, 0x110, v128
	v_mul_u32_u24_e32 v81, 0x110, v178
	v_mul_u32_u24_e32 v82, 0x110, v179
	v_mul_u32_u24_e32 v83, 0x110, v180
	v_mul_u32_u24_e32 v84, 0x110, v182
	v_mul_u32_u24_e32 v85, 0x110, v183
	v_mul_u32_u24_e32 v86, 0x110, v184
	v_or_b32_e32 v181, 64, v128
	v_lshlrev_b32_e32 v192, 2, v138
	v_add_u32_e32 v193, v77, v78
	v_add_u32_e32 v194, v79, v80
	v_add_u32_e32 v195, v79, v81
	v_add_u32_e32 v196, v79, v82
	v_add_u32_e32 v197, v79, v83
	v_add_u32_e32 v198, v79, v84
	v_add_u32_e32 v199, v79, v85
	v_add_u32_e32 v200, v79, v86
	v_mbcnt_hi_u32_b32 v201, -1, v155
	v_mov_b32_e32 v202, 0x3db504f3
	s_waitcnt lgkmcnt(0)
	s_mov_b64 s[58:59], -1
	s_cmp_lt_i32 s65, 4
	s_branch .Lmy_ip1_epi
